# score R-merge: med3 insertion with one-position safety margin and row-0 tie pass, strict-order check and exact fallback
# speedup vs baseline: 1.0013x; 1.0013x over previous
; DEV int tidx() { int t = threadIdx.x; asm volatile("" : "+v"(t)); return t; }
; DEV f32x4 mfma16(bf16x8 a, bf16x8 b, f32x4 c) { return __builtin_amdgcn_mfma_f32_16x16x32_bf16(a, b, c, 0, 0, 0); }
; DEV void peer_top16(const bf16_t* __restrict__ pq, const bf16_t* sk  , float (&l)[16]) {
;   const int lane = tidx() & 63, l15 = lane & 15, quad = lane >> 4;
;   f32x4 acc[8];
; #pragma unroll
;   for (int nt = 0; nt < 8; nt++) acc[nt] = (f32x4){0.f, 0.f, 0.f, 0.f};
; #pragma unroll 1
;   for (int ks = 0; ks < 4; ks++) {
;     const bf16x8 bqk = *(const bf16x8*)(pq + ks * 32 + quad * 8);
; #pragma unroll
;     for (int nt = 0; nt < 8; nt++) {
;       bf16x8 ak = *(const bf16x8*)(sk + (nt * 16 + l15) * 144 + ks * 32 + quad * 8);
;       acc[nt] = mfma16(ak, bqk, acc[nt]);
;     }
;   }
.LBB0_170:
	v_add_u32_e32 v139, 0x10e00, v122
	ds_read_b128 v[164:167], v122 offset:36864
	ds_read_b128 v[168:171], v122 offset:41472
	ds_read_b128 v[172:175], v122 offset:46080
	ds_read_b128 v[176:179], v122 offset:50688
	ds_read_b128 v[180:183], v122 offset:55296
	ds_read_b128 v[184:187], v122 offset:59904
	ds_read_b128 v[188:191], v122 offset:64512
	ds_read_b128 v[128:131], v139
	s_waitcnt vmcnt(3) lgkmcnt(7)
	v_mfma_f32_16x16x32_bf16 v[30:33], v[164:167], v[148:151], v[30:33]
	ds_read_b128 v[164:167], v122 offset:36928
	s_waitcnt lgkmcnt(7)
	v_mfma_f32_16x16x32_bf16 v[22:25], v[168:171], v[148:151], v[22:25]
	ds_read_b128 v[168:171], v122 offset:41536
	s_waitcnt lgkmcnt(7)
	v_mfma_f32_16x16x32_bf16 v[14:17], v[172:175], v[148:151], v[14:17]
	ds_read_b128 v[172:175], v122 offset:46144
	s_waitcnt lgkmcnt(7)
	v_mfma_f32_16x16x32_bf16 v[6:9], v[176:179], v[148:151], v[6:9]
	ds_read_b128 v[176:179], v122 offset:50752
	s_waitcnt lgkmcnt(7)
	v_mfma_f32_16x16x32_bf16 v[26:29], v[180:183], v[148:151], v[26:29]
	ds_read_b128 v[180:183], v122 offset:55360
	s_waitcnt lgkmcnt(7)
	v_mfma_f32_16x16x32_bf16 v[18:21], v[184:187], v[148:151], v[18:21]
	ds_read_b128 v[184:187], v122 offset:59968
	s_waitcnt lgkmcnt(7)
	v_mfma_f32_16x16x32_bf16 v[10:13], v[188:191], v[148:151], v[10:13]
	ds_read_b128 v[188:191], v122 offset:64576
	s_waitcnt lgkmcnt(7)
	v_mfma_f32_16x16x32_bf16 v[2:5], v[128:131], v[148:151], v[2:5]
	ds_read_b128 v[128:131], v139 offset:64
	s_waitcnt vmcnt(2) lgkmcnt(7)
	v_mfma_f32_16x16x32_bf16 v[30:33], v[164:167], v[152:155], v[30:33]
	ds_read_b128 v[164:167], v122 offset:36992
	s_waitcnt lgkmcnt(7)
	v_mfma_f32_16x16x32_bf16 v[22:25], v[168:171], v[152:155], v[22:25]
	ds_read_b128 v[168:171], v122 offset:41600
	s_waitcnt lgkmcnt(7)
	v_mfma_f32_16x16x32_bf16 v[14:17], v[172:175], v[152:155], v[14:17]
	ds_read_b128 v[172:175], v122 offset:46208
	s_waitcnt lgkmcnt(7)
	v_mfma_f32_16x16x32_bf16 v[6:9], v[176:179], v[152:155], v[6:9]
	ds_read_b128 v[176:179], v122 offset:50816
	s_waitcnt lgkmcnt(7)
	v_mfma_f32_16x16x32_bf16 v[26:29], v[180:183], v[152:155], v[26:29]
	ds_read_b128 v[180:183], v122 offset:55424
	s_waitcnt lgkmcnt(7)
	v_mfma_f32_16x16x32_bf16 v[18:21], v[184:187], v[152:155], v[18:21]
	ds_read_b128 v[184:187], v122 offset:60032
	s_waitcnt lgkmcnt(7)
	v_mfma_f32_16x16x32_bf16 v[10:13], v[188:191], v[152:155], v[10:13]
	ds_read_b128 v[188:191], v122 offset:64640
	s_waitcnt lgkmcnt(7)
	v_mfma_f32_16x16x32_bf16 v[2:5], v[128:131], v[152:155], v[2:5]
	ds_read_b128 v[128:131], v139 offset:128
	s_waitcnt vmcnt(1) lgkmcnt(7)
	v_mfma_f32_16x16x32_bf16 v[30:33], v[164:167], v[156:159], v[30:33]
	ds_read_b128 v[164:167], v122 offset:37056
	s_waitcnt lgkmcnt(7)
	v_mfma_f32_16x16x32_bf16 v[22:25], v[168:171], v[156:159], v[22:25]
	ds_read_b128 v[168:171], v122 offset:41664
	s_waitcnt lgkmcnt(7)
	v_mfma_f32_16x16x32_bf16 v[14:17], v[172:175], v[156:159], v[14:17]
	ds_read_b128 v[172:175], v122 offset:46272
	s_waitcnt lgkmcnt(7)
	v_mfma_f32_16x16x32_bf16 v[6:9], v[176:179], v[156:159], v[6:9]
	ds_read_b128 v[176:179], v122 offset:50880
	s_waitcnt lgkmcnt(7)
	v_mfma_f32_16x16x32_bf16 v[26:29], v[180:183], v[156:159], v[26:29]
	ds_read_b128 v[180:183], v122 offset:55488
	s_waitcnt lgkmcnt(7)
	v_mfma_f32_16x16x32_bf16 v[18:21], v[184:187], v[156:159], v[18:21]
	ds_read_b128 v[184:187], v122 offset:60096
	s_waitcnt lgkmcnt(7)
	v_mfma_f32_16x16x32_bf16 v[10:13], v[188:191], v[156:159], v[10:13]
	ds_read_b128 v[188:191], v122 offset:64704
	s_waitcnt lgkmcnt(7)
	v_mfma_f32_16x16x32_bf16 v[2:5], v[128:131], v[156:159], v[2:5]
	ds_read_b128 v[128:131], v139 offset:192
	s_waitcnt vmcnt(0) lgkmcnt(7)
	v_mfma_f32_16x16x32_bf16 v[30:33], v[164:167], v[160:163], v[30:33]
	s_waitcnt lgkmcnt(6)
	v_mfma_f32_16x16x32_bf16 v[22:25], v[168:171], v[160:163], v[22:25]
	s_waitcnt lgkmcnt(5)
	v_mfma_f32_16x16x32_bf16 v[14:17], v[172:175], v[160:163], v[14:17]
	s_waitcnt lgkmcnt(4)
	v_mfma_f32_16x16x32_bf16 v[6:9], v[176:179], v[160:163], v[6:9]
	s_waitcnt lgkmcnt(3)
	v_mfma_f32_16x16x32_bf16 v[26:29], v[180:183], v[160:163], v[26:29]
	s_waitcnt lgkmcnt(2)
	v_mfma_f32_16x16x32_bf16 v[18:21], v[184:187], v[160:163], v[18:21]
	s_waitcnt lgkmcnt(1)
	v_mfma_f32_16x16x32_bf16 v[10:13], v[188:191], v[160:163], v[10:13]
	s_waitcnt lgkmcnt(0)
; DEV void peer_top16(const bf16_t* __restrict__ pq, const bf16_t* sk  , float (&l)[16]) {
;     ...
;   float hi[16];
; #pragma unroll
;   for (int nt = 0; nt < 4; nt++)
; #pragma unroll
;     for (int r = 0; r < 4; r++) {
;       l[nt * 4 + r] = __uint_as_float((__float_as_uint(acc[nt][r]) & ~127u) | (unsigned)(nt * 16 + quad * 4 + r));
;       hi[nt * 4 + r] = __uint_as_float((__float_as_uint(acc[nt + 4][r]) & ~127u) | (unsigned)((nt + 4) * 16 + quad * 4 + r));
;     }
;   sort16_desc(l);
;   sort16_desc(hi);
; #pragma unroll
;   for (int i = 0; i < 16; i++) l[i] = fmaxf(l[i], hi[15 - i]);
;   bitonic16(l);
	v_mfma_f32_16x16x32_bf16 v[2:5], v[128:131], v[160:163], v[2:5]
	s_movk_i32 s0, 0x100
	v_max_f32_e32 v0, v109, v121
	v_max_f32_e32 v100, v107, v120
	v_max_f32_e32 v101, v105, v119
	v_max_f32_e32 v103, v103, v118
	v_max_f32_e32 v87, v87, v116
	v_max_f32_e32 v79, v79, v115
	v_max_f32_e32 v75, v75, v114
	v_max_f32_e32 v71, v71, v113
	v_max_f32_e32 v67, v67, v112
	v_max_f32_e32 v63, v63, v111
	v_max_f32_e32 v59, v59, v110
	v_max_f32_e32 v55, v55, v108
	v_max_f32_e32 v51, v51, v106
	v_max_f32_e32 v47, v47, v104
	v_max_f32_e32 v43, v43, v91
	v_max_f32_e32 v39, v39, v83
	v_max_f32_e32 v83, v0, v67
	v_min_f32_e32 v0, v0, v67
	v_max_f32_e32 v67, v100, v63
	v_min_f32_e32 v63, v100, v63
	v_max_f32_e32 v91, v101, v59
	v_min_f32_e32 v59, v101, v59
	v_max_f32_e32 v100, v103, v55
	v_min_f32_e32 v55, v103, v55
	v_max_f32_e32 v101, v87, v51
	v_min_f32_e32 v51, v87, v51
	v_max_f32_e32 v87, v79, v47
	v_min_f32_e32 v47, v79, v47
	v_max_f32_e32 v79, v75, v43
	v_min_f32_e32 v43, v75, v43
	v_max_f32_e32 v75, v71, v39
	v_min_f32_e32 v39, v71, v39
	v_max_f32_e32 v71, v83, v101
	v_min_f32_e32 v101, v83, v101
	v_max_f32_e32 v103, v67, v87
	v_min_f32_e32 v67, v67, v87
	v_max_f32_e32 v87, v91, v79
	v_min_f32_e32 v79, v91, v79
	v_max_f32_e32 v91, v100, v75
	v_min_f32_e32 v75, v100, v75
	v_max_f32_e32 v100, v0, v51
	v_min_f32_e32 v0, v0, v51
	v_max_f32_e32 v51, v63, v47
	v_max_f32_e32 v105, v59, v43
	v_min_f32_e32 v43, v59, v43
	v_max_f32_e32 v59, v55, v39
	v_min_f32_e32 v107, v101, v79
	v_min_f32_e32 v108, v67, v75
	v_min_f32_e32 v110, v51, v59
	v_max_f32_e32 v79, v101, v79
	v_max_f32_e32 v67, v67, v75
	v_max_f32_e32 v101, v100, v105
	v_max_f32_e32 v51, v51, v59
	v_min_f32_e32 v75, v79, v67
	v_min_f32_e32 v59, v101, v51
	v_max_f32_e32 v79, v79, v67
	v_max_f32_e32 v67, v101, v51
	v_lshlrev_b32_e32 v101, 2, v102
	s_movk_i32 s0, 0xff80
	v_and_or_b32 v30, v30, s0, v101
	v_and_b32_e32 v27, 0xffffff80, v27
	s_movk_i32 s0, 0x41
	v_or3_b32 v27, v101, v27, s0
	v_and_b32_e32 v28, 0xffffff80, v28
	s_movk_i32 s0, 0x42
	v_or3_b32 v28, v101, v28, s0
	v_and_b32_e32 v29, 0xffffff80, v29
	s_movk_i32 s0, 0x43
	v_or3_b32 v29, v101, v29, s0
	v_and_b32_e32 v18, 0xffffff80, v18
	s_movk_i32 s0, 0x50
	v_or3_b32 v18, v101, v18, s0
	v_and_b32_e32 v19, 0xffffff80, v19
	s_movk_i32 s0, 0x51
	v_or3_b32 v19, v101, v19, s0
	v_and_b32_e32 v20, 0xffffff80, v20
	s_movk_i32 s0, 0x52
	v_or3_b32 v20, v101, v20, s0
	v_and_b32_e32 v21, 0xffffff80, v21
	s_movk_i32 s0, 0x53
	v_or3_b32 v21, v101, v21, s0
	v_and_b32_e32 v10, 0xffffff80, v10
	s_movk_i32 s0, 0x60
	v_or3_b32 v10, v101, v10, s0
	v_and_b32_e32 v11, 0xffffff80, v11
	s_movk_i32 s0, 0x61
	v_or3_b32 v11, v101, v11, s0
	v_and_b32_e32 v12, 0xffffff80, v12
	s_movk_i32 s0, 0x62
	v_or3_b32 v12, v101, v12, s0
	v_and_b32_e32 v13, 0xffffff80, v13
	s_movk_i32 s0, 0x63
	v_or3_b32 v13, v101, v13, s0
	v_and_b32_e32 v2, 0xffffff80, v2
	s_movk_i32 s0, 0x70
	v_and_b32_e32 v26, 0xffffff80, v26
	v_and_b32_e32 v31, 0xffffff80, v31
	v_or3_b32 v2, v101, v2, s0
	v_and_b32_e32 v3, 0xffffff80, v3
	s_movk_i32 s0, 0x71
	v_or3_b32 v26, v101, v26, 64
	v_or3_b32 v31, v101, v31, 1
	v_and_b32_e32 v32, 0xffffff80, v32
	v_and_b32_e32 v33, 0xffffff80, v33
	v_and_b32_e32 v22, 0xffffff80, v22
	v_and_b32_e32 v23, 0xffffff80, v23
	v_or3_b32 v3, v101, v3, s0
	v_and_b32_e32 v4, 0xffffff80, v4
	s_movk_i32 s0, 0x72
	v_min_f32_e32 v39, v55, v39
	v_min_f32_e32 v55, v71, v87
	v_min_f32_e32 v106, v103, v91
	v_min_f32_e32 v109, v100, v105
	v_max_f32_e32 v71, v71, v87
	v_max_f32_e32 v87, v103, v91
	v_or3_b32 v32, v101, v32, 2
	v_or3_b32 v33, v101, v33, 3
	v_or3_b32 v22, v101, v22, 16
	v_or3_b32 v23, v101, v23, 17
	v_and_b32_e32 v24, 0xffffff80, v24
	v_and_b32_e32 v25, 0xffffff80, v25
	v_and_b32_e32 v14, 0xffffff80, v14
	v_and_b32_e32 v15, 0xffffff80, v15
	v_and_b32_e32 v16, 0xffffff80, v16
	v_and_b32_e32 v17, 0xffffff80, v17
	v_and_b32_e32 v6, 0xffffff80, v6
	v_and_b32_e32 v7, 0xffffff80, v7
	v_and_b32_e32 v8, 0xffffff80, v8
	v_or3_b32 v4, v101, v4, s0
	v_and_b32_e32 v9, 0xffffff80, v9
	v_and_b32_e32 v5, 0xffffff80, v5
	s_movk_i32 s0, 0x73
	v_min_f32_e32 v104, v63, v47
	v_min_f32_e32 v83, v55, v106
	v_min_f32_e32 v47, v109, v110
	v_min_f32_e32 v91, v71, v87
	v_max_f32_e32 v100, v71, v87
	v_max_f32_e32 v87, v55, v106
	v_max_f32_e32 v55, v109, v110
	v_or3_b32 v24, v101, v24, 18
	v_or3_b32 v25, v101, v25, 19
	v_or3_b32 v14, v101, v14, 32
	v_or3_b32 v15, v101, v15, 33
	v_or3_b32 v16, v101, v16, 34
	v_or3_b32 v17, v101, v17, 35
	v_or3_b32 v6, v101, v6, 48
	v_or3_b32 v7, v101, v7, 49
	v_or3_b32 v8, v101, v8, 50
	v_or3_b32 v9, v101, v9, 51
	v_or3_b32 v5, v101, v5, s0
	v_max_f32_e32 v101, v30, v31
	v_min_f32_e32 v30, v30, v31
	v_max_f32_e32 v31, v32, v32
	v_max_f32_e32 v32, v33, v33
	v_max_f32_e32 v109, v26, v27
	v_min_f32_e32 v26, v26, v27
	v_max_f32_e32 v27, v28, v28
	v_max_f32_e32 v28, v29, v29
	v_max_f32_e32 v33, v32, v31
	v_min_f32_e32 v31, v32, v31
	v_max_f32_e32 v32, v22, v23
	v_min_f32_e32 v22, v22, v23
	v_max_f32_e32 v23, v24, v24
	v_max_f32_e32 v24, v25, v25
	v_max_f32_e32 v29, v28, v27
	v_min_f32_e32 v27, v28, v27
	v_max_f32_e32 v28, v18, v19
	v_min_f32_e32 v18, v18, v19
	v_max_f32_e32 v19, v20, v20
	v_max_f32_e32 v20, v21, v21
	v_max_f32_e32 v25, v24, v23
	v_min_f32_e32 v23, v24, v23
	v_max_f32_e32 v24, v14, v15
	v_min_f32_e32 v14, v14, v15
	v_max_f32_e32 v15, v16, v16
	v_max_f32_e32 v16, v17, v17
	v_max_f32_e32 v21, v20, v19
	v_min_f32_e32 v19, v20, v19
	v_max_f32_e32 v20, v10, v11
	v_min_f32_e32 v10, v10, v11
	v_max_f32_e32 v11, v12, v12
	v_max_f32_e32 v12, v13, v13
	v_max_f32_e32 v17, v16, v15
	v_min_f32_e32 v15, v16, v15
	v_max_f32_e32 v16, v6, v7
	v_min_f32_e32 v6, v6, v7
; DEV void ce(float& a, float& b) { float hi = fmaxf(a, b), lo = fminf(a, b); a = hi; b = lo; }
; DEV void sort16_desc(float (&a)[16]) {
; #pragma unroll
;   for (int k = 2; k <= 16; k <<= 1)
; #pragma unroll
;     for (int j = k >> 1; j > 0; j >>= 1)
; #pragma unroll
;       for (int i = 0; i < 16; i++) {
;         const int p = i ^ j;
;         if (p > i) { if ((i & k) == 0) ce(a[i], a[p]); else ce(a[p], a[i]); }
;       }
; }
	v_max_f32_e32 v7, v8, v8
	v_max_f32_e32 v8, v9, v9
	v_max_f32_e32 v13, v12, v11
	v_min_f32_e32 v11, v12, v11
	v_max_f32_e32 v12, v2, v3
	v_min_f32_e32 v2, v2, v3
	v_max_f32_e32 v3, v4, v4
	v_max_f32_e32 v4, v5, v5
	v_max_f32_e32 v9, v8, v7
	v_min_f32_e32 v7, v8, v7
	v_max_f32_e32 v5, v4, v3
	v_min_f32_e32 v3, v4, v3
	v_max_f32_e32 v8, v101, v31
	v_min_f32_e32 v31, v101, v31
	v_max_f32_e32 v101, v30, v33
	v_min_f32_e32 v30, v30, v33
	v_max_f32_e32 v33, v23, v32
	v_min_f32_e32 v23, v23, v32
	v_max_f32_e32 v32, v25, v22
	v_min_f32_e32 v22, v25, v22
	v_max_f32_e32 v25, v24, v15
	v_min_f32_e32 v15, v24, v15
	v_max_f32_e32 v24, v14, v17
	v_min_f32_e32 v14, v14, v17
	v_max_f32_e32 v17, v7, v16
	v_min_f32_e32 v7, v7, v16
	v_max_f32_e32 v16, v9, v6
	v_min_f32_e32 v6, v9, v6
	v_max_f32_e32 v4, v109, v27
	v_min_f32_e32 v27, v109, v27
	v_max_f32_e32 v109, v26, v29
	v_min_f32_e32 v26, v26, v29
	v_max_f32_e32 v29, v19, v28
	v_min_f32_e32 v19, v19, v28
	v_max_f32_e32 v28, v21, v18
	v_min_f32_e32 v18, v21, v18
	v_max_f32_e32 v21, v20, v11
	v_min_f32_e32 v11, v20, v11
	v_max_f32_e32 v20, v10, v13
	v_min_f32_e32 v10, v10, v13
	v_max_f32_e32 v13, v3, v12
	v_min_f32_e32 v3, v3, v12
	v_max_f32_e32 v12, v5, v2
	v_min_f32_e32 v2, v5, v2
	v_max_f32_e32 v9, v8, v101
	v_min_f32_e32 v8, v8, v101
	v_max_f32_e32 v101, v31, v30
	v_min_f32_e32 v30, v31, v30
	v_max_f32_e32 v31, v22, v23
	v_min_f32_e32 v22, v22, v23
	v_max_f32_e32 v23, v32, v33
	v_min_f32_e32 v32, v32, v33
	v_max_f32_e32 v33, v25, v24
	v_min_f32_e32 v24, v25, v24
	v_max_f32_e32 v25, v15, v14
	v_min_f32_e32 v14, v15, v14
	v_max_f32_e32 v15, v6, v7
	v_min_f32_e32 v6, v6, v7
	v_max_f32_e32 v7, v16, v17
	v_min_f32_e32 v16, v16, v17
	v_max_f32_e32 v5, v4, v109
	v_min_f32_e32 v4, v4, v109
	v_max_f32_e32 v109, v27, v26
	v_min_f32_e32 v26, v27, v26
	v_max_f32_e32 v27, v18, v19
	v_min_f32_e32 v18, v18, v19
	v_max_f32_e32 v19, v28, v29
	v_min_f32_e32 v28, v28, v29
	v_max_f32_e32 v29, v21, v20
	v_min_f32_e32 v20, v21, v20
	v_max_f32_e32 v21, v11, v10
	v_min_f32_e32 v10, v11, v10
	v_max_f32_e32 v11, v2, v3
	v_min_f32_e32 v2, v2, v3
	v_max_f32_e32 v3, v12, v13
	v_min_f32_e32 v12, v12, v13
	v_max_f32_e32 v17, v9, v22
	v_min_f32_e32 v9, v9, v22
	v_max_f32_e32 v22, v8, v31
	v_min_f32_e32 v8, v8, v31
	v_max_f32_e32 v31, v101, v32
	v_min_f32_e32 v32, v101, v32
	v_max_f32_e32 v101, v30, v23
	v_min_f32_e32 v23, v30, v23
	v_max_f32_e32 v30, v6, v33
	v_min_f32_e32 v6, v6, v33
	v_max_f32_e32 v33, v15, v24
	v_min_f32_e32 v15, v15, v24
	v_max_f32_e32 v24, v16, v25
	v_min_f32_e32 v16, v16, v25
	v_max_f32_e32 v25, v7, v14
	v_min_f32_e32 v7, v7, v14
	v_max_f32_e32 v13, v5, v18
	v_min_f32_e32 v5, v5, v18
	v_max_f32_e32 v18, v4, v27
	v_min_f32_e32 v4, v4, v27
	v_max_f32_e32 v27, v109, v28
	v_min_f32_e32 v28, v109, v28
	v_max_f32_e32 v109, v26, v19
	v_min_f32_e32 v19, v26, v19
	v_max_f32_e32 v26, v2, v29
	v_min_f32_e32 v2, v2, v29
	v_max_f32_e32 v29, v11, v20
	v_min_f32_e32 v11, v11, v20
	v_max_f32_e32 v20, v12, v21
	v_min_f32_e32 v12, v12, v21
	v_max_f32_e32 v21, v3, v10
	v_min_f32_e32 v3, v3, v10
	v_max_f32_e32 v14, v17, v31
	v_min_f32_e32 v17, v17, v31
	v_max_f32_e32 v31, v22, v101
	v_min_f32_e32 v22, v22, v101
	v_max_f32_e32 v101, v9, v32
	v_min_f32_e32 v9, v9, v32
	v_max_f32_e32 v32, v8, v23
	v_min_f32_e32 v8, v8, v23
	v_max_f32_e32 v23, v16, v6
	v_min_f32_e32 v6, v16, v6
	v_max_f32_e32 v16, v7, v15
	v_min_f32_e32 v7, v7, v15
	v_max_f32_e32 v15, v24, v30
	v_min_f32_e32 v24, v24, v30
	v_max_f32_e32 v30, v25, v33
	v_min_f32_e32 v25, v25, v33
	v_max_f32_e32 v10, v13, v27
	v_min_f32_e32 v13, v13, v27
	v_max_f32_e32 v27, v18, v109
	v_min_f32_e32 v18, v18, v109
	v_max_f32_e32 v109, v5, v28
	v_min_f32_e32 v5, v5, v28
	v_max_f32_e32 v28, v4, v19
	v_min_f32_e32 v4, v4, v19
	v_max_f32_e32 v19, v12, v2
	v_min_f32_e32 v2, v12, v2
	v_max_f32_e32 v12, v3, v11
	v_min_f32_e32 v3, v3, v11
	v_max_f32_e32 v11, v20, v26
	v_min_f32_e32 v20, v20, v26
	v_max_f32_e32 v26, v21, v29
	v_min_f32_e32 v21, v21, v29
	v_max_f32_e32 v33, v14, v31
	v_min_f32_e32 v14, v14, v31
	v_max_f32_e32 v31, v17, v22
	v_min_f32_e32 v17, v17, v22
	v_max_f32_e32 v22, v101, v32
	v_min_f32_e32 v32, v101, v32
	v_max_f32_e32 v101, v9, v8
	v_min_f32_e32 v8, v9, v8
	v_max_f32_e32 v9, v7, v6
	v_min_f32_e32 v6, v7, v6
	v_max_f32_e32 v7, v16, v23
	v_min_f32_e32 v16, v16, v23
	v_max_f32_e32 v23, v25, v24
	v_min_f32_e32 v24, v25, v24
	v_max_f32_e32 v25, v30, v15
	v_min_f32_e32 v15, v30, v15
	v_max_f32_e32 v29, v10, v27
	v_min_f32_e32 v10, v10, v27
	v_max_f32_e32 v27, v13, v18
	v_min_f32_e32 v13, v13, v18
	v_max_f32_e32 v18, v109, v28
	v_min_f32_e32 v28, v109, v28
	v_max_f32_e32 v109, v5, v4
	v_min_f32_e32 v4, v5, v4
	v_max_f32_e32 v5, v3, v2
	v_min_f32_e32 v2, v3, v2
	v_max_f32_e32 v3, v12, v19
	v_min_f32_e32 v12, v12, v19
	v_max_f32_e32 v19, v21, v20
	v_min_f32_e32 v20, v21, v20
	v_max_f32_e32 v21, v26, v11
	v_min_f32_e32 v11, v26, v11
	v_max_f32_e32 v30, v33, v6
	v_min_f32_e32 v6, v33, v6
	v_max_f32_e32 v33, v14, v9
	v_min_f32_e32 v9, v14, v9
	v_max_f32_e32 v14, v31, v16
	v_min_f32_e32 v16, v31, v16
	v_max_f32_e32 v31, v17, v7
	v_min_f32_e32 v7, v17, v7
	v_max_f32_e32 v17, v22, v24
	v_min_f32_e32 v22, v22, v24
	v_max_f32_e32 v24, v32, v23
	v_min_f32_e32 v23, v32, v23
	v_max_f32_e32 v32, v101, v15
	v_min_f32_e32 v15, v101, v15
	v_max_f32_e32 v101, v8, v25
	v_min_f32_e32 v8, v8, v25
	v_max_f32_e32 v26, v29, v2
	v_min_f32_e32 v2, v29, v2
	v_max_f32_e32 v29, v10, v5
	v_min_f32_e32 v5, v10, v5
	v_max_f32_e32 v10, v27, v12
	v_min_f32_e32 v12, v27, v12
	v_max_f32_e32 v27, v13, v3
	v_min_f32_e32 v3, v13, v3
	v_max_f32_e32 v13, v18, v20
	v_min_f32_e32 v18, v18, v20
	v_max_f32_e32 v20, v28, v19
; DEV void ce(float& a, float& b) { float hi = fmaxf(a, b), lo = fminf(a, b); a = hi; b = lo; }
; DEV void bitonic16(float (&l)[16]) {
; #pragma unroll
;   for (int s = 8; s > 0; s >>= 1)
; #pragma unroll
;     for (int i = 0; i < 16; i++)
;       if (!(i & s)) ce(l[i], l[i + s]);
; }
; DEV void sort16_desc(float (&a)[16]) {
; #pragma unroll
;   for (int k = 2; k <= 16; k <<= 1)
; #pragma unroll
;     for (int j = k >> 1; j > 0; j >>= 1)
; #pragma unroll
;       for (int i = 0; i < 16; i++) {
;         const int p = i ^ j;
;         if (p > i) { if ((i & k) == 0) ce(a[i], a[p]); else ce(a[p], a[i]); }
;       }
; }
; DEV void merge_xor(float (&l)[16], int mask) {
;   float t[16];
; #pragma unroll
;   for (int i = 0; i < 16; i++) t[i] = __shfl_xor(l[15 - i], mask);
; #pragma unroll
;   for (int i = 0; i < 16; i++) l[i] = fmaxf(l[i], t[i]);
;   bitonic16(l);
; DEV void peer_top16(const bf16_t* __restrict__ pq, const bf16_t* sk  , float (&l)[16]) {
;     ...
;   sort16_desc(l);
;   sort16_desc(hi);
; #pragma unroll
;   for (int i = 0; i < 16; i++) l[i] = fmaxf(l[i], hi[15 - i]);
;   bitonic16(l);
;   merge_xor(l, 16);
	v_min_f32_e32 v19, v28, v19
	v_max_f32_e32 v28, v109, v11
	v_min_f32_e32 v11, v109, v11
	v_max_f32_e32 v109, v4, v21
	v_min_f32_e32 v4, v4, v21
	v_max_f32_e32 v25, v30, v17
	v_min_f32_e32 v17, v30, v17
	v_max_f32_e32 v30, v33, v24
	v_min_f32_e32 v24, v33, v24
	v_max_f32_e32 v33, v14, v32
	v_min_f32_e32 v14, v14, v32
	v_max_f32_e32 v32, v31, v101
	v_min_f32_e32 v31, v31, v101
	v_max_f32_e32 v101, v6, v22
	v_min_f32_e32 v6, v6, v22
	v_max_f32_e32 v22, v9, v23
	v_min_f32_e32 v9, v9, v23
	v_max_f32_e32 v23, v16, v15
	v_min_f32_e32 v15, v16, v15
	v_max_f32_e32 v16, v7, v8
	v_min_f32_e32 v7, v7, v8
	v_max_f32_e32 v21, v26, v13
	v_min_f32_e32 v13, v26, v13
	v_max_f32_e32 v26, v29, v20
	v_min_f32_e32 v20, v29, v20
	v_max_f32_e32 v29, v10, v28
	v_min_f32_e32 v10, v10, v28
	v_max_f32_e32 v28, v27, v109
	v_min_f32_e32 v27, v27, v109
	v_max_f32_e32 v109, v2, v18
	v_min_f32_e32 v2, v2, v18
	v_max_f32_e32 v18, v5, v19
	v_min_f32_e32 v5, v5, v19
	v_max_f32_e32 v19, v12, v11
	v_min_f32_e32 v11, v12, v11
	v_max_f32_e32 v12, v3, v4
	v_min_f32_e32 v3, v3, v4
	v_max_f32_e32 v111, v0, v43
	v_min_f32_e32 v112, v104, v39
	v_max_f32_e32 v103, v104, v39
	v_min_f32_e32 v0, v0, v43
	v_max_f32_e32 v8, v25, v33
	v_min_f32_e32 v25, v25, v33
	v_max_f32_e32 v33, v30, v32
	v_min_f32_e32 v30, v30, v32
	v_max_f32_e32 v32, v17, v14
	v_min_f32_e32 v14, v17, v14
	v_max_f32_e32 v17, v24, v31
	v_min_f32_e32 v24, v24, v31
	v_max_f32_e32 v31, v101, v23
	v_min_f32_e32 v23, v101, v23
	v_max_f32_e32 v101, v22, v16
	v_min_f32_e32 v16, v22, v16
	v_max_f32_e32 v22, v6, v15
	v_min_f32_e32 v6, v6, v15
	v_max_f32_e32 v15, v9, v7
	v_min_f32_e32 v7, v9, v7
	v_max_f32_e32 v4, v21, v29
	v_min_f32_e32 v21, v21, v29
	v_max_f32_e32 v29, v26, v28
	v_min_f32_e32 v26, v26, v28
	v_max_f32_e32 v28, v13, v10
	v_min_f32_e32 v10, v13, v10
	v_max_f32_e32 v13, v20, v27
	v_min_f32_e32 v20, v20, v27
	v_max_f32_e32 v27, v109, v19
	v_min_f32_e32 v19, v109, v19
	v_max_f32_e32 v109, v18, v12
	v_min_f32_e32 v12, v18, v12
	v_max_f32_e32 v18, v2, v11
	v_min_f32_e32 v2, v2, v11
	v_max_f32_e32 v11, v5, v3
	v_min_f32_e32 v3, v5, v3
	v_min_f32_e32 v63, v107, v108
	v_min_f32_e32 v39, v111, v103
	v_max_f32_e32 v71, v107, v108
	v_max_f32_e32 v51, v111, v103
	v_max_f32_e32 v43, v0, v112
	v_min_f32_e32 v0, v0, v112
	v_min_f32_e32 v9, v8, v33
	v_min_f32_e32 v102, v25, v30
	v_min_f32_e32 v103, v32, v17
	v_min_f32_e32 v104, v14, v24
	v_min_f32_e32 v105, v31, v101
	v_min_f32_e32 v106, v23, v16
	v_min_f32_e32 v107, v22, v15
	v_min_f32_e32 v108, v6, v7
	v_min_f32_e32 v5, v4, v29
	v_min_f32_e32 v110, v21, v26
	v_min_f32_e32 v111, v28, v13
	v_min_f32_e32 v112, v10, v20
	v_min_f32_e32 v113, v27, v109
	v_min_f32_e32 v114, v19, v12
	v_min_f32_e32 v115, v18, v11
	v_min_f32_e32 v116, v2, v3
	v_max3_f32 v8, v8, v33, v116
	v_max3_f32 v2, v9, v2, v3
	v_max3_f32 v3, v25, v30, v115
	v_max3_f32 v9, v102, v18, v11
	v_max3_f32 v11, v32, v17, v114
	v_max3_f32 v12, v103, v19, v12
	v_max3_f32 v14, v14, v24, v113
	v_max3_f32 v17, v104, v27, v109
	v_max3_f32 v18, v31, v101, v112
	v_max3_f32 v10, v105, v10, v20
	v_max3_f32 v16, v23, v16, v111
	v_max3_f32 v13, v106, v28, v13
	v_max3_f32 v15, v22, v15, v110
	v_max3_f32 v19, v107, v21, v26
	v_max3_f32 v5, v6, v7, v5
	v_max3_f32 v4, v108, v4, v29
	v_max_f32_e32 v6, v8, v18
	v_min_f32_e32 v7, v8, v18
	v_max_f32_e32 v8, v2, v10
	v_min_f32_e32 v2, v2, v10
	v_max_f32_e32 v10, v3, v16
	v_min_f32_e32 v3, v3, v16
	v_max_f32_e32 v16, v9, v13
	v_min_f32_e32 v9, v9, v13
	v_max_f32_e32 v13, v11, v15
	v_min_f32_e32 v11, v11, v15
	v_max_f32_e32 v15, v12, v19
	v_min_f32_e32 v12, v12, v19
	v_max_f32_e32 v18, v14, v5
	v_min_f32_e32 v5, v14, v5
	v_max_f32_e32 v14, v17, v4
	v_min_f32_e32 v4, v17, v4
	v_max_f32_e32 v17, v6, v13
	v_min_f32_e32 v6, v6, v13
	v_max_f32_e32 v13, v8, v15
	v_min_f32_e32 v8, v8, v15
	v_max_f32_e32 v15, v10, v18
	v_min_f32_e32 v10, v10, v18
	v_max_f32_e32 v18, v16, v14
	v_min_f32_e32 v14, v16, v14
	v_max_f32_e32 v16, v7, v11
	v_min_f32_e32 v7, v7, v11
	v_max_f32_e32 v11, v2, v12
	v_min_f32_e32 v2, v2, v12
	v_max_f32_e32 v12, v3, v5
	v_min_f32_e32 v3, v3, v5
	v_max_f32_e32 v5, v9, v4
	v_min_f32_e32 v4, v9, v4
	v_max_f32_e32 v9, v17, v15
	v_min_f32_e32 v15, v17, v15
	v_max_f32_e32 v17, v13, v18
	v_min_f32_e32 v13, v13, v18
	v_max_f32_e32 v18, v6, v10
	v_min_f32_e32 v6, v6, v10
	v_max_f32_e32 v10, v8, v14
	v_min_f32_e32 v8, v8, v14
	v_max_f32_e32 v14, v16, v12
	v_min_f32_e32 v12, v16, v12
	v_max_f32_e32 v16, v11, v5
	v_min_f32_e32 v5, v11, v5
	v_max_f32_e32 v11, v7, v3
	v_min_f32_e32 v3, v7, v3
	v_max_f32_e32 v7, v2, v4
	v_min_f32_e32 v2, v2, v4
	v_max_f32_e32 v4, v9, v17
	v_min_f32_e32 v9, v9, v17
	v_max_f32_e32 v17, v15, v13
	v_min_f32_e32 v13, v15, v13
	v_max_f32_e32 v15, v18, v10
	v_min_f32_e32 v10, v18, v10
	v_max_f32_e32 v18, v6, v8
	v_min_f32_e32 v6, v6, v8
	v_max_f32_e32 v8, v14, v16
	v_min_f32_e32 v14, v14, v16
	v_max_f32_e32 v16, v12, v5
	v_min_f32_e32 v5, v12, v5
	v_max_f32_e32 v12, v11, v7
	v_min_f32_e32 v7, v11, v7
	v_max_f32_e32 v11, v3, v2
	v_min_f32_e32 v2, v3, v2
	ds_bpermute_b32 v3, v95, v2
	ds_bpermute_b32 v19, v95, v11
	ds_bpermute_b32 v20, v95, v7
	ds_bpermute_b32 v21, v95, v12
	ds_bpermute_b32 v22, v95, v5
	ds_bpermute_b32 v23, v95, v16
	s_waitcnt lgkmcnt(5)
	ds_bpermute_b32 v24, v95, v14
	ds_bpermute_b32 v33, v95, v4
	v_max_f32_e32 v3, v4, v3
	s_waitcnt lgkmcnt(6)
	ds_bpermute_b32 v25, v95, v8
	ds_bpermute_b32 v32, v95, v9
	v_max_f32_e32 v4, v9, v19
	s_waitcnt lgkmcnt(7)
	ds_bpermute_b32 v26, v95, v6
	ds_bpermute_b32 v31, v95, v17
	v_max_f32_e32 v9, v17, v20
	s_waitcnt lgkmcnt(8)
	ds_bpermute_b32 v27, v95, v18
	ds_bpermute_b32 v30, v95, v13
	v_max_f32_e32 v13, v13, v21
	s_waitcnt lgkmcnt(9)
; DEV void merge_xor(float (&l)[16], int mask) {
;   float t[16];
; #pragma unroll
;   for (int i = 0; i < 16; i++) t[i] = __shfl_xor(l[15 - i], mask);
; #pragma unroll
;   for (int i = 0; i < 16; i++) l[i] = fmaxf(l[i], t[i]);
;   bitonic16(l);
; }
; DEV void phase_peer_score(const Params& p, int layer, int M, char* smem) {
;     ...
;     unsigned char* tab = (unsigned char*)smem + 73728 + (w * 16 + l15) * 32;
; #pragma unroll
;     for (int i = 0; i < 16; i++) { tab[i] = (unsigned char)(__float_as_uint(L0[i]) & 127u); tab[16 + i] = (unsigned char)(__float_as_uint(L1[i]) & 127u); }
	ds_bpermute_b32 v28, v95, v10
	ds_bpermute_b32 v29, v95, v15
	v_max_f32_e32 v15, v15, v22
	s_waitcnt lgkmcnt(10)
	v_max_f32_e32 v10, v10, v23
	s_waitcnt lgkmcnt(9)
	v_max_f32_e32 v17, v18, v24
	s_waitcnt lgkmcnt(7)
	v_max_f32_e32 v6, v6, v25
	s_waitcnt lgkmcnt(5)
	v_max_f32_e32 v8, v8, v26
	s_waitcnt lgkmcnt(3)
	v_max_f32_e32 v14, v14, v27
	s_waitcnt lgkmcnt(1)
	v_max_f32_e32 v16, v16, v28
	s_waitcnt lgkmcnt(0)
	v_max_f32_e32 v5, v5, v29
	v_max_f32_e32 v12, v12, v30
	v_max_f32_e32 v7, v7, v31
	v_max_f32_e32 v11, v11, v32
	v_max_f32_e32 v2, v2, v33
	v_max_f32_e32 v18, v3, v8
	v_min_f32_e32 v3, v3, v8
	v_max_f32_e32 v8, v4, v14
	v_min_f32_e32 v4, v4, v14
	v_max_f32_e32 v14, v9, v16
	v_min_f32_e32 v9, v9, v16
	v_max_f32_e32 v16, v13, v5
	v_min_f32_e32 v5, v13, v5
	v_max_f32_e32 v13, v15, v12
	v_min_f32_e32 v12, v15, v12
	v_max_f32_e32 v15, v10, v7
	v_min_f32_e32 v7, v10, v7
	v_max_f32_e32 v10, v17, v11
	v_min_f32_e32 v11, v17, v11
	v_max_f32_e32 v17, v6, v2
	v_min_f32_e32 v2, v6, v2
	v_max_f32_e32 v6, v18, v13
	v_min_f32_e32 v13, v18, v13
	v_max_f32_e32 v18, v8, v15
	v_min_f32_e32 v8, v8, v15
	v_max_f32_e32 v15, v14, v10
	v_min_f32_e32 v10, v14, v10
	v_max_f32_e32 v14, v16, v17
	v_min_f32_e32 v16, v16, v17
	v_max_f32_e32 v17, v3, v12
	v_min_f32_e32 v3, v3, v12
	v_max_f32_e32 v12, v4, v7
	v_min_f32_e32 v4, v4, v7
	v_max_f32_e32 v7, v9, v11
	v_min_f32_e32 v9, v9, v11
	v_max_f32_e32 v11, v5, v2
	v_min_f32_e32 v2, v5, v2
	v_max_f32_e32 v5, v6, v15
	v_min_f32_e32 v6, v6, v15
	v_max_f32_e32 v15, v18, v14
	v_min_f32_e32 v14, v18, v14
	v_max_f32_e32 v18, v13, v10
	v_min_f32_e32 v10, v13, v10
	v_max_f32_e32 v13, v8, v16
	v_min_f32_e32 v8, v8, v16
	v_max_f32_e32 v16, v17, v7
	v_min_f32_e32 v7, v17, v7
	v_max_f32_e32 v17, v12, v11
	v_min_f32_e32 v11, v12, v11
	v_max_f32_e32 v12, v3, v9
	v_min_f32_e32 v3, v3, v9
	v_max_f32_e32 v9, v4, v2
	v_min_f32_e32 v2, v4, v2
	v_max_f32_e32 v4, v5, v15
	v_min_f32_e32 v5, v5, v15
	v_max_f32_e32 v15, v6, v14
	v_min_f32_e32 v6, v6, v14
	v_max_f32_e32 v14, v18, v13
	v_min_f32_e32 v13, v18, v13
	v_max_f32_e32 v18, v10, v8
	v_min_f32_e32 v8, v10, v8
	v_max_f32_e32 v10, v16, v17
	v_min_f32_e32 v16, v16, v17
	v_max_f32_e32 v17, v7, v11
	v_min_f32_e32 v7, v7, v11
	v_max_f32_e32 v11, v12, v9
	v_min_f32_e32 v9, v12, v9
	v_max_f32_e32 v12, v3, v2
	v_min_f32_e32 v2, v3, v2
	ds_bpermute_b32 v3, v99, v2
	ds_bpermute_b32 v19, v99, v12
	ds_bpermute_b32 v20, v99, v9
	ds_bpermute_b32 v21, v99, v11
	ds_bpermute_b32 v22, v99, v7
	ds_bpermute_b32 v23, v99, v17
	s_waitcnt lgkmcnt(5)
	ds_bpermute_b32 v24, v99, v16
	ds_bpermute_b32 v33, v99, v4
	v_max_f32_e32 v3, v4, v3
	s_waitcnt lgkmcnt(6)
	ds_bpermute_b32 v25, v99, v10
	ds_bpermute_b32 v32, v99, v5
	v_max_f32_e32 v4, v5, v19
	s_waitcnt lgkmcnt(7)
	ds_bpermute_b32 v26, v99, v8
	ds_bpermute_b32 v31, v99, v15
	v_max_f32_e32 v5, v15, v20
	s_waitcnt lgkmcnt(8)
	ds_bpermute_b32 v27, v99, v18
	ds_bpermute_b32 v30, v99, v6
	v_max_f32_e32 v6, v6, v21
	s_waitcnt lgkmcnt(9)
	ds_bpermute_b32 v28, v99, v13
	ds_bpermute_b32 v29, v99, v14
	v_max_f32_e32 v14, v14, v22
	s_waitcnt lgkmcnt(10)
	v_max_f32_e32 v13, v13, v23
	s_waitcnt lgkmcnt(9)
	v_max_f32_e32 v15, v18, v24
	s_waitcnt lgkmcnt(7)
	v_max_f32_e32 v8, v8, v25
	s_waitcnt lgkmcnt(5)
	v_max_f32_e32 v10, v10, v26
	s_waitcnt lgkmcnt(3)
	v_max_f32_e32 v16, v16, v27
	s_waitcnt lgkmcnt(1)
	v_max_f32_e32 v17, v17, v28
	s_waitcnt lgkmcnt(0)
	v_max_f32_e32 v7, v7, v29
	v_max_f32_e32 v11, v11, v30
	v_max_f32_e32 v9, v9, v31
	v_max_f32_e32 v12, v12, v32
	v_max_f32_e32 v2, v2, v33
	v_max_f32_e32 v18, v3, v10
	v_min_f32_e32 v3, v3, v10
	v_max_f32_e32 v10, v4, v16
	v_min_f32_e32 v4, v4, v16
	v_max_f32_e32 v16, v5, v17
	v_min_f32_e32 v5, v5, v17
	v_max_f32_e32 v17, v6, v7
	v_min_f32_e32 v6, v6, v7
	v_max_f32_e32 v7, v14, v11
	v_min_f32_e32 v11, v14, v11
	v_max_f32_e32 v14, v13, v9
	v_min_f32_e32 v9, v13, v9
	v_max_f32_e32 v13, v15, v12
	v_min_f32_e32 v12, v15, v12
	v_max_f32_e32 v15, v8, v2
	v_min_f32_e32 v2, v8, v2
	v_max_f32_e32 v8, v18, v7
	v_min_f32_e32 v7, v18, v7
	v_max_f32_e32 v18, v10, v14
	v_min_f32_e32 v10, v10, v14
	v_max_f32_e32 v14, v16, v13
	v_min_f32_e32 v13, v16, v13
	v_max_f32_e32 v16, v17, v15
	v_min_f32_e32 v15, v17, v15
	v_max_f32_e32 v17, v3, v11
	v_min_f32_e32 v3, v3, v11
	v_max_f32_e32 v11, v4, v9
	v_min_f32_e32 v4, v4, v9
	v_max_f32_e32 v9, v5, v12
	v_min_f32_e32 v5, v5, v12
	v_max_f32_e32 v12, v6, v2
	v_min_f32_e32 v2, v6, v2
	v_max_f32_e32 v6, v8, v14
	v_min_f32_e32 v8, v8, v14
	v_max_f32_e32 v14, v18, v16
	v_min_f32_e32 v16, v18, v16
	v_max_f32_e32 v18, v7, v13
	v_max_f32_e32 v19, v10, v15
	s_movk_i32 s0, 0x7f
	v_min_f32_e32 v13, v7, v13
	v_min_f32_e32 v10, v10, v15
	v_max_f32_e32 v15, v17, v9
	v_min_f32_e32 v21, v17, v9
	v_max_f32_e32 v17, v11, v12
	v_min_f32_e32 v22, v11, v12
	v_max_f32_e32 v23, v3, v5
	v_min_f32_e32 v3, v3, v5
	v_max_f32_e32 v5, v4, v2
	v_min_f32_e32 v24, v4, v2
	v_max_f32_e32 v9, v18, v19
	v_min_f32_e32 v12, v18, v19
	v_and_b32_sdwa v18, v63, s0 dst_sel:BYTE_1 dst_unused:UNUSED_PAD src0_sel:DWORD src1_sel:DWORD
	v_max_f32_e32 v2, v6, v14
	v_min_f32_e32 v4, v6, v14
	v_max_f32_e32 v11, v13, v10
	v_min_f32_e32 v10, v13, v10
	v_max_f32_e32 v14, v23, v5
	v_min_f32_e32 v13, v23, v5
	v_max_f32_e32 v6, v3, v24
	v_min_f32_e32 v5, v3, v24
	v_and_b32_sdwa v3, v75, s0 dst_sel:BYTE_1 dst_unused:UNUSED_PAD src0_sel:DWORD src1_sel:DWORD
	v_bitop3_b16 v18, v71, v18, s0 bitop3:0xec
	v_bitop3_b16 v3, v79, v3, s0 bitop3:0xec
	v_lshlrev_b32_e32 v18, 16, v18
	v_or_b32_sdwa v23, v3, v18 dst_sel:DWORD dst_unused:UNUSED_PAD src0_sel:WORD_0 src1_sel:DWORD
	v_and_b32_sdwa v18, v83, s0 dst_sel:BYTE_1 dst_unused:UNUSED_PAD src0_sel:DWORD src1_sel:DWORD
; DEV void ce(float& a, float& b) { float hi = fmaxf(a, b), lo = fminf(a, b); a = hi; b = lo; }
; DEV void phase_peer_score(const Params& p, int layer, int M, char* smem) {
;     ...
; #pragma unroll
;     for (int i = 0; i < 16; i++) R[i] = -3.0e38f;
; #pragma unroll
;     for (int i = 0; i < 16; i++)
; #pragma unroll
;       for (int j = 0; j < 16; j++)
;         if ((i + 1) * (j + 1) <= 16) {
;           float v = L0[i] + L1[j];
;           v = __uint_as_float((__float_as_uint(v) & ~255u) | (unsigned)(i * 16 + j));
; #pragma unroll
;           for (int t = 0; t < 16; t++)
;             if (t >= (i + 1) * (j + 1) - 1) ce(R[t], v);
;         }
;     unsigned char* tab = (unsigned char*)smem + 73728 + (w * 16 + l15) * 32;
; #pragma unroll
;     for (int i = 0; i < 16; i++) { tab[i] = (unsigned char)(__float_as_uint(L0[i]) & 127u); tab[16 + i] = (unsigned char)(__float_as_uint(L1[i]) & 127u); }
	v_and_b32_sdwa v3, v91, s0 dst_sel:BYTE_1 dst_unused:UNUSED_PAD src0_sel:DWORD src1_sel:DWORD
	v_bitop3_b16 v18, v87, v18, s0 bitop3:0xec
	v_bitop3_b16 v3, v100, v3, s0 bitop3:0xec
	v_lshlrev_b32_e32 v18, 16, v18
	v_max_f32_e32 v7, v8, v16
	v_min_f32_e32 v8, v8, v16
	v_max_f32_e32 v20, v15, v17
	v_min_f32_e32 v17, v15, v17
	v_max_f32_e32 v16, v21, v22
	v_min_f32_e32 v15, v21, v22
	v_or_b32_sdwa v22, v3, v18 dst_sel:DWORD dst_unused:UNUSED_PAD src0_sel:WORD_0 src1_sel:DWORD
	v_and_b32_sdwa v18, v10, s0 dst_sel:BYTE_1 dst_unused:UNUSED_PAD src0_sel:DWORD src1_sel:DWORD
	v_and_b32_sdwa v3, v12, s0 dst_sel:BYTE_1 dst_unused:UNUSED_PAD src0_sel:DWORD src1_sel:DWORD
	v_bitop3_b16 v18, v11, v18, s0 bitop3:0xec
	v_bitop3_b16 v3, v9, v3, s0 bitop3:0xec
	v_lshlrev_b32_e32 v18, 16, v18
	v_or_b32_sdwa v27, v3, v18 dst_sel:DWORD dst_unused:UNUSED_PAD src0_sel:WORD_0 src1_sel:DWORD
	v_and_b32_sdwa v18, v8, s0 dst_sel:BYTE_1 dst_unused:UNUSED_PAD src0_sel:DWORD src1_sel:DWORD
	v_and_b32_sdwa v3, v4, s0 dst_sel:BYTE_1 dst_unused:UNUSED_PAD src0_sel:DWORD src1_sel:DWORD
	v_bitop3_b16 v18, v7, v18, s0 bitop3:0xec
	v_bitop3_b16 v3, v2, v3, s0 bitop3:0xec
	v_lshlrev_b32_e32 v18, 16, v18
	v_or_b32_sdwa v26, v3, v18 dst_sel:DWORD dst_unused:UNUSED_PAD src0_sel:WORD_0 src1_sel:DWORD
	v_and_b32_sdwa v18, v0, s0 dst_sel:BYTE_1 dst_unused:UNUSED_PAD src0_sel:DWORD src1_sel:DWORD
	v_and_b32_sdwa v3, v39, s0 dst_sel:BYTE_1 dst_unused:UNUSED_PAD src0_sel:DWORD src1_sel:DWORD
	v_bitop3_b16 v18, v43, v18, s0 bitop3:0xec
	v_bitop3_b16 v3, v51, v3, s0 bitop3:0xec
	v_lshlrev_b32_e32 v18, 16, v18
	v_or_b32_sdwa v25, v3, v18 dst_sel:DWORD dst_unused:UNUSED_PAD src0_sel:WORD_0 src1_sel:DWORD
	v_and_b32_sdwa v18, v47, s0 dst_sel:BYTE_1 dst_unused:UNUSED_PAD src0_sel:DWORD src1_sel:DWORD
	v_and_b32_sdwa v3, v59, s0 dst_sel:BYTE_1 dst_unused:UNUSED_PAD src0_sel:DWORD src1_sel:DWORD
	v_bitop3_b16 v18, v55, v18, s0 bitop3:0xec
	v_bitop3_b16 v3, v67, v3, s0 bitop3:0xec
	v_lshlrev_b32_e32 v18, 16, v18
	v_or_b32_sdwa v24, v3, v18 dst_sel:DWORD dst_unused:UNUSED_PAD src0_sel:WORD_0 src1_sel:DWORD
	v_and_b32_sdwa v18, v5, s0 dst_sel:BYTE_1 dst_unused:UNUSED_PAD src0_sel:DWORD src1_sel:DWORD
	v_and_b32_sdwa v3, v13, s0 dst_sel:BYTE_1 dst_unused:UNUSED_PAD src0_sel:DWORD src1_sel:DWORD
	v_bitop3_b16 v18, v6, v18, s0 bitop3:0xec
	v_bitop3_b16 v3, v14, v3, s0 bitop3:0xec
	v_lshlrev_b32_e32 v18, 16, v18
	v_or_b32_sdwa v29, v3, v18 dst_sel:DWORD dst_unused:UNUSED_PAD src0_sel:WORD_0 src1_sel:DWORD
	v_and_b32_sdwa v18, v15, s0 dst_sel:BYTE_1 dst_unused:UNUSED_PAD src0_sel:DWORD src1_sel:DWORD
	v_and_b32_sdwa v3, v17, s0 dst_sel:BYTE_1 dst_unused:UNUSED_PAD src0_sel:DWORD src1_sel:DWORD
	v_bitop3_b16 v18, v16, v18, s0 bitop3:0xec
	v_bitop3_b16 v3, v20, v3, s0 bitop3:0xec
	v_lshlrev_b32_e32 v18, 16, v18
	v_or_b32_sdwa v28, v3, v18 dst_sel:DWORD dst_unused:UNUSED_PAD src0_sel:WORD_0 src1_sel:DWORD
	ds_write_b128 v138, v[22:25]
	ds_write_b128 v138, v[26:29] offset:16
	s_and_saveexec_b64 s[14:15], s[38:39]
	s_cbranch_execz .LBB0_162
	s_movk_i32 s0, 0xff00
	v_add_f32_e32 v164, v100, v2
	v_and_or_b32 v164, v164, s0, 0
	v_max_f32_e32 v148, 0xff61b1e6, v164
	v_add_f32_e32 v164, v100, v4
	v_and_or_b32 v164, v164, s0, 1
	v_max_f32_e32 v149, 0xff61b1e6, v164
	v_add_f32_e32 v164, v100, v7
	v_and_or_b32 v164, v164, s0, 2
	v_max_f32_e32 v150, 0xff61b1e6, v164
	v_add_f32_e32 v164, v100, v8
	v_and_or_b32 v164, v164, s0, 3
	v_max_f32_e32 v151, 0xff61b1e6, v164
	v_add_f32_e32 v164, v100, v9
	v_and_or_b32 v164, v164, s0, 4
	v_max_f32_e32 v152, 0xff61b1e6, v164
	v_add_f32_e32 v164, v100, v12
	v_and_or_b32 v164, v164, s0, 5
	v_max_f32_e32 v153, 0xff61b1e6, v164
	v_add_f32_e32 v164, v100, v11
	v_and_or_b32 v164, v164, s0, 6
	v_max_f32_e32 v154, 0xff61b1e6, v164
	v_add_f32_e32 v164, v100, v10
	v_and_or_b32 v164, v164, s0, 7
	v_max_f32_e32 v155, 0xff61b1e6, v164
	v_add_f32_e32 v164, v100, v20
	v_and_or_b32 v164, v164, s0, 8
	v_max_f32_e32 v156, 0xff61b1e6, v164
	v_add_f32_e32 v164, v100, v17
	v_and_or_b32 v164, v164, s0, 9
	v_max_f32_e32 v157, 0xff61b1e6, v164
	v_add_f32_e32 v164, v100, v16
	v_and_or_b32 v164, v164, s0, 10
	v_max_f32_e32 v158, 0xff61b1e6, v164
	v_add_f32_e32 v164, v100, v15
	v_and_or_b32 v164, v164, s0, 11
	v_max_f32_e32 v159, 0xff61b1e6, v164
	v_add_f32_e32 v164, v100, v14
	v_and_or_b32 v164, v164, s0, 12
	v_max_f32_e32 v160, 0xff61b1e6, v164
	v_add_f32_e32 v164, v100, v13
	v_and_or_b32 v164, v164, s0, 13
	v_max_f32_e32 v161, 0xff61b1e6, v164
	v_add_f32_e32 v164, v100, v6
	v_and_or_b32 v164, v164, s0, 14
	v_max_f32_e32 v162, 0xff61b1e6, v164
	v_add_f32_e32 v164, v100, v5
	v_and_or_b32 v164, v164, s0, 15
	v_max_f32_e32 v163, 0xff61b1e6, v164
	v_min_f32_e32 v164, v148, v149
	v_max_f32_e32 v148, v148, v149
	v_mov_b32_e32 v149, v164
	v_min_f32_e32 v164, v149, v150
	v_max_f32_e32 v149, v149, v150
	v_mov_b32_e32 v150, v164
	v_min_f32_e32 v164, v150, v151
	v_max_f32_e32 v150, v150, v151
	v_mov_b32_e32 v151, v164
	v_min_f32_e32 v164, v151, v152
	v_max_f32_e32 v151, v151, v152
	v_mov_b32_e32 v152, v164
	v_min_f32_e32 v164, v152, v153
	v_max_f32_e32 v152, v152, v153
	v_mov_b32_e32 v153, v164
	v_min_f32_e32 v164, v153, v154
	v_max_f32_e32 v153, v153, v154
	v_mov_b32_e32 v154, v164
	v_min_f32_e32 v164, v154, v155
	v_max_f32_e32 v154, v154, v155
	v_mov_b32_e32 v155, v164
	v_min_f32_e32 v164, v155, v156
	v_max_f32_e32 v155, v155, v156
	v_mov_b32_e32 v156, v164
	v_min_f32_e32 v164, v156, v157
	v_max_f32_e32 v156, v156, v157
	v_mov_b32_e32 v157, v164
	v_min_f32_e32 v164, v157, v158
	v_max_f32_e32 v157, v157, v158
	v_mov_b32_e32 v158, v164
	v_min_f32_e32 v164, v158, v159
	v_max_f32_e32 v158, v158, v159
; DEV void ce(float& a, float& b) { float hi = fmaxf(a, b), lo = fminf(a, b); a = hi; b = lo; }
; DEV void phase_peer_score(const Params& p, int layer, int M, char* smem) {
;     ...
; #pragma unroll
;     for (int i = 0; i < 16; i++)
; #pragma unroll
;       for (int j = 0; j < 16; j++)
;         if ((i + 1) * (j + 1) <= 16) {
;           float v = L0[i] + L1[j];
;           v = __uint_as_float((__float_as_uint(v) & ~255u) | (unsigned)(i * 16 + j));
; #pragma unroll
;           for (int t = 0; t < 16; t++)
;             if (t >= (i + 1) * (j + 1) - 1) ce(R[t], v);
;         }
	v_mov_b32_e32 v159, v164
	v_min_f32_e32 v164, v159, v160
	v_max_f32_e32 v159, v159, v160
	v_mov_b32_e32 v160, v164
	v_min_f32_e32 v164, v160, v161
	v_max_f32_e32 v160, v160, v161
	v_mov_b32_e32 v161, v164
	v_min_f32_e32 v164, v161, v162
	v_max_f32_e32 v161, v161, v162
	v_mov_b32_e32 v162, v164
	v_min_f32_e32 v164, v162, v163
	v_max_f32_e32 v162, v162, v163
	v_mov_b32_e32 v163, v164
	v_add_f32_e32 v164, v91, v2
	v_and_or_b32 v164, v164, s0, 16
	v_med3_f32 v163, v162, v163, v164
	v_med3_f32 v162, v161, v162, v164
	v_med3_f32 v161, v160, v161, v164
	v_med3_f32 v160, v159, v160, v164
	v_med3_f32 v159, v158, v159, v164
	v_med3_f32 v158, v157, v158, v164
	v_med3_f32 v157, v156, v157, v164
	v_med3_f32 v156, v155, v156, v164
	v_med3_f32 v155, v154, v155, v164
	v_med3_f32 v154, v153, v154, v164
	v_med3_f32 v153, v152, v153, v164
	v_med3_f32 v152, v151, v152, v164
	v_med3_f32 v151, v150, v151, v164
	v_med3_f32 v150, v149, v150, v164
	v_med3_f32 v149, v148, v149, v164
	v_max_f32_e32 v148, v148, v164
	v_add_f32_e32 v164, v91, v4
	v_and_or_b32 v164, v164, s0, 17
	v_med3_f32 v163, v162, v163, v164
	v_med3_f32 v162, v161, v162, v164
	v_med3_f32 v161, v160, v161, v164
	v_med3_f32 v160, v159, v160, v164
	v_med3_f32 v159, v158, v159, v164
	v_med3_f32 v158, v157, v158, v164
	v_med3_f32 v157, v156, v157, v164
	v_med3_f32 v156, v155, v156, v164
	v_med3_f32 v155, v154, v155, v164
	v_med3_f32 v154, v153, v154, v164
	v_med3_f32 v153, v152, v153, v164
	v_med3_f32 v152, v151, v152, v164
	v_med3_f32 v151, v150, v151, v164
	v_max_f32_e32 v150, v150, v164
	v_add_f32_e32 v164, v91, v7
	v_and_or_b32 v164, v164, s0, 18
	v_med3_f32 v163, v162, v163, v164
	v_med3_f32 v162, v161, v162, v164
	v_med3_f32 v161, v160, v161, v164
	v_med3_f32 v160, v159, v160, v164
	v_med3_f32 v159, v158, v159, v164
	v_med3_f32 v158, v157, v158, v164
	v_med3_f32 v157, v156, v157, v164
	v_med3_f32 v156, v155, v156, v164
	v_med3_f32 v155, v154, v155, v164
	v_med3_f32 v154, v153, v154, v164
	v_med3_f32 v153, v152, v153, v164
	v_max_f32_e32 v152, v152, v164
	v_add_f32_e32 v164, v91, v8
	v_and_or_b32 v164, v164, s0, 19
	v_med3_f32 v163, v162, v163, v164
	v_med3_f32 v162, v161, v162, v164
	v_med3_f32 v161, v160, v161, v164
	v_med3_f32 v160, v159, v160, v164
	v_med3_f32 v159, v158, v159, v164
	v_med3_f32 v158, v157, v158, v164
	v_med3_f32 v157, v156, v157, v164
	v_med3_f32 v156, v155, v156, v164
	v_med3_f32 v155, v154, v155, v164
	v_max_f32_e32 v154, v154, v164
	v_add_f32_e32 v164, v91, v9
	v_and_or_b32 v164, v164, s0, 20
	v_med3_f32 v163, v162, v163, v164
	v_med3_f32 v162, v161, v162, v164
	v_med3_f32 v161, v160, v161, v164
	v_med3_f32 v160, v159, v160, v164
	v_med3_f32 v159, v158, v159, v164
	v_med3_f32 v158, v157, v158, v164
	v_med3_f32 v157, v156, v157, v164
	v_max_f32_e32 v156, v156, v164
	v_add_f32_e32 v164, v91, v12
	v_and_or_b32 v164, v164, s0, 21
	v_med3_f32 v163, v162, v163, v164
	v_med3_f32 v162, v161, v162, v164
	v_med3_f32 v161, v160, v161, v164
	v_med3_f32 v160, v159, v160, v164
	v_med3_f32 v159, v158, v159, v164
	v_max_f32_e32 v158, v158, v164
	v_add_f32_e32 v164, v91, v11
	v_and_or_b32 v164, v164, s0, 22
	v_med3_f32 v163, v162, v163, v164
	v_med3_f32 v162, v161, v162, v164
	v_med3_f32 v161, v160, v161, v164
	v_max_f32_e32 v160, v160, v164
	v_add_f32_e32 v164, v91, v10
	v_and_or_b32 v164, v164, s0, 23
	v_med3_f32 v163, v162, v163, v164
	v_max_f32_e32 v162, v162, v164
	v_add_f32_e32 v164, v87, v2
	v_and_or_b32 v164, v164, s0, 32
	v_med3_f32 v163, v162, v163, v164
	v_med3_f32 v162, v161, v162, v164
	v_med3_f32 v161, v160, v161, v164
	v_med3_f32 v160, v159, v160, v164
	v_med3_f32 v159, v158, v159, v164
	v_med3_f32 v158, v157, v158, v164
	v_med3_f32 v157, v156, v157, v164
	v_med3_f32 v156, v155, v156, v164
	v_med3_f32 v155, v154, v155, v164
	v_med3_f32 v154, v153, v154, v164
	v_med3_f32 v153, v152, v153, v164
	v_med3_f32 v152, v151, v152, v164
	v_med3_f32 v151, v150, v151, v164
	v_med3_f32 v150, v149, v150, v164
	v_max_f32_e32 v149, v149, v164
	v_add_f32_e32 v164, v87, v4
	v_and_or_b32 v164, v164, s0, 33
	v_med3_f32 v163, v162, v163, v164
	v_med3_f32 v162, v161, v162, v164
	v_med3_f32 v161, v160, v161, v164
	v_med3_f32 v160, v159, v160, v164
	v_med3_f32 v159, v158, v159, v164
	v_med3_f32 v158, v157, v158, v164
	v_med3_f32 v157, v156, v157, v164
	v_med3_f32 v156, v155, v156, v164
	v_med3_f32 v155, v154, v155, v164
	v_med3_f32 v154, v153, v154, v164
	v_med3_f32 v153, v152, v153, v164
	v_max_f32_e32 v152, v152, v164
	v_add_f32_e32 v164, v87, v7
	v_and_or_b32 v164, v164, s0, 34
	v_med3_f32 v163, v162, v163, v164
	v_med3_f32 v162, v161, v162, v164
	v_med3_f32 v161, v160, v161, v164
	v_med3_f32 v160, v159, v160, v164
	v_med3_f32 v159, v158, v159, v164
	v_med3_f32 v158, v157, v158, v164
	v_med3_f32 v157, v156, v157, v164
	v_med3_f32 v156, v155, v156, v164
	v_max_f32_e32 v155, v155, v164
	v_add_f32_e32 v164, v87, v8
	v_and_or_b32 v164, v164, s0, 35
	v_med3_f32 v163, v162, v163, v164
	v_med3_f32 v162, v161, v162, v164
	v_med3_f32 v161, v160, v161, v164
	v_med3_f32 v160, v159, v160, v164
	v_med3_f32 v159, v158, v159, v164
	v_max_f32_e32 v158, v158, v164
	v_add_f32_e32 v164, v87, v9
	v_and_or_b32 v164, v164, s0, 36
	v_med3_f32 v163, v162, v163, v164
	v_med3_f32 v162, v161, v162, v164
	v_max_f32_e32 v161, v161, v164
	v_add_f32_e32 v164, v83, v2
	v_and_or_b32 v164, v164, s0, 48
	v_med3_f32 v163, v162, v163, v164
	v_med3_f32 v162, v161, v162, v164
	v_med3_f32 v161, v160, v161, v164
	v_med3_f32 v160, v159, v160, v164
	v_med3_f32 v159, v158, v159, v164
	v_med3_f32 v158, v157, v158, v164
	v_med3_f32 v157, v156, v157, v164
	v_med3_f32 v156, v155, v156, v164
	v_med3_f32 v155, v154, v155, v164
; DEV void ce(float& a, float& b) { float hi = fmaxf(a, b), lo = fminf(a, b); a = hi; b = lo; }
; DEV void phase_peer_score(const Params& p, int layer, int M, char* smem) {
;     ...
; #pragma unroll
;     for (int i = 0; i < 16; i++)
; #pragma unroll
;       for (int j = 0; j < 16; j++)
;         if ((i + 1) * (j + 1) <= 16) {
;           float v = L0[i] + L1[j];
;           v = __uint_as_float((__float_as_uint(v) & ~255u) | (unsigned)(i * 16 + j));
; #pragma unroll
;           for (int t = 0; t < 16; t++)
;             if (t >= (i + 1) * (j + 1) - 1) ce(R[t], v);
;         }
	v_med3_f32 v154, v153, v154, v164
	v_med3_f32 v153, v152, v153, v164
	v_med3_f32 v152, v151, v152, v164
	v_med3_f32 v151, v150, v151, v164
	v_max_f32_e32 v150, v150, v164
	v_add_f32_e32 v164, v83, v4
	v_and_or_b32 v164, v164, s0, 49
	v_med3_f32 v163, v162, v163, v164
	v_med3_f32 v162, v161, v162, v164
	v_med3_f32 v161, v160, v161, v164
	v_med3_f32 v160, v159, v160, v164
	v_med3_f32 v159, v158, v159, v164
	v_med3_f32 v158, v157, v158, v164
	v_med3_f32 v157, v156, v157, v164
	v_med3_f32 v156, v155, v156, v164
	v_med3_f32 v155, v154, v155, v164
	v_max_f32_e32 v154, v154, v164
	v_add_f32_e32 v164, v83, v7
	v_and_or_b32 v164, v164, s0, 50
	v_med3_f32 v163, v162, v163, v164
	v_med3_f32 v162, v161, v162, v164
	v_med3_f32 v161, v160, v161, v164
	v_med3_f32 v160, v159, v160, v164
	v_med3_f32 v159, v158, v159, v164
	v_max_f32_e32 v158, v158, v164
	v_add_f32_e32 v164, v83, v8
	v_and_or_b32 v164, v164, s0, 51
	v_med3_f32 v163, v162, v163, v164
	v_max_f32_e32 v162, v162, v164
	v_add_f32_e32 v164, v79, v2
	v_and_or_b32 v164, v164, s0, 64
	v_med3_f32 v163, v162, v163, v164
	v_med3_f32 v162, v161, v162, v164
	v_med3_f32 v161, v160, v161, v164
	v_med3_f32 v160, v159, v160, v164
	v_med3_f32 v159, v158, v159, v164
	v_med3_f32 v158, v157, v158, v164
	v_med3_f32 v157, v156, v157, v164
	v_med3_f32 v156, v155, v156, v164
	v_med3_f32 v155, v154, v155, v164
	v_med3_f32 v154, v153, v154, v164
	v_med3_f32 v153, v152, v153, v164
	v_med3_f32 v152, v151, v152, v164
	v_max_f32_e32 v151, v151, v164
	v_add_f32_e32 v164, v79, v4
	v_and_b32_e32 v164, 0xffffff00, v164
	v_or_b32_e32 v164, 0x41, v164
	v_med3_f32 v163, v162, v163, v164
	v_med3_f32 v162, v161, v162, v164
	v_med3_f32 v161, v160, v161, v164
	v_med3_f32 v160, v159, v160, v164
	v_med3_f32 v159, v158, v159, v164
	v_med3_f32 v158, v157, v158, v164
	v_med3_f32 v157, v156, v157, v164
	v_max_f32_e32 v156, v156, v164
	v_add_f32_e32 v164, v79, v7
	v_and_b32_e32 v164, 0xffffff00, v164
	v_or_b32_e32 v164, 0x42, v164
	v_med3_f32 v163, v162, v163, v164
	v_med3_f32 v162, v161, v162, v164
	v_max_f32_e32 v161, v161, v164
	v_add_f32_e32 v164, v75, v2
	v_and_b32_e32 v164, 0xffffff00, v164
	v_or_b32_e32 v164, 0x50, v164
	v_med3_f32 v163, v162, v163, v164
	v_med3_f32 v162, v161, v162, v164
	v_med3_f32 v161, v160, v161, v164
	v_med3_f32 v160, v159, v160, v164
	v_med3_f32 v159, v158, v159, v164
	v_med3_f32 v158, v157, v158, v164
	v_med3_f32 v157, v156, v157, v164
	v_med3_f32 v156, v155, v156, v164
	v_med3_f32 v155, v154, v155, v164
	v_med3_f32 v154, v153, v154, v164
	v_med3_f32 v153, v152, v153, v164
	v_max_f32_e32 v152, v152, v164
	v_add_f32_e32 v164, v75, v4
	v_and_b32_e32 v164, 0xffffff00, v164
	v_or_b32_e32 v164, 0x51, v164
	v_med3_f32 v163, v162, v163, v164
	v_med3_f32 v162, v161, v162, v164
	v_med3_f32 v161, v160, v161, v164
	v_med3_f32 v160, v159, v160, v164
	v_med3_f32 v159, v158, v159, v164
	v_max_f32_e32 v158, v158, v164
	v_add_f32_e32 v164, v71, v2
	v_and_b32_e32 v164, 0xffffff00, v164
	v_or_b32_e32 v164, 0x60, v164
	v_med3_f32 v163, v162, v163, v164
	v_med3_f32 v162, v161, v162, v164
	v_med3_f32 v161, v160, v161, v164
	v_med3_f32 v160, v159, v160, v164
	v_med3_f32 v159, v158, v159, v164
	v_med3_f32 v158, v157, v158, v164
	v_med3_f32 v157, v156, v157, v164
	v_med3_f32 v156, v155, v156, v164
	v_med3_f32 v155, v154, v155, v164
	v_med3_f32 v154, v153, v154, v164
	v_max_f32_e32 v153, v153, v164
	v_add_f32_e32 v164, v71, v4
	v_and_b32_e32 v164, 0xffffff00, v164
	v_or_b32_e32 v164, 0x61, v164
	v_med3_f32 v163, v162, v163, v164
	v_med3_f32 v162, v161, v162, v164
	v_med3_f32 v161, v160, v161, v164
	v_max_f32_e32 v160, v160, v164
	v_add_f32_e32 v164, v63, v2
	v_and_b32_e32 v164, 0xffffff00, v164
	v_or_b32_e32 v164, 0x70, v164
	v_med3_f32 v163, v162, v163, v164
	v_med3_f32 v162, v161, v162, v164
	v_med3_f32 v161, v160, v161, v164
	v_med3_f32 v160, v159, v160, v164
	v_med3_f32 v159, v158, v159, v164
	v_med3_f32 v158, v157, v158, v164
	v_med3_f32 v157, v156, v157, v164
	v_med3_f32 v156, v155, v156, v164
	v_med3_f32 v155, v154, v155, v164
	v_max_f32_e32 v154, v154, v164
	v_add_f32_e32 v164, v63, v4
	v_and_b32_e32 v164, 0xffffff00, v164
	v_or_b32_e32 v164, 0x71, v164
	v_med3_f32 v163, v162, v163, v164
	v_max_f32_e32 v162, v162, v164
	v_add_f32_e32 v164, v67, v2
	v_and_b32_e32 v164, 0xffffff00, v164
	v_or_b32_e32 v164, 0x80, v164
	v_med3_f32 v163, v162, v163, v164
	v_med3_f32 v162, v161, v162, v164
	v_med3_f32 v161, v160, v161, v164
	v_med3_f32 v160, v159, v160, v164
	v_med3_f32 v159, v158, v159, v164
	v_med3_f32 v158, v157, v158, v164
	v_med3_f32 v157, v156, v157, v164
	v_med3_f32 v156, v155, v156, v164
	v_max_f32_e32 v155, v155, v164
	v_add_f32_e32 v164, v59, v2
	v_and_b32_e32 v164, 0xffffff00, v164
	v_or_b32_e32 v164, 0x90, v164
	v_med3_f32 v163, v162, v163, v164
	v_med3_f32 v162, v161, v162, v164
	v_med3_f32 v161, v160, v161, v164
	v_med3_f32 v160, v159, v160, v164
	v_med3_f32 v159, v158, v159, v164
	v_med3_f32 v158, v157, v158, v164
	v_med3_f32 v157, v156, v157, v164
	v_max_f32_e32 v156, v156, v164
	v_add_f32_e32 v164, v55, v2
	v_and_b32_e32 v164, 0xffffff00, v164
	v_or_b32_e32 v164, 0xa0, v164
	v_med3_f32 v163, v162, v163, v164
	v_med3_f32 v162, v161, v162, v164
	v_med3_f32 v161, v160, v161, v164
	v_med3_f32 v160, v159, v160, v164
	v_med3_f32 v159, v158, v159, v164
	v_med3_f32 v158, v157, v158, v164
	v_max_f32_e32 v157, v157, v164
	v_add_f32_e32 v164, v47, v2
	v_and_b32_e32 v164, 0xffffff00, v164
	v_or_b32_e32 v164, 0xb0, v164
	v_med3_f32 v163, v162, v163, v164
	v_med3_f32 v162, v161, v162, v164
	v_med3_f32 v161, v160, v161, v164
	v_med3_f32 v160, v159, v160, v164
	v_med3_f32 v159, v158, v159, v164
	v_max_f32_e32 v158, v158, v164
; DEV void ce(float& a, float& b) { float hi = fmaxf(a, b), lo = fminf(a, b); a = hi; b = lo; }
; DEV void phase_peer_score(const Params& p, int layer, int M, char* smem) {
;     ...
; #pragma unroll
;     for (int i = 0; i < 16; i++)
; #pragma unroll
;       for (int j = 0; j < 16; j++)
;         if ((i + 1) * (j + 1) <= 16) {
;           float v = L0[i] + L1[j];
;           v = __uint_as_float((__float_as_uint(v) & ~255u) | (unsigned)(i * 16 + j));
; #pragma unroll
;           for (int t = 0; t < 16; t++)
;             if (t >= (i + 1) * (j + 1) - 1) ce(R[t], v);
;         }
	v_add_f32_e32 v164, v51, v2
	v_and_b32_e32 v164, 0xffffff00, v164
	v_or_b32_e32 v164, 0xc0, v164
	v_med3_f32 v163, v162, v163, v164
	v_med3_f32 v162, v161, v162, v164
	v_med3_f32 v161, v160, v161, v164
	v_med3_f32 v160, v159, v160, v164
	v_max_f32_e32 v159, v159, v164
	v_add_f32_e32 v164, v39, v2
	v_and_b32_e32 v164, 0xffffff00, v164
	v_or_b32_e32 v164, 0xd0, v164
	v_med3_f32 v163, v162, v163, v164
	v_med3_f32 v162, v161, v162, v164
	v_med3_f32 v161, v160, v161, v164
	v_max_f32_e32 v160, v160, v164
	v_add_f32_e32 v164, v43, v2
	v_and_b32_e32 v164, 0xffffff00, v164
	v_or_b32_e32 v164, 0xe0, v164
	v_med3_f32 v163, v162, v163, v164
	v_med3_f32 v162, v161, v162, v164
	v_max_f32_e32 v161, v161, v164
	v_add_f32_e32 v164, v0, v2
	v_and_b32_e32 v164, 0xffffff00, v164
	v_or_b32_e32 v164, 0xf0, v164
	v_med3_f32 v163, v162, v163, v164
	v_max_f32_e32 v162, v162, v164
	v_cmp_le_f32_e64 s[40:41], v148, v149
	v_cmp_le_f32_e32 vcc, v149, v150
	s_or_b64 s[40:41], s[40:41], vcc
	v_cmp_le_f32_e32 vcc, v150, v151
	s_or_b64 s[40:41], s[40:41], vcc
	v_cmp_le_f32_e32 vcc, v151, v152
	s_or_b64 s[40:41], s[40:41], vcc
	v_cmp_le_f32_e32 vcc, v152, v153
	s_or_b64 s[40:41], s[40:41], vcc
	v_cmp_le_f32_e32 vcc, v153, v154
	s_or_b64 s[40:41], s[40:41], vcc
	v_cmp_le_f32_e32 vcc, v154, v155
	s_or_b64 s[40:41], s[40:41], vcc
	v_cmp_le_f32_e32 vcc, v155, v156
	s_or_b64 s[40:41], s[40:41], vcc
	v_cmp_le_f32_e32 vcc, v156, v157
	s_or_b64 s[40:41], s[40:41], vcc
	v_cmp_le_f32_e32 vcc, v157, v158
	s_or_b64 s[40:41], s[40:41], vcc
	v_cmp_le_f32_e32 vcc, v158, v159
	s_or_b64 s[40:41], s[40:41], vcc
	v_cmp_le_f32_e32 vcc, v159, v160
	s_or_b64 s[40:41], s[40:41], vcc
	v_cmp_le_f32_e32 vcc, v160, v161
	s_or_b64 s[40:41], s[40:41], vcc
	v_cmp_le_f32_e32 vcc, v161, v162
	s_or_b64 s[40:41], s[40:41], vcc
	v_cmp_le_f32_e32 vcc, v162, v163
	s_or_b64 s[40:41], s[40:41], vcc
	s_and_b64 s[40:41], s[40:41], exec
	s_cbranch_scc0 .Lmed3_ok_bb_172
	v_mov_b32_e32 v148, 0xff61b1e6
	v_mov_b32_e32 v149, 0xff61b1e6
	v_mov_b32_e32 v150, 0xff61b1e6
	v_mov_b32_e32 v151, 0xff61b1e6
	v_mov_b32_e32 v152, 0xff61b1e6
	v_mov_b32_e32 v153, 0xff61b1e6
	v_mov_b32_e32 v154, 0xff61b1e6
	v_mov_b32_e32 v155, 0xff61b1e6
	v_mov_b32_e32 v156, 0xff61b1e6
	v_mov_b32_e32 v157, 0xff61b1e6
	v_mov_b32_e32 v158, 0xff61b1e6
	v_mov_b32_e32 v159, 0xff61b1e6
	v_mov_b32_e32 v160, 0xff61b1e6
	v_mov_b32_e32 v161, 0xff61b1e6
	v_mov_b32_e32 v162, 0xff61b1e6
	v_mov_b32_e32 v163, 0xff61b1e6
	v_add_f32_e32 v164, v100, v2
	v_and_or_b32 v164, v164, s0, 0
	v_min_f32_e32 v165, v148, v164
	v_max_f32_e32 v148, v148, v164
	v_min_f32_e32 v164, v149, v165
	v_max_f32_e32 v149, v149, v165
	v_min_f32_e32 v165, v150, v164
	v_max_f32_e32 v150, v150, v164
	v_min_f32_e32 v164, v151, v165
	v_max_f32_e32 v151, v151, v165
	v_min_f32_e32 v165, v152, v164
	v_max_f32_e32 v152, v152, v164
	v_min_f32_e32 v164, v153, v165
	v_max_f32_e32 v153, v153, v165
	v_min_f32_e32 v165, v154, v164
	v_max_f32_e32 v154, v154, v164
	v_min_f32_e32 v164, v155, v165
	v_max_f32_e32 v155, v155, v165
	v_min_f32_e32 v165, v156, v164
	v_max_f32_e32 v156, v156, v164
	v_min_f32_e32 v164, v157, v165
	v_max_f32_e32 v157, v157, v165
	v_min_f32_e32 v165, v158, v164
	v_max_f32_e32 v158, v158, v164
	v_min_f32_e32 v164, v159, v165
	v_max_f32_e32 v159, v159, v165
	v_min_f32_e32 v165, v160, v164
	v_max_f32_e32 v160, v160, v164
	v_min_f32_e32 v164, v161, v165
	v_max_f32_e32 v161, v161, v165
	v_min_f32_e32 v165, v162, v164
	v_max_f32_e32 v162, v162, v164
	v_max_f32_e32 v163, v163, v165
	v_add_f32_e32 v164, v100, v4
	v_and_or_b32 v164, v164, s0, 1
	v_min_f32_e32 v165, v149, v164
	v_max_f32_e32 v149, v149, v164
	v_min_f32_e32 v164, v150, v165
	v_max_f32_e32 v150, v150, v165
	v_min_f32_e32 v165, v151, v164
	v_max_f32_e32 v151, v151, v164
	v_min_f32_e32 v164, v152, v165
	v_max_f32_e32 v152, v152, v165
	v_min_f32_e32 v165, v153, v164
	v_max_f32_e32 v153, v153, v164
	v_min_f32_e32 v164, v154, v165
	v_max_f32_e32 v154, v154, v165
	v_min_f32_e32 v165, v155, v164
	v_max_f32_e32 v155, v155, v164
	v_min_f32_e32 v164, v156, v165
	v_max_f32_e32 v156, v156, v165
	v_min_f32_e32 v165, v157, v164
	v_max_f32_e32 v157, v157, v164
	v_min_f32_e32 v164, v158, v165
	v_max_f32_e32 v158, v158, v165
	v_min_f32_e32 v165, v159, v164
	v_max_f32_e32 v159, v159, v164
	v_min_f32_e32 v164, v160, v165
	v_max_f32_e32 v160, v160, v165
	v_min_f32_e32 v165, v161, v164
	v_max_f32_e32 v161, v161, v164
	v_min_f32_e32 v164, v162, v165
	v_max_f32_e32 v162, v162, v165
	v_max_f32_e32 v163, v163, v164
	v_add_f32_e32 v164, v100, v7
	v_and_or_b32 v164, v164, s0, 2
	v_min_f32_e32 v165, v150, v164
	v_max_f32_e32 v150, v150, v164
	v_min_f32_e32 v164, v151, v165
	v_max_f32_e32 v151, v151, v165
	v_min_f32_e32 v165, v152, v164
	v_max_f32_e32 v152, v152, v164
	v_min_f32_e32 v164, v153, v165
	v_max_f32_e32 v153, v153, v165
	v_min_f32_e32 v165, v154, v164
	v_max_f32_e32 v154, v154, v164
	v_min_f32_e32 v164, v155, v165
	v_max_f32_e32 v155, v155, v165
	v_min_f32_e32 v165, v156, v164
	v_max_f32_e32 v156, v156, v164
	v_min_f32_e32 v164, v157, v165
	v_max_f32_e32 v157, v157, v165
	v_min_f32_e32 v165, v158, v164
	v_max_f32_e32 v158, v158, v164
	v_min_f32_e32 v164, v159, v165
	v_max_f32_e32 v159, v159, v165
	v_min_f32_e32 v165, v160, v164
	v_max_f32_e32 v160, v160, v164
	v_min_f32_e32 v164, v161, v165
	v_max_f32_e32 v161, v161, v165
	v_min_f32_e32 v165, v162, v164
	v_max_f32_e32 v162, v162, v164
	v_max_f32_e32 v163, v163, v165
	v_add_f32_e32 v164, v100, v8
	v_and_or_b32 v164, v164, s0, 3
	v_min_f32_e32 v165, v151, v164
	v_max_f32_e32 v151, v151, v164
	v_min_f32_e32 v164, v152, v165
	v_max_f32_e32 v152, v152, v165
	v_min_f32_e32 v165, v153, v164
; DEV void ce(float& a, float& b) { float hi = fmaxf(a, b), lo = fminf(a, b); a = hi; b = lo; }
; DEV void phase_peer_score(const Params& p, int layer, int M, char* smem) {
;     ...
;     float R[16];
; #pragma unroll
;     for (int i = 0; i < 16; i++) R[i] = -3.0e38f;
; #pragma unroll
;     for (int i = 0; i < 16; i++)
; #pragma unroll
;       for (int j = 0; j < 16; j++)
;         if ((i + 1) * (j + 1) <= 16) {
;           float v = L0[i] + L1[j];
;           v = __uint_as_float((__float_as_uint(v) & ~255u) | (unsigned)(i * 16 + j));
; #pragma unroll
;           for (int t = 0; t < 16; t++)
;             if (t >= (i + 1) * (j + 1) - 1) ce(R[t], v);
;         }
	v_max_f32_e32 v153, v153, v164
	v_min_f32_e32 v164, v154, v165
	v_max_f32_e32 v154, v154, v165
	v_min_f32_e32 v165, v155, v164
	v_max_f32_e32 v155, v155, v164
	v_min_f32_e32 v164, v156, v165
	v_max_f32_e32 v156, v156, v165
	v_min_f32_e32 v165, v157, v164
	v_max_f32_e32 v157, v157, v164
	v_min_f32_e32 v164, v158, v165
	v_max_f32_e32 v158, v158, v165
	v_min_f32_e32 v165, v159, v164
	v_max_f32_e32 v159, v159, v164
	v_min_f32_e32 v164, v160, v165
	v_max_f32_e32 v160, v160, v165
	v_min_f32_e32 v165, v161, v164
	v_max_f32_e32 v161, v161, v164
	v_min_f32_e32 v164, v162, v165
	v_max_f32_e32 v162, v162, v165
	v_max_f32_e32 v163, v163, v164
	v_add_f32_e32 v164, v100, v9
	v_and_or_b32 v164, v164, s0, 4
	v_min_f32_e32 v165, v152, v164
	v_max_f32_e32 v152, v152, v164
	v_min_f32_e32 v164, v153, v165
	v_max_f32_e32 v153, v153, v165
	v_min_f32_e32 v165, v154, v164
	v_max_f32_e32 v154, v154, v164
	v_min_f32_e32 v164, v155, v165
	v_max_f32_e32 v155, v155, v165
	v_min_f32_e32 v165, v156, v164
	v_max_f32_e32 v156, v156, v164
	v_min_f32_e32 v164, v157, v165
	v_max_f32_e32 v157, v157, v165
	v_min_f32_e32 v165, v158, v164
	v_max_f32_e32 v158, v158, v164
	v_min_f32_e32 v164, v159, v165
	v_max_f32_e32 v159, v159, v165
	v_min_f32_e32 v165, v160, v164
	v_max_f32_e32 v160, v160, v164
	v_min_f32_e32 v164, v161, v165
	v_max_f32_e32 v161, v161, v165
	v_min_f32_e32 v165, v162, v164
	v_max_f32_e32 v162, v162, v164
	v_max_f32_e32 v163, v163, v165
	v_add_f32_e32 v164, v100, v12
	v_and_or_b32 v164, v164, s0, 5
	v_min_f32_e32 v165, v153, v164
	v_max_f32_e32 v153, v153, v164
	v_min_f32_e32 v164, v154, v165
	v_max_f32_e32 v154, v154, v165
	v_min_f32_e32 v165, v155, v164
	v_max_f32_e32 v155, v155, v164
	v_min_f32_e32 v164, v156, v165
	v_max_f32_e32 v156, v156, v165
	v_min_f32_e32 v165, v157, v164
	v_max_f32_e32 v157, v157, v164
	v_min_f32_e32 v164, v158, v165
	v_max_f32_e32 v158, v158, v165
	v_min_f32_e32 v165, v159, v164
	v_max_f32_e32 v159, v159, v164
	v_min_f32_e32 v164, v160, v165
	v_max_f32_e32 v160, v160, v165
	v_min_f32_e32 v165, v161, v164
	v_max_f32_e32 v161, v161, v164
	v_min_f32_e32 v164, v162, v165
	v_max_f32_e32 v162, v162, v165
	v_max_f32_e32 v163, v163, v164
	v_add_f32_e32 v164, v100, v11
	v_and_or_b32 v164, v164, s0, 6
	v_min_f32_e32 v165, v154, v164
	v_max_f32_e32 v154, v154, v164
	v_min_f32_e32 v164, v155, v165
	v_max_f32_e32 v155, v155, v165
	v_min_f32_e32 v165, v156, v164
	v_max_f32_e32 v156, v156, v164
	v_min_f32_e32 v164, v157, v165
	v_max_f32_e32 v157, v157, v165
	v_min_f32_e32 v165, v158, v164
	v_max_f32_e32 v158, v158, v164
	v_min_f32_e32 v164, v159, v165
	v_max_f32_e32 v159, v159, v165
	v_min_f32_e32 v165, v160, v164
	v_max_f32_e32 v160, v160, v164
	v_min_f32_e32 v164, v161, v165
	v_max_f32_e32 v161, v161, v165
	v_min_f32_e32 v165, v162, v164
	v_max_f32_e32 v162, v162, v164
	v_max_f32_e32 v163, v163, v165
	v_add_f32_e32 v164, v100, v10
	v_and_or_b32 v164, v164, s0, 7
	v_min_f32_e32 v165, v155, v164
	v_max_f32_e32 v155, v155, v164
	v_min_f32_e32 v164, v156, v165
	v_max_f32_e32 v156, v156, v165
	v_min_f32_e32 v165, v157, v164
	v_max_f32_e32 v157, v157, v164
	v_min_f32_e32 v164, v158, v165
	v_max_f32_e32 v158, v158, v165
	v_min_f32_e32 v165, v159, v164
	v_max_f32_e32 v159, v159, v164
	v_min_f32_e32 v164, v160, v165
	v_max_f32_e32 v160, v160, v165
	v_min_f32_e32 v165, v161, v164
	v_max_f32_e32 v161, v161, v164
	v_min_f32_e32 v164, v162, v165
	v_max_f32_e32 v162, v162, v165
	v_max_f32_e32 v163, v163, v164
	v_add_f32_e32 v164, v100, v20
	v_and_or_b32 v164, v164, s0, 8
	v_min_f32_e32 v165, v156, v164
	v_max_f32_e32 v156, v156, v164
	v_min_f32_e32 v164, v157, v165
	v_max_f32_e32 v157, v157, v165
	v_min_f32_e32 v165, v158, v164
	v_max_f32_e32 v158, v158, v164
	v_min_f32_e32 v164, v159, v165
	v_max_f32_e32 v159, v159, v165
	v_min_f32_e32 v165, v160, v164
	v_max_f32_e32 v160, v160, v164
	v_min_f32_e32 v164, v161, v165
	v_max_f32_e32 v161, v161, v165
	v_min_f32_e32 v165, v162, v164
	v_max_f32_e32 v162, v162, v164
	v_max_f32_e32 v163, v163, v165
	v_add_f32_e32 v164, v100, v17
	v_and_or_b32 v164, v164, s0, 9
	v_min_f32_e32 v165, v157, v164
	v_max_f32_e32 v157, v157, v164
	v_min_f32_e32 v164, v158, v165
	v_max_f32_e32 v158, v158, v165
	v_min_f32_e32 v165, v159, v164
	v_max_f32_e32 v159, v159, v164
	v_min_f32_e32 v164, v160, v165
	v_max_f32_e32 v160, v160, v165
	v_min_f32_e32 v165, v161, v164
	v_max_f32_e32 v161, v161, v164
	v_min_f32_e32 v164, v162, v165
	v_max_f32_e32 v162, v162, v165
	v_max_f32_e32 v163, v163, v164
	v_add_f32_e32 v164, v100, v16
	v_and_or_b32 v164, v164, s0, 10
	v_min_f32_e32 v165, v158, v164
	v_max_f32_e32 v158, v158, v164
	v_min_f32_e32 v164, v159, v165
	v_max_f32_e32 v159, v159, v165
	v_min_f32_e32 v165, v160, v164
	v_max_f32_e32 v160, v160, v164
	v_min_f32_e32 v164, v161, v165
	v_max_f32_e32 v161, v161, v165
	v_min_f32_e32 v165, v162, v164
	v_max_f32_e32 v162, v162, v164
	v_max_f32_e32 v163, v163, v165
	v_add_f32_e32 v164, v100, v15
	v_and_or_b32 v164, v164, s0, 11
	v_min_f32_e32 v165, v159, v164
	v_max_f32_e32 v159, v159, v164
	v_min_f32_e32 v164, v160, v165
	v_max_f32_e32 v160, v160, v165
	v_min_f32_e32 v165, v161, v164
	v_max_f32_e32 v161, v161, v164
	v_min_f32_e32 v164, v162, v165
	v_max_f32_e32 v162, v162, v165
	v_max_f32_e32 v163, v163, v164
	v_add_f32_e32 v164, v100, v14
	v_and_or_b32 v164, v164, s0, 12
	v_min_f32_e32 v165, v160, v164
	v_max_f32_e32 v160, v160, v164
	v_min_f32_e32 v164, v161, v165
	v_max_f32_e32 v161, v161, v165
	v_min_f32_e32 v165, v162, v164
	v_max_f32_e32 v162, v162, v164
	v_max_f32_e32 v163, v163, v165
	v_add_f32_e32 v164, v100, v13
	v_and_or_b32 v164, v164, s0, 13
	v_min_f32_e32 v165, v161, v164
; DEV void ce(float& a, float& b) { float hi = fmaxf(a, b), lo = fminf(a, b); a = hi; b = lo; }
; DEV void phase_peer_score(const Params& p, int layer, int M, char* smem) {
;     ...
;     float R[16];
; #pragma unroll
;     for (int i = 0; i < 16; i++) R[i] = -3.0e38f;
; #pragma unroll
;     for (int i = 0; i < 16; i++)
; #pragma unroll
;       for (int j = 0; j < 16; j++)
;         if ((i + 1) * (j + 1) <= 16) {
;           float v = L0[i] + L1[j];
;           v = __uint_as_float((__float_as_uint(v) & ~255u) | (unsigned)(i * 16 + j));
; #pragma unroll
;           for (int t = 0; t < 16; t++)
;             if (t >= (i + 1) * (j + 1) - 1) ce(R[t], v);
;         }
	v_max_f32_e32 v161, v161, v164
	v_min_f32_e32 v164, v162, v165
	v_max_f32_e32 v162, v162, v165
	v_max_f32_e32 v163, v163, v164
	v_add_f32_e32 v164, v100, v6
	v_and_or_b32 v164, v164, s0, 14
	v_min_f32_e32 v165, v162, v164
	v_max_f32_e32 v162, v162, v164
	v_max_f32_e32 v163, v163, v165
	v_add_f32_e32 v164, v100, v5
	v_and_or_b32 v164, v164, s0, 15
	v_max_f32_e32 v163, v163, v164
	v_add_f32_e32 v164, v91, v2
	v_and_or_b32 v164, v164, s0, 16
	v_min_f32_e32 v165, v149, v164
	v_max_f32_e32 v149, v149, v164
	v_min_f32_e32 v164, v150, v165
	v_max_f32_e32 v150, v150, v165
	v_min_f32_e32 v165, v151, v164
	v_max_f32_e32 v151, v151, v164
	v_min_f32_e32 v164, v152, v165
	v_max_f32_e32 v152, v152, v165
	v_min_f32_e32 v165, v153, v164
	v_max_f32_e32 v153, v153, v164
	v_min_f32_e32 v164, v154, v165
	v_max_f32_e32 v154, v154, v165
	v_min_f32_e32 v165, v155, v164
	v_max_f32_e32 v155, v155, v164
	v_min_f32_e32 v164, v156, v165
	v_max_f32_e32 v156, v156, v165
	v_min_f32_e32 v165, v157, v164
	v_max_f32_e32 v157, v157, v164
	v_min_f32_e32 v164, v158, v165
	v_max_f32_e32 v158, v158, v165
	v_min_f32_e32 v165, v159, v164
	v_max_f32_e32 v159, v159, v164
	v_min_f32_e32 v164, v160, v165
	v_max_f32_e32 v160, v160, v165
	v_min_f32_e32 v165, v161, v164
	v_max_f32_e32 v161, v161, v164
	v_min_f32_e32 v164, v162, v165
	v_max_f32_e32 v162, v162, v165
	v_max_f32_e32 v163, v163, v164
	v_add_f32_e32 v164, v91, v4
	v_and_or_b32 v164, v164, s0, 17
	v_min_f32_e32 v165, v151, v164
	v_max_f32_e32 v151, v151, v164
	v_min_f32_e32 v164, v152, v165
	v_max_f32_e32 v152, v152, v165
	v_min_f32_e32 v165, v153, v164
	v_max_f32_e32 v153, v153, v164
	v_min_f32_e32 v164, v154, v165
	v_max_f32_e32 v154, v154, v165
	v_min_f32_e32 v165, v155, v164
	v_max_f32_e32 v155, v155, v164
	v_min_f32_e32 v164, v156, v165
	v_max_f32_e32 v156, v156, v165
	v_min_f32_e32 v165, v157, v164
	v_max_f32_e32 v157, v157, v164
	v_min_f32_e32 v164, v158, v165
	v_max_f32_e32 v158, v158, v165
	v_min_f32_e32 v165, v159, v164
	v_max_f32_e32 v159, v159, v164
	v_min_f32_e32 v164, v160, v165
	v_max_f32_e32 v160, v160, v165
	v_min_f32_e32 v165, v161, v164
	v_max_f32_e32 v161, v161, v164
	v_min_f32_e32 v164, v162, v165
	v_max_f32_e32 v162, v162, v165
	v_max_f32_e32 v163, v163, v164
	v_add_f32_e32 v164, v91, v7
	v_and_or_b32 v164, v164, s0, 18
	v_min_f32_e32 v165, v153, v164
	v_max_f32_e32 v153, v153, v164
	v_min_f32_e32 v164, v154, v165
	v_max_f32_e32 v154, v154, v165
	v_min_f32_e32 v165, v155, v164
	v_max_f32_e32 v155, v155, v164
	v_min_f32_e32 v164, v156, v165
	v_max_f32_e32 v156, v156, v165
	v_min_f32_e32 v165, v157, v164
	v_max_f32_e32 v157, v157, v164
	v_min_f32_e32 v164, v158, v165
	v_max_f32_e32 v158, v158, v165
	v_min_f32_e32 v165, v159, v164
	v_max_f32_e32 v159, v159, v164
	v_min_f32_e32 v164, v160, v165
	v_max_f32_e32 v160, v160, v165
	v_min_f32_e32 v165, v161, v164
	v_max_f32_e32 v161, v161, v164
	v_min_f32_e32 v164, v162, v165
	v_max_f32_e32 v162, v162, v165
	v_max_f32_e32 v163, v163, v164
	v_add_f32_e32 v164, v91, v8
	v_and_or_b32 v164, v164, s0, 19
	v_min_f32_e32 v165, v155, v164
	v_max_f32_e32 v155, v155, v164
	v_min_f32_e32 v164, v156, v165
	v_max_f32_e32 v156, v156, v165
	v_min_f32_e32 v165, v157, v164
	v_max_f32_e32 v157, v157, v164
	v_min_f32_e32 v164, v158, v165
	v_max_f32_e32 v158, v158, v165
	v_min_f32_e32 v165, v159, v164
	v_max_f32_e32 v159, v159, v164
	v_min_f32_e32 v164, v160, v165
	v_max_f32_e32 v160, v160, v165
	v_min_f32_e32 v165, v161, v164
	v_max_f32_e32 v161, v161, v164
	v_min_f32_e32 v164, v162, v165
	v_max_f32_e32 v162, v162, v165
	v_max_f32_e32 v163, v163, v164
	v_add_f32_e32 v164, v91, v9
	v_and_or_b32 v164, v164, s0, 20
	v_min_f32_e32 v165, v157, v164
	v_max_f32_e32 v157, v157, v164
	v_min_f32_e32 v164, v158, v165
	v_max_f32_e32 v158, v158, v165
	v_min_f32_e32 v165, v159, v164
	v_max_f32_e32 v159, v159, v164
	v_min_f32_e32 v164, v160, v165
	v_max_f32_e32 v160, v160, v165
	v_min_f32_e32 v165, v161, v164
	v_max_f32_e32 v161, v161, v164
	v_min_f32_e32 v164, v162, v165
	v_max_f32_e32 v162, v162, v165
	v_max_f32_e32 v163, v163, v164
	v_add_f32_e32 v164, v91, v12
	v_and_or_b32 v164, v164, s0, 21
	v_min_f32_e32 v165, v159, v164
	v_max_f32_e32 v159, v159, v164
	v_min_f32_e32 v164, v160, v165
	v_max_f32_e32 v160, v160, v165
	v_min_f32_e32 v165, v161, v164
	v_max_f32_e32 v161, v161, v164
	v_min_f32_e32 v164, v162, v165
	v_max_f32_e32 v162, v162, v165
	v_max_f32_e32 v163, v163, v164
	v_add_f32_e32 v164, v91, v11
	v_and_or_b32 v164, v164, s0, 22
	v_min_f32_e32 v165, v161, v164
	v_max_f32_e32 v161, v161, v164
	v_min_f32_e32 v164, v162, v165
	v_max_f32_e32 v162, v162, v165
	v_max_f32_e32 v163, v163, v164
	v_add_f32_e32 v164, v91, v10
	v_and_or_b32 v164, v164, s0, 23
	v_max_f32_e32 v163, v163, v164
	v_add_f32_e32 v164, v87, v2
	v_and_or_b32 v164, v164, s0, 32
	v_min_f32_e32 v165, v150, v164
	v_max_f32_e32 v150, v150, v164
	v_min_f32_e32 v164, v151, v165
	v_max_f32_e32 v151, v151, v165
	v_min_f32_e32 v165, v152, v164
	v_max_f32_e32 v152, v152, v164
	v_min_f32_e32 v164, v153, v165
	v_max_f32_e32 v153, v153, v165
	v_min_f32_e32 v165, v154, v164
	v_max_f32_e32 v154, v154, v164
	v_min_f32_e32 v164, v155, v165
	v_max_f32_e32 v155, v155, v165
	v_min_f32_e32 v165, v156, v164
	v_max_f32_e32 v156, v156, v164
	v_min_f32_e32 v164, v157, v165
	v_max_f32_e32 v157, v157, v165
	v_min_f32_e32 v165, v158, v164
	v_max_f32_e32 v158, v158, v164
	v_min_f32_e32 v164, v159, v165
	v_max_f32_e32 v159, v159, v165
	v_min_f32_e32 v165, v160, v164
	v_max_f32_e32 v160, v160, v164
	v_min_f32_e32 v164, v161, v165
	v_max_f32_e32 v161, v161, v165
	v_min_f32_e32 v165, v162, v164
	v_max_f32_e32 v162, v162, v164
	v_max_f32_e32 v163, v163, v165
; DEV void ce(float& a, float& b) { float hi = fmaxf(a, b), lo = fminf(a, b); a = hi; b = lo; }
; DEV void phase_peer_score(const Params& p, int layer, int M, char* smem) {
;     ...
;     float R[16];
; #pragma unroll
;     for (int i = 0; i < 16; i++) R[i] = -3.0e38f;
; #pragma unroll
;     for (int i = 0; i < 16; i++)
; #pragma unroll
;       for (int j = 0; j < 16; j++)
;         if ((i + 1) * (j + 1) <= 16) {
;           float v = L0[i] + L1[j];
;           v = __uint_as_float((__float_as_uint(v) & ~255u) | (unsigned)(i * 16 + j));
; #pragma unroll
;           for (int t = 0; t < 16; t++)
;             if (t >= (i + 1) * (j + 1) - 1) ce(R[t], v);
;         }
	v_add_f32_e32 v164, v87, v4
	v_and_or_b32 v164, v164, s0, 33
	v_min_f32_e32 v165, v153, v164
	v_max_f32_e32 v153, v153, v164
	v_min_f32_e32 v164, v154, v165
	v_max_f32_e32 v154, v154, v165
	v_min_f32_e32 v165, v155, v164
	v_max_f32_e32 v155, v155, v164
	v_min_f32_e32 v164, v156, v165
	v_max_f32_e32 v156, v156, v165
	v_min_f32_e32 v165, v157, v164
	v_max_f32_e32 v157, v157, v164
	v_min_f32_e32 v164, v158, v165
	v_max_f32_e32 v158, v158, v165
	v_min_f32_e32 v165, v159, v164
	v_max_f32_e32 v159, v159, v164
	v_min_f32_e32 v164, v160, v165
	v_max_f32_e32 v160, v160, v165
	v_min_f32_e32 v165, v161, v164
	v_max_f32_e32 v161, v161, v164
	v_min_f32_e32 v164, v162, v165
	v_max_f32_e32 v162, v162, v165
	v_max_f32_e32 v163, v163, v164
	v_add_f32_e32 v164, v87, v7
	v_and_or_b32 v164, v164, s0, 34
	v_min_f32_e32 v165, v156, v164
	v_max_f32_e32 v156, v156, v164
	v_min_f32_e32 v164, v157, v165
	v_max_f32_e32 v157, v157, v165
	v_min_f32_e32 v165, v158, v164
	v_max_f32_e32 v158, v158, v164
	v_min_f32_e32 v164, v159, v165
	v_max_f32_e32 v159, v159, v165
	v_min_f32_e32 v165, v160, v164
	v_max_f32_e32 v160, v160, v164
	v_min_f32_e32 v164, v161, v165
	v_max_f32_e32 v161, v161, v165
	v_min_f32_e32 v165, v162, v164
	v_max_f32_e32 v162, v162, v164
	v_max_f32_e32 v163, v163, v165
	v_add_f32_e32 v164, v87, v8
	v_and_or_b32 v164, v164, s0, 35
	v_min_f32_e32 v165, v159, v164
	v_max_f32_e32 v159, v159, v164
	v_min_f32_e32 v164, v160, v165
	v_max_f32_e32 v160, v160, v165
	v_min_f32_e32 v165, v161, v164
	v_max_f32_e32 v161, v161, v164
	v_min_f32_e32 v164, v162, v165
	v_max_f32_e32 v162, v162, v165
	v_max_f32_e32 v163, v163, v164
	v_add_f32_e32 v164, v87, v9
	v_and_or_b32 v164, v164, s0, 36
	v_min_f32_e32 v165, v162, v164
	v_max_f32_e32 v162, v162, v164
	v_max_f32_e32 v163, v163, v165
	v_add_f32_e32 v164, v83, v2
	v_and_or_b32 v164, v164, s0, 48
	v_min_f32_e32 v165, v151, v164
	v_max_f32_e32 v151, v151, v164
	v_min_f32_e32 v164, v152, v165
	v_max_f32_e32 v152, v152, v165
	v_min_f32_e32 v165, v153, v164
	v_max_f32_e32 v153, v153, v164
	v_min_f32_e32 v164, v154, v165
	v_max_f32_e32 v154, v154, v165
	v_min_f32_e32 v165, v155, v164
	v_max_f32_e32 v155, v155, v164
	v_min_f32_e32 v164, v156, v165
	v_max_f32_e32 v156, v156, v165
	v_min_f32_e32 v165, v157, v164
	v_max_f32_e32 v157, v157, v164
	v_min_f32_e32 v164, v158, v165
	v_max_f32_e32 v158, v158, v165
	v_min_f32_e32 v165, v159, v164
	v_max_f32_e32 v159, v159, v164
	v_min_f32_e32 v164, v160, v165
	v_max_f32_e32 v160, v160, v165
	v_min_f32_e32 v165, v161, v164
	v_max_f32_e32 v161, v161, v164
	v_min_f32_e32 v164, v162, v165
	v_max_f32_e32 v162, v162, v165
	v_max_f32_e32 v163, v163, v164
	v_add_f32_e32 v164, v83, v4
	v_and_or_b32 v164, v164, s0, 49
	v_min_f32_e32 v165, v155, v164
	v_max_f32_e32 v155, v155, v164
	v_min_f32_e32 v164, v156, v165
	v_max_f32_e32 v156, v156, v165
	v_min_f32_e32 v165, v157, v164
	v_max_f32_e32 v157, v157, v164
	v_min_f32_e32 v164, v158, v165
	v_max_f32_e32 v158, v158, v165
	v_min_f32_e32 v165, v159, v164
	v_max_f32_e32 v159, v159, v164
	v_min_f32_e32 v164, v160, v165
	v_max_f32_e32 v160, v160, v165
	v_min_f32_e32 v165, v161, v164
	v_max_f32_e32 v161, v161, v164
	v_min_f32_e32 v164, v162, v165
	v_max_f32_e32 v162, v162, v165
	v_max_f32_e32 v163, v163, v164
	v_add_f32_e32 v164, v83, v7
	v_and_or_b32 v164, v164, s0, 50
	v_min_f32_e32 v165, v159, v164
	v_max_f32_e32 v159, v159, v164
	v_min_f32_e32 v164, v160, v165
	v_max_f32_e32 v160, v160, v165
	v_min_f32_e32 v165, v161, v164
	v_max_f32_e32 v161, v161, v164
	v_min_f32_e32 v164, v162, v165
	v_max_f32_e32 v162, v162, v165
	v_max_f32_e32 v163, v163, v164
	v_add_f32_e32 v164, v83, v8
	v_and_or_b32 v164, v164, s0, 51
	v_max_f32_e32 v163, v163, v164
	v_add_f32_e32 v164, v79, v2
	v_and_or_b32 v164, v164, s0, 64
	v_min_f32_e32 v165, v152, v164
	v_max_f32_e32 v152, v152, v164
	v_min_f32_e32 v164, v153, v165
	v_max_f32_e32 v153, v153, v165
	v_min_f32_e32 v165, v154, v164
	v_max_f32_e32 v154, v154, v164
	v_min_f32_e32 v164, v155, v165
	v_max_f32_e32 v155, v155, v165
	v_min_f32_e32 v165, v156, v164
	v_max_f32_e32 v156, v156, v164
	v_min_f32_e32 v164, v157, v165
	v_max_f32_e32 v157, v157, v165
	v_min_f32_e32 v165, v158, v164
	v_max_f32_e32 v158, v158, v164
	v_min_f32_e32 v164, v159, v165
	v_max_f32_e32 v159, v159, v165
	v_min_f32_e32 v165, v160, v164
	v_max_f32_e32 v160, v160, v164
	v_min_f32_e32 v164, v161, v165
	v_max_f32_e32 v161, v161, v165
	v_min_f32_e32 v165, v162, v164
	v_max_f32_e32 v162, v162, v164
	v_max_f32_e32 v163, v163, v165
	v_add_f32_e32 v164, v79, v4
	v_and_b32_e32 v164, 0xffffff00, v164
	v_or_b32_e32 v164, 0x41, v164
	v_min_f32_e32 v165, v157, v164
	v_max_f32_e32 v157, v157, v164
	v_min_f32_e32 v164, v158, v165
	v_max_f32_e32 v158, v158, v165
	v_min_f32_e32 v165, v159, v164
	v_max_f32_e32 v159, v159, v164
	v_min_f32_e32 v164, v160, v165
	v_max_f32_e32 v160, v160, v165
	v_min_f32_e32 v165, v161, v164
	v_max_f32_e32 v161, v161, v164
	v_min_f32_e32 v164, v162, v165
	v_max_f32_e32 v162, v162, v165
	v_max_f32_e32 v163, v163, v164
	v_add_f32_e32 v164, v79, v7
	v_and_b32_e32 v164, 0xffffff00, v164
	v_or_b32_e32 v164, 0x42, v164
	v_min_f32_e32 v165, v162, v164
	v_max_f32_e32 v162, v162, v164
	v_max_f32_e32 v163, v163, v165
	v_add_f32_e32 v164, v75, v2
	v_and_b32_e32 v164, 0xffffff00, v164
	v_or_b32_e32 v164, 0x50, v164
	v_min_f32_e32 v165, v153, v164
	v_max_f32_e32 v153, v153, v164
	v_min_f32_e32 v164, v154, v165
	v_max_f32_e32 v154, v154, v165
	v_min_f32_e32 v165, v155, v164
; DEV void ce(float& a, float& b) { float hi = fmaxf(a, b), lo = fminf(a, b); a = hi; b = lo; }
; DEV void phase_peer_score(const Params& p, int layer, int M, char* smem) {
;     ...
;     float R[16];
; #pragma unroll
;     for (int i = 0; i < 16; i++) R[i] = -3.0e38f;
; #pragma unroll
;     for (int i = 0; i < 16; i++)
; #pragma unroll
;       for (int j = 0; j < 16; j++)
;         if ((i + 1) * (j + 1) <= 16) {
;           float v = L0[i] + L1[j];
;           v = __uint_as_float((__float_as_uint(v) & ~255u) | (unsigned)(i * 16 + j));
; #pragma unroll
;           for (int t = 0; t < 16; t++)
;             if (t >= (i + 1) * (j + 1) - 1) ce(R[t], v);
;         }
	v_max_f32_e32 v155, v155, v164
	v_min_f32_e32 v164, v156, v165
	v_max_f32_e32 v156, v156, v165
	v_min_f32_e32 v165, v157, v164
	v_max_f32_e32 v157, v157, v164
	v_min_f32_e32 v164, v158, v165
	v_max_f32_e32 v158, v158, v165
	v_min_f32_e32 v165, v159, v164
	v_max_f32_e32 v159, v159, v164
	v_min_f32_e32 v164, v160, v165
	v_max_f32_e32 v160, v160, v165
	v_min_f32_e32 v165, v161, v164
	v_max_f32_e32 v161, v161, v164
	v_min_f32_e32 v164, v162, v165
	v_max_f32_e32 v162, v162, v165
	v_max_f32_e32 v163, v163, v164
	v_add_f32_e32 v164, v75, v4
	v_and_b32_e32 v164, 0xffffff00, v164
	v_or_b32_e32 v164, 0x51, v164
	v_min_f32_e32 v165, v159, v164
	v_max_f32_e32 v159, v159, v164
	v_min_f32_e32 v164, v160, v165
	v_max_f32_e32 v160, v160, v165
	v_min_f32_e32 v165, v161, v164
	v_max_f32_e32 v161, v161, v164
	v_min_f32_e32 v164, v162, v165
	v_max_f32_e32 v162, v162, v165
	v_max_f32_e32 v163, v163, v164
	v_add_f32_e32 v164, v71, v2
	v_and_b32_e32 v164, 0xffffff00, v164
	v_or_b32_e32 v164, 0x60, v164
	v_min_f32_e32 v165, v154, v164
	v_max_f32_e32 v154, v154, v164
	v_min_f32_e32 v164, v155, v165
	v_max_f32_e32 v155, v155, v165
	v_min_f32_e32 v165, v156, v164
	v_max_f32_e32 v156, v156, v164
	v_min_f32_e32 v164, v157, v165
	v_max_f32_e32 v157, v157, v165
	v_min_f32_e32 v165, v158, v164
	v_max_f32_e32 v158, v158, v164
	v_min_f32_e32 v164, v159, v165
	v_max_f32_e32 v159, v159, v165
	v_min_f32_e32 v165, v160, v164
	v_max_f32_e32 v160, v160, v164
	v_min_f32_e32 v164, v161, v165
	v_max_f32_e32 v161, v161, v165
	v_min_f32_e32 v165, v162, v164
	v_max_f32_e32 v162, v162, v164
	v_max_f32_e32 v163, v163, v165
	v_add_f32_e32 v164, v71, v4
	v_and_b32_e32 v164, 0xffffff00, v164
	v_or_b32_e32 v164, 0x61, v164
	v_min_f32_e32 v165, v161, v164
	v_max_f32_e32 v161, v161, v164
	v_min_f32_e32 v164, v162, v165
	v_max_f32_e32 v162, v162, v165
	v_max_f32_e32 v163, v163, v164
	v_add_f32_e32 v164, v63, v2
	v_and_b32_e32 v164, 0xffffff00, v164
	v_or_b32_e32 v164, 0x70, v164
	v_min_f32_e32 v165, v155, v164
	v_max_f32_e32 v155, v155, v164
	v_min_f32_e32 v164, v156, v165
	v_max_f32_e32 v156, v156, v165
	v_min_f32_e32 v165, v157, v164
	v_max_f32_e32 v157, v157, v164
	v_min_f32_e32 v164, v158, v165
	v_max_f32_e32 v158, v158, v165
	v_min_f32_e32 v165, v159, v164
	v_max_f32_e32 v159, v159, v164
	v_min_f32_e32 v164, v160, v165
	v_max_f32_e32 v160, v160, v165
	v_min_f32_e32 v165, v161, v164
	v_max_f32_e32 v161, v161, v164
	v_min_f32_e32 v164, v162, v165
	v_max_f32_e32 v162, v162, v165
	v_max_f32_e32 v163, v163, v164
	v_add_f32_e32 v164, v63, v4
	v_and_b32_e32 v164, 0xffffff00, v164
	v_or_b32_e32 v164, 0x71, v164
	v_max_f32_e32 v163, v163, v164
	v_add_f32_e32 v164, v67, v2
	v_and_b32_e32 v164, 0xffffff00, v164
	v_or_b32_e32 v164, 0x80, v164
	v_min_f32_e32 v165, v156, v164
	v_max_f32_e32 v156, v156, v164
	v_min_f32_e32 v164, v157, v165
	v_max_f32_e32 v157, v157, v165
	v_min_f32_e32 v165, v158, v164
	v_max_f32_e32 v158, v158, v164
	v_min_f32_e32 v164, v159, v165
	v_max_f32_e32 v159, v159, v165
	v_min_f32_e32 v165, v160, v164
	v_max_f32_e32 v160, v160, v164
	v_min_f32_e32 v164, v161, v165
	v_max_f32_e32 v161, v161, v165
	v_min_f32_e32 v165, v162, v164
	v_max_f32_e32 v162, v162, v164
	v_max_f32_e32 v163, v163, v165
	v_add_f32_e32 v164, v59, v2
	v_and_b32_e32 v164, 0xffffff00, v164
	v_or_b32_e32 v164, 0x90, v164
	v_min_f32_e32 v165, v157, v164
	v_max_f32_e32 v157, v157, v164
	v_min_f32_e32 v164, v158, v165
	v_max_f32_e32 v158, v158, v165
	v_min_f32_e32 v165, v159, v164
	v_max_f32_e32 v159, v159, v164
	v_min_f32_e32 v164, v160, v165
	v_max_f32_e32 v160, v160, v165
	v_min_f32_e32 v165, v161, v164
	v_max_f32_e32 v161, v161, v164
	v_min_f32_e32 v164, v162, v165
	v_max_f32_e32 v162, v162, v165
	v_max_f32_e32 v163, v163, v164
	v_add_f32_e32 v164, v55, v2
	v_and_b32_e32 v164, 0xffffff00, v164
	v_or_b32_e32 v164, 0xa0, v164
	v_min_f32_e32 v165, v158, v164
	v_max_f32_e32 v158, v158, v164
	v_min_f32_e32 v164, v159, v165
	v_max_f32_e32 v159, v159, v165
	v_min_f32_e32 v165, v160, v164
	v_max_f32_e32 v160, v160, v164
	v_min_f32_e32 v164, v161, v165
	v_max_f32_e32 v161, v161, v165
	v_min_f32_e32 v165, v162, v164
	v_max_f32_e32 v162, v162, v164
	v_max_f32_e32 v163, v163, v165
	v_add_f32_e32 v164, v47, v2
	v_and_b32_e32 v164, 0xffffff00, v164
	v_or_b32_e32 v164, 0xb0, v164
	v_min_f32_e32 v165, v159, v164
	v_max_f32_e32 v159, v159, v164
	v_min_f32_e32 v164, v160, v165
	v_max_f32_e32 v160, v160, v165
	v_min_f32_e32 v165, v161, v164
	v_max_f32_e32 v161, v161, v164
	v_min_f32_e32 v164, v162, v165
	v_max_f32_e32 v162, v162, v165
	v_max_f32_e32 v163, v163, v164
	v_add_f32_e32 v164, v51, v2
	v_and_b32_e32 v164, 0xffffff00, v164
	v_or_b32_e32 v164, 0xc0, v164
	v_min_f32_e32 v165, v160, v164
	v_max_f32_e32 v160, v160, v164
	v_min_f32_e32 v164, v161, v165
	v_max_f32_e32 v161, v161, v165
	v_min_f32_e32 v165, v162, v164
	v_max_f32_e32 v162, v162, v164
	v_max_f32_e32 v163, v163, v165
	v_add_f32_e32 v164, v39, v2
	v_and_b32_e32 v164, 0xffffff00, v164
	v_or_b32_e32 v164, 0xd0, v164
	v_min_f32_e32 v165, v161, v164
	v_max_f32_e32 v161, v161, v164
	v_min_f32_e32 v164, v162, v165
	v_max_f32_e32 v162, v162, v165
	v_max_f32_e32 v163, v163, v164
	v_add_f32_e32 v164, v43, v2
	v_and_b32_e32 v164, 0xffffff00, v164
	v_or_b32_e32 v164, 0xe0, v164
	v_min_f32_e32 v165, v162, v164
	v_max_f32_e32 v162, v162, v164
	v_max_f32_e32 v163, v163, v165
	v_add_f32_e32 v164, v0, v2
	v_and_b32_e32 v164, 0xffffff00, v164
	v_or_b32_e32 v164, 0xf0, v164
	v_max_f32_e32 v163, v163, v164

; DEV f32x4 mfma16(bf16x8 a, bf16x8 b, f32x4 c) { return __builtin_amdgcn_mfma_f32_16x16x32_bf16(a, b, c, 0, 0, 0); }
; DEV void peer_top16(const bf16_t* __restrict__ pq, const bf16_t* sk  , float (&l)[16]) {
;     ...
; #pragma unroll 1
;   for (int ks = 0; ks < 4; ks++) {
;     const bf16x8 bqk = *(const bf16x8*)(pq + ks * 32 + quad * 8);
; #pragma unroll
;     for (int nt = 0; nt < 8; nt++) {
;       bf16x8 ak = *(const bf16x8*)(sk + (nt * 16 + l15) * 144 + ks * 32 + quad * 8);
;       acc[nt] = mfma16(ak, bqk, acc[nt]);
;     }
;   }
.LBB0_635:
	v_add_u32_e32 v139, 0x10e00, v122
	ds_read_b128 v[164:167], v122 offset:36864
	ds_read_b128 v[168:171], v122 offset:41472
	ds_read_b128 v[172:175], v122 offset:46080
	ds_read_b128 v[176:179], v122 offset:50688
	ds_read_b128 v[180:183], v122 offset:55296
	ds_read_b128 v[184:187], v122 offset:59904
	ds_read_b128 v[188:191], v122 offset:64512
	ds_read_b128 v[128:131], v139
	s_waitcnt vmcnt(3) lgkmcnt(7)
	v_mfma_f32_16x16x32_bf16 v[30:33], v[164:167], v[148:151], v[30:33]
	ds_read_b128 v[164:167], v122 offset:36928
	s_waitcnt lgkmcnt(7)
	v_mfma_f32_16x16x32_bf16 v[22:25], v[168:171], v[148:151], v[22:25]
	ds_read_b128 v[168:171], v122 offset:41536
	s_waitcnt lgkmcnt(7)
	v_mfma_f32_16x16x32_bf16 v[14:17], v[172:175], v[148:151], v[14:17]
	ds_read_b128 v[172:175], v122 offset:46144
	s_waitcnt lgkmcnt(7)
	v_mfma_f32_16x16x32_bf16 v[6:9], v[176:179], v[148:151], v[6:9]
	ds_read_b128 v[176:179], v122 offset:50752
	s_waitcnt lgkmcnt(7)
	v_mfma_f32_16x16x32_bf16 v[26:29], v[180:183], v[148:151], v[26:29]
	ds_read_b128 v[180:183], v122 offset:55360
	s_waitcnt lgkmcnt(7)
	v_mfma_f32_16x16x32_bf16 v[18:21], v[184:187], v[148:151], v[18:21]
	ds_read_b128 v[184:187], v122 offset:59968
	s_waitcnt lgkmcnt(7)
	v_mfma_f32_16x16x32_bf16 v[10:13], v[188:191], v[148:151], v[10:13]
	ds_read_b128 v[188:191], v122 offset:64576
	s_waitcnt lgkmcnt(7)
	v_mfma_f32_16x16x32_bf16 v[2:5], v[128:131], v[148:151], v[2:5]
	ds_read_b128 v[128:131], v139 offset:64
	s_waitcnt vmcnt(2) lgkmcnt(7)
	v_mfma_f32_16x16x32_bf16 v[30:33], v[164:167], v[152:155], v[30:33]
	ds_read_b128 v[164:167], v122 offset:36992
	s_waitcnt lgkmcnt(7)
	v_mfma_f32_16x16x32_bf16 v[22:25], v[168:171], v[152:155], v[22:25]
	ds_read_b128 v[168:171], v122 offset:41600
	s_waitcnt lgkmcnt(7)
	v_mfma_f32_16x16x32_bf16 v[14:17], v[172:175], v[152:155], v[14:17]
	ds_read_b128 v[172:175], v122 offset:46208
	s_waitcnt lgkmcnt(7)
	v_mfma_f32_16x16x32_bf16 v[6:9], v[176:179], v[152:155], v[6:9]
	ds_read_b128 v[176:179], v122 offset:50816
	s_waitcnt lgkmcnt(7)
	v_mfma_f32_16x16x32_bf16 v[26:29], v[180:183], v[152:155], v[26:29]
	ds_read_b128 v[180:183], v122 offset:55424
	s_waitcnt lgkmcnt(7)
	v_mfma_f32_16x16x32_bf16 v[18:21], v[184:187], v[152:155], v[18:21]
	ds_read_b128 v[184:187], v122 offset:60032
	s_waitcnt lgkmcnt(7)
	v_mfma_f32_16x16x32_bf16 v[10:13], v[188:191], v[152:155], v[10:13]
	ds_read_b128 v[188:191], v122 offset:64640
	s_waitcnt lgkmcnt(7)
	v_mfma_f32_16x16x32_bf16 v[2:5], v[128:131], v[152:155], v[2:5]
	ds_read_b128 v[128:131], v139 offset:128
	s_waitcnt vmcnt(1) lgkmcnt(7)
	v_mfma_f32_16x16x32_bf16 v[30:33], v[164:167], v[156:159], v[30:33]
	ds_read_b128 v[164:167], v122 offset:37056
	s_waitcnt lgkmcnt(7)
	v_mfma_f32_16x16x32_bf16 v[22:25], v[168:171], v[156:159], v[22:25]
	ds_read_b128 v[168:171], v122 offset:41664
	s_waitcnt lgkmcnt(7)
	v_mfma_f32_16x16x32_bf16 v[14:17], v[172:175], v[156:159], v[14:17]
	ds_read_b128 v[172:175], v122 offset:46272
	s_waitcnt lgkmcnt(7)
	v_mfma_f32_16x16x32_bf16 v[6:9], v[176:179], v[156:159], v[6:9]
	ds_read_b128 v[176:179], v122 offset:50880
	s_waitcnt lgkmcnt(7)
	v_mfma_f32_16x16x32_bf16 v[26:29], v[180:183], v[156:159], v[26:29]
	ds_read_b128 v[180:183], v122 offset:55488
	s_waitcnt lgkmcnt(7)
	v_mfma_f32_16x16x32_bf16 v[18:21], v[184:187], v[156:159], v[18:21]
	ds_read_b128 v[184:187], v122 offset:60096
	s_waitcnt lgkmcnt(7)
	v_mfma_f32_16x16x32_bf16 v[10:13], v[188:191], v[156:159], v[10:13]
	ds_read_b128 v[188:191], v122 offset:64704
	s_waitcnt lgkmcnt(7)
	v_mfma_f32_16x16x32_bf16 v[2:5], v[128:131], v[156:159], v[2:5]
	ds_read_b128 v[128:131], v139 offset:192
	s_waitcnt vmcnt(0) lgkmcnt(7)
	v_mfma_f32_16x16x32_bf16 v[30:33], v[164:167], v[160:163], v[30:33]
	s_waitcnt lgkmcnt(6)
	v_mfma_f32_16x16x32_bf16 v[22:25], v[168:171], v[160:163], v[22:25]
	s_waitcnt lgkmcnt(5)
	v_mfma_f32_16x16x32_bf16 v[14:17], v[172:175], v[160:163], v[14:17]
	s_waitcnt lgkmcnt(4)
	v_mfma_f32_16x16x32_bf16 v[6:9], v[176:179], v[160:163], v[6:9]
	s_waitcnt lgkmcnt(3)
	v_mfma_f32_16x16x32_bf16 v[26:29], v[180:183], v[160:163], v[26:29]
	s_waitcnt lgkmcnt(2)
	v_mfma_f32_16x16x32_bf16 v[18:21], v[184:187], v[160:163], v[18:21]
	s_waitcnt lgkmcnt(1)
	v_mfma_f32_16x16x32_bf16 v[10:13], v[188:191], v[160:163], v[10:13]
	s_waitcnt lgkmcnt(0)
; DEV void ce(float& a, float& b) { float hi = fmaxf(a, b), lo = fminf(a, b); a = hi; b = lo; }
; DEV void bitonic16(float (&l)[16]) {
; #pragma unroll
;   for (int s = 8; s > 0; s >>= 1)
; #pragma unroll
;     for (int i = 0; i < 16; i++)
;       if (!(i & s)) ce(l[i], l[i + s]);
; }
; DEV void peer_top16(const bf16_t* __restrict__ pq, const bf16_t* sk  , float (&l)[16]) {
;     ...
;   float hi[16];
; #pragma unroll
;   for (int nt = 0; nt < 4; nt++)
; #pragma unroll
;     for (int r = 0; r < 4; r++) {
;       l[nt * 4 + r] = __uint_as_float((__float_as_uint(acc[nt][r]) & ~127u) | (unsigned)(nt * 16 + quad * 4 + r));
;       hi[nt * 4 + r] = __uint_as_float((__float_as_uint(acc[nt + 4][r]) & ~127u) | (unsigned)((nt + 4) * 16 + quad * 4 + r));
;     }
;   sort16_desc(l);
;   sort16_desc(hi);
; #pragma unroll
;   for (int i = 0; i < 16; i++) l[i] = fmaxf(l[i], hi[15 - i]);
;   bitonic16(l);
;   merge_xor(l, 16);
;   merge_xor(l, 32);
	v_mfma_f32_16x16x32_bf16 v[2:5], v[128:131], v[160:163], v[2:5]
	s_movk_i32 s18, 0x100
	v_max_f32_e32 v0, v109, v121
	v_max_f32_e32 v100, v107, v120
	v_max_f32_e32 v101, v105, v119
	v_max_f32_e32 v103, v103, v118
	v_max_f32_e32 v87, v87, v116
	v_max_f32_e32 v79, v79, v115
	v_max_f32_e32 v75, v75, v114
	v_max_f32_e32 v71, v71, v113
	v_max_f32_e32 v67, v67, v112
	v_max_f32_e32 v63, v63, v111
	v_max_f32_e32 v59, v59, v110
	v_max_f32_e32 v55, v55, v108
	v_max_f32_e32 v51, v51, v106
	v_max_f32_e32 v47, v47, v104
	v_max_f32_e32 v43, v43, v91
	v_max_f32_e32 v39, v39, v83
	v_max_f32_e32 v83, v0, v67
	v_min_f32_e32 v0, v0, v67
	v_max_f32_e32 v67, v100, v63
	v_min_f32_e32 v63, v100, v63
	v_max_f32_e32 v91, v101, v59
	v_min_f32_e32 v59, v101, v59
	v_max_f32_e32 v100, v103, v55
	v_min_f32_e32 v55, v103, v55
	v_max_f32_e32 v101, v87, v51
	v_min_f32_e32 v51, v87, v51
	v_max_f32_e32 v87, v79, v47
	v_min_f32_e32 v47, v79, v47
	v_max_f32_e32 v79, v75, v43
	v_min_f32_e32 v43, v75, v43
	v_max_f32_e32 v75, v71, v39
	v_min_f32_e32 v39, v71, v39
	v_max_f32_e32 v71, v83, v101
	v_min_f32_e32 v101, v83, v101
	v_max_f32_e32 v103, v67, v87
	v_min_f32_e32 v67, v67, v87
	v_max_f32_e32 v87, v91, v79
	v_min_f32_e32 v79, v91, v79
	v_max_f32_e32 v91, v100, v75
	v_min_f32_e32 v75, v100, v75
	v_max_f32_e32 v100, v0, v51
	v_min_f32_e32 v0, v0, v51
	v_max_f32_e32 v51, v63, v47
	v_max_f32_e32 v105, v59, v43
	v_min_f32_e32 v43, v59, v43
	v_max_f32_e32 v59, v55, v39
	v_min_f32_e32 v107, v101, v79
	v_min_f32_e32 v108, v67, v75
	v_min_f32_e32 v110, v51, v59
	v_max_f32_e32 v79, v101, v79
	v_max_f32_e32 v67, v67, v75
	v_max_f32_e32 v101, v100, v105
	v_max_f32_e32 v51, v51, v59
	v_min_f32_e32 v75, v79, v67
	v_min_f32_e32 v59, v101, v51
	v_max_f32_e32 v79, v79, v67
	v_max_f32_e32 v67, v101, v51
	v_lshlrev_b32_e32 v101, 2, v102
	s_movk_i32 s8, 0xff80
	v_and_or_b32 v30, v30, s8, v101
	v_and_b32_e32 v27, 0xffffff80, v27
	s_movk_i32 s8, 0x41
	v_or3_b32 v27, v101, v27, s8
	v_and_b32_e32 v28, 0xffffff80, v28
	s_movk_i32 s8, 0x42
	v_or3_b32 v28, v101, v28, s8
	v_and_b32_e32 v29, 0xffffff80, v29
	s_movk_i32 s8, 0x43
	v_or3_b32 v29, v101, v29, s8
	v_and_b32_e32 v18, 0xffffff80, v18
	s_movk_i32 s8, 0x50
	v_or3_b32 v18, v101, v18, s8
	v_and_b32_e32 v19, 0xffffff80, v19
	s_movk_i32 s8, 0x51
	v_or3_b32 v19, v101, v19, s8
	v_and_b32_e32 v20, 0xffffff80, v20
	s_movk_i32 s8, 0x52
	v_or3_b32 v20, v101, v20, s8
	v_and_b32_e32 v21, 0xffffff80, v21
	s_movk_i32 s8, 0x53
	v_or3_b32 v21, v101, v21, s8
	v_and_b32_e32 v10, 0xffffff80, v10
	s_movk_i32 s8, 0x60
	v_or3_b32 v10, v101, v10, s8
	v_and_b32_e32 v11, 0xffffff80, v11
	s_movk_i32 s8, 0x61
	v_or3_b32 v11, v101, v11, s8
	v_and_b32_e32 v12, 0xffffff80, v12
	s_movk_i32 s8, 0x62
	v_or3_b32 v12, v101, v12, s8
	v_and_b32_e32 v13, 0xffffff80, v13
	s_movk_i32 s8, 0x63
	v_or3_b32 v13, v101, v13, s8
	v_and_b32_e32 v2, 0xffffff80, v2
	s_movk_i32 s8, 0x70
	v_and_b32_e32 v26, 0xffffff80, v26
	v_and_b32_e32 v31, 0xffffff80, v31
	v_or3_b32 v2, v101, v2, s8
	v_and_b32_e32 v3, 0xffffff80, v3
	s_movk_i32 s8, 0x71
	v_or3_b32 v26, v101, v26, 64
	v_or3_b32 v31, v101, v31, 1
	v_and_b32_e32 v32, 0xffffff80, v32
	v_and_b32_e32 v33, 0xffffff80, v33
	v_and_b32_e32 v22, 0xffffff80, v22
	v_and_b32_e32 v23, 0xffffff80, v23
	v_or3_b32 v3, v101, v3, s8
	v_and_b32_e32 v4, 0xffffff80, v4
	s_movk_i32 s8, 0x72
	v_min_f32_e32 v39, v55, v39
	v_min_f32_e32 v55, v71, v87
	v_min_f32_e32 v106, v103, v91
	v_min_f32_e32 v109, v100, v105
	v_max_f32_e32 v71, v71, v87
	v_max_f32_e32 v87, v103, v91
	v_or3_b32 v32, v101, v32, 2
	v_or3_b32 v33, v101, v33, 3
	v_or3_b32 v22, v101, v22, 16
	v_or3_b32 v23, v101, v23, 17
	v_and_b32_e32 v24, 0xffffff80, v24
	v_and_b32_e32 v25, 0xffffff80, v25
	v_and_b32_e32 v14, 0xffffff80, v14
	v_and_b32_e32 v15, 0xffffff80, v15
	v_and_b32_e32 v16, 0xffffff80, v16
	v_and_b32_e32 v17, 0xffffff80, v17
	v_and_b32_e32 v6, 0xffffff80, v6
	v_and_b32_e32 v7, 0xffffff80, v7
	v_and_b32_e32 v8, 0xffffff80, v8
	v_or3_b32 v4, v101, v4, s8
	v_and_b32_e32 v9, 0xffffff80, v9
	v_and_b32_e32 v5, 0xffffff80, v5
	s_movk_i32 s8, 0x73
	v_min_f32_e32 v104, v63, v47
	v_min_f32_e32 v83, v55, v106
	v_min_f32_e32 v47, v109, v110
	v_min_f32_e32 v91, v71, v87
	v_max_f32_e32 v100, v71, v87
	v_max_f32_e32 v87, v55, v106
	v_max_f32_e32 v55, v109, v110
	v_or3_b32 v24, v101, v24, 18
	v_or3_b32 v25, v101, v25, 19
	v_or3_b32 v14, v101, v14, 32
	v_or3_b32 v15, v101, v15, 33
	v_or3_b32 v16, v101, v16, 34
	v_or3_b32 v17, v101, v17, 35
	v_or3_b32 v6, v101, v6, 48
	v_or3_b32 v7, v101, v7, 49
	v_or3_b32 v8, v101, v8, 50
	v_or3_b32 v9, v101, v9, 51
	v_or3_b32 v5, v101, v5, s8
	v_max_f32_e32 v101, v30, v31
	v_min_f32_e32 v30, v30, v31
	v_max_f32_e32 v31, v32, v32
	v_max_f32_e32 v32, v33, v33
	v_max_f32_e32 v109, v26, v27
	v_min_f32_e32 v26, v26, v27
	v_max_f32_e32 v27, v28, v28
	v_max_f32_e32 v28, v29, v29
	v_max_f32_e32 v33, v32, v31
	v_min_f32_e32 v31, v32, v31
	v_max_f32_e32 v32, v22, v23
	v_min_f32_e32 v22, v22, v23
	v_max_f32_e32 v23, v24, v24
	v_max_f32_e32 v24, v25, v25
	v_max_f32_e32 v29, v28, v27
	v_min_f32_e32 v27, v28, v27
	v_max_f32_e32 v28, v18, v19
	v_min_f32_e32 v18, v18, v19
	v_max_f32_e32 v19, v20, v20
	v_max_f32_e32 v20, v21, v21
	v_max_f32_e32 v25, v24, v23
	v_min_f32_e32 v23, v24, v23
	v_max_f32_e32 v24, v14, v15
	v_min_f32_e32 v14, v14, v15
	v_max_f32_e32 v15, v16, v16
	v_max_f32_e32 v16, v17, v17
	v_max_f32_e32 v21, v20, v19
	v_min_f32_e32 v19, v20, v19
	v_max_f32_e32 v20, v10, v11
	v_min_f32_e32 v10, v10, v11
	v_max_f32_e32 v11, v12, v12
	v_max_f32_e32 v12, v13, v13
	v_max_f32_e32 v17, v16, v15
	v_min_f32_e32 v15, v16, v15
	v_max_f32_e32 v16, v6, v7
	v_min_f32_e32 v6, v6, v7
; DEV void ce(float& a, float& b) { float hi = fmaxf(a, b), lo = fminf(a, b); a = hi; b = lo; }
; DEV void sort16_desc(float (&a)[16]) {
; #pragma unroll
;   for (int k = 2; k <= 16; k <<= 1)
; #pragma unroll
;     for (int j = k >> 1; j > 0; j >>= 1)
; #pragma unroll
;       for (int i = 0; i < 16; i++) {
;         const int p = i ^ j;
;         if (p > i) { if ((i & k) == 0) ce(a[i], a[p]); else ce(a[p], a[i]); }
;       }
; }
	v_max_f32_e32 v7, v8, v8
	v_max_f32_e32 v8, v9, v9
	v_max_f32_e32 v13, v12, v11
	v_min_f32_e32 v11, v12, v11
	v_max_f32_e32 v12, v2, v3
	v_min_f32_e32 v2, v2, v3
	v_max_f32_e32 v3, v4, v4
	v_max_f32_e32 v4, v5, v5
	v_max_f32_e32 v9, v8, v7
	v_min_f32_e32 v7, v8, v7
	v_max_f32_e32 v5, v4, v3
	v_min_f32_e32 v3, v4, v3
	v_max_f32_e32 v8, v101, v31
	v_min_f32_e32 v31, v101, v31
	v_max_f32_e32 v101, v30, v33
	v_min_f32_e32 v30, v30, v33
	v_max_f32_e32 v33, v23, v32
	v_min_f32_e32 v23, v23, v32
	v_max_f32_e32 v32, v25, v22
	v_min_f32_e32 v22, v25, v22
	v_max_f32_e32 v25, v24, v15
	v_min_f32_e32 v15, v24, v15
	v_max_f32_e32 v24, v14, v17
	v_min_f32_e32 v14, v14, v17
	v_max_f32_e32 v17, v7, v16
	v_min_f32_e32 v7, v7, v16
	v_max_f32_e32 v16, v9, v6
	v_min_f32_e32 v6, v9, v6
	v_max_f32_e32 v4, v109, v27
	v_min_f32_e32 v27, v109, v27
	v_max_f32_e32 v109, v26, v29
	v_min_f32_e32 v26, v26, v29
	v_max_f32_e32 v29, v19, v28
	v_min_f32_e32 v19, v19, v28
	v_max_f32_e32 v28, v21, v18
	v_min_f32_e32 v18, v21, v18
	v_max_f32_e32 v21, v20, v11
	v_min_f32_e32 v11, v20, v11
	v_max_f32_e32 v20, v10, v13
	v_min_f32_e32 v10, v10, v13
	v_max_f32_e32 v13, v3, v12
	v_min_f32_e32 v3, v3, v12
	v_max_f32_e32 v12, v5, v2
	v_min_f32_e32 v2, v5, v2
	v_max_f32_e32 v9, v8, v101
	v_min_f32_e32 v8, v8, v101
	v_max_f32_e32 v101, v31, v30
	v_min_f32_e32 v30, v31, v30
	v_max_f32_e32 v31, v22, v23
	v_min_f32_e32 v22, v22, v23
	v_max_f32_e32 v23, v32, v33
	v_min_f32_e32 v32, v32, v33
	v_max_f32_e32 v33, v25, v24
	v_min_f32_e32 v24, v25, v24
	v_max_f32_e32 v25, v15, v14
	v_min_f32_e32 v14, v15, v14
	v_max_f32_e32 v15, v6, v7
	v_min_f32_e32 v6, v6, v7
	v_max_f32_e32 v7, v16, v17
	v_min_f32_e32 v16, v16, v17
	v_max_f32_e32 v5, v4, v109
	v_min_f32_e32 v4, v4, v109
	v_max_f32_e32 v109, v27, v26
	v_min_f32_e32 v26, v27, v26
	v_max_f32_e32 v27, v18, v19
	v_min_f32_e32 v18, v18, v19
	v_max_f32_e32 v19, v28, v29
	v_min_f32_e32 v28, v28, v29
	v_max_f32_e32 v29, v21, v20
	v_min_f32_e32 v20, v21, v20
	v_max_f32_e32 v21, v11, v10
	v_min_f32_e32 v10, v11, v10
	v_max_f32_e32 v11, v2, v3
	v_min_f32_e32 v2, v2, v3
	v_max_f32_e32 v3, v12, v13
	v_min_f32_e32 v12, v12, v13
	v_max_f32_e32 v17, v9, v22
	v_min_f32_e32 v9, v9, v22
	v_max_f32_e32 v22, v8, v31
	v_min_f32_e32 v8, v8, v31
	v_max_f32_e32 v31, v101, v32
	v_min_f32_e32 v32, v101, v32
	v_max_f32_e32 v101, v30, v23
	v_min_f32_e32 v23, v30, v23
	v_max_f32_e32 v30, v6, v33
	v_min_f32_e32 v6, v6, v33
	v_max_f32_e32 v33, v15, v24
	v_min_f32_e32 v15, v15, v24
	v_max_f32_e32 v24, v16, v25
	v_min_f32_e32 v16, v16, v25
	v_max_f32_e32 v25, v7, v14
	v_min_f32_e32 v7, v7, v14
	v_max_f32_e32 v13, v5, v18
	v_min_f32_e32 v5, v5, v18
	v_max_f32_e32 v18, v4, v27
	v_min_f32_e32 v4, v4, v27
	v_max_f32_e32 v27, v109, v28
	v_min_f32_e32 v28, v109, v28
	v_max_f32_e32 v109, v26, v19
	v_min_f32_e32 v19, v26, v19
	v_max_f32_e32 v26, v2, v29
	v_min_f32_e32 v2, v2, v29
	v_max_f32_e32 v29, v11, v20
	v_min_f32_e32 v11, v11, v20
	v_max_f32_e32 v20, v12, v21
	v_min_f32_e32 v12, v12, v21
	v_max_f32_e32 v21, v3, v10
	v_min_f32_e32 v3, v3, v10
	v_max_f32_e32 v14, v17, v31
	v_min_f32_e32 v17, v17, v31
	v_max_f32_e32 v31, v22, v101
	v_min_f32_e32 v22, v22, v101
	v_max_f32_e32 v101, v9, v32
	v_min_f32_e32 v9, v9, v32
	v_max_f32_e32 v32, v8, v23
	v_min_f32_e32 v8, v8, v23
	v_max_f32_e32 v23, v16, v6
	v_min_f32_e32 v6, v16, v6
	v_max_f32_e32 v16, v7, v15
	v_min_f32_e32 v7, v7, v15
	v_max_f32_e32 v15, v24, v30
	v_min_f32_e32 v24, v24, v30
	v_max_f32_e32 v30, v25, v33
	v_min_f32_e32 v25, v25, v33
	v_max_f32_e32 v10, v13, v27
	v_min_f32_e32 v13, v13, v27
	v_max_f32_e32 v27, v18, v109
	v_min_f32_e32 v18, v18, v109
	v_max_f32_e32 v109, v5, v28
	v_min_f32_e32 v5, v5, v28
	v_max_f32_e32 v28, v4, v19
	v_min_f32_e32 v4, v4, v19
	v_max_f32_e32 v19, v12, v2
	v_min_f32_e32 v2, v12, v2
	v_max_f32_e32 v12, v3, v11
	v_min_f32_e32 v3, v3, v11
	v_max_f32_e32 v11, v20, v26
	v_min_f32_e32 v20, v20, v26
	v_max_f32_e32 v26, v21, v29
	v_min_f32_e32 v21, v21, v29
	v_max_f32_e32 v33, v14, v31
	v_min_f32_e32 v14, v14, v31
	v_max_f32_e32 v31, v17, v22
	v_min_f32_e32 v17, v17, v22
	v_max_f32_e32 v22, v101, v32
	v_min_f32_e32 v32, v101, v32
	v_max_f32_e32 v101, v9, v8
	v_min_f32_e32 v8, v9, v8
	v_max_f32_e32 v9, v7, v6
	v_min_f32_e32 v6, v7, v6
	v_max_f32_e32 v7, v16, v23
	v_min_f32_e32 v16, v16, v23
	v_max_f32_e32 v23, v25, v24
	v_min_f32_e32 v24, v25, v24
	v_max_f32_e32 v25, v30, v15
	v_min_f32_e32 v15, v30, v15
	v_max_f32_e32 v29, v10, v27
	v_min_f32_e32 v10, v10, v27
	v_max_f32_e32 v27, v13, v18
	v_min_f32_e32 v13, v13, v18
	v_max_f32_e32 v18, v109, v28
	v_min_f32_e32 v28, v109, v28
	v_max_f32_e32 v109, v5, v4
	v_min_f32_e32 v4, v5, v4
	v_max_f32_e32 v5, v3, v2
	v_min_f32_e32 v2, v3, v2
	v_max_f32_e32 v3, v12, v19
	v_min_f32_e32 v12, v12, v19
	v_max_f32_e32 v19, v21, v20
	v_min_f32_e32 v20, v21, v20
	v_max_f32_e32 v21, v26, v11
	v_min_f32_e32 v11, v26, v11
	v_max_f32_e32 v30, v33, v6
	v_min_f32_e32 v6, v33, v6
	v_max_f32_e32 v33, v14, v9
	v_min_f32_e32 v9, v14, v9
	v_max_f32_e32 v14, v31, v16
	v_min_f32_e32 v16, v31, v16
	v_max_f32_e32 v31, v17, v7
	v_min_f32_e32 v7, v17, v7
	v_max_f32_e32 v17, v22, v24
	v_min_f32_e32 v22, v22, v24
	v_max_f32_e32 v24, v32, v23
	v_min_f32_e32 v23, v32, v23
	v_max_f32_e32 v32, v101, v15
	v_min_f32_e32 v15, v101, v15
	v_max_f32_e32 v101, v8, v25
	v_min_f32_e32 v8, v8, v25
	v_max_f32_e32 v26, v29, v2
	v_min_f32_e32 v2, v29, v2
	v_max_f32_e32 v29, v10, v5
	v_min_f32_e32 v5, v10, v5
	v_max_f32_e32 v10, v27, v12
	v_min_f32_e32 v12, v27, v12
	v_max_f32_e32 v27, v13, v3
	v_min_f32_e32 v3, v13, v3
	v_max_f32_e32 v13, v18, v20
	v_min_f32_e32 v18, v18, v20
	v_max_f32_e32 v20, v28, v19
; DEV void ce(float& a, float& b) { float hi = fmaxf(a, b), lo = fminf(a, b); a = hi; b = lo; }
; DEV void sort16_desc(float (&a)[16]) {
; #pragma unroll
;   for (int k = 2; k <= 16; k <<= 1)
; #pragma unroll
;     for (int j = k >> 1; j > 0; j >>= 1)
; #pragma unroll
;       for (int i = 0; i < 16; i++) {
;         const int p = i ^ j;
;         if (p > i) { if ((i & k) == 0) ce(a[i], a[p]); else ce(a[p], a[i]); }
;       }
; }
; DEV void merge_xor(float (&l)[16], int mask) {
;   float t[16];
; #pragma unroll
;   for (int i = 0; i < 16; i++) t[i] = __shfl_xor(l[15 - i], mask);
; #pragma unroll
;   for (int i = 0; i < 16; i++) l[i] = fmaxf(l[i], t[i]);
;   bitonic16(l);
; }
; DEV void peer_top16(const bf16_t* __restrict__ pq, const bf16_t* sk  , float (&l)[16]) {
;     ...
;   sort16_desc(l);
;   sort16_desc(hi);
; #pragma unroll
;   for (int i = 0; i < 16; i++) l[i] = fmaxf(l[i], hi[15 - i]);
;   bitonic16(l);
;   merge_xor(l, 16);
	v_min_f32_e32 v19, v28, v19
	v_max_f32_e32 v28, v109, v11
	v_min_f32_e32 v11, v109, v11
	v_max_f32_e32 v109, v4, v21
	v_min_f32_e32 v4, v4, v21
	v_max_f32_e32 v25, v30, v17
	v_min_f32_e32 v17, v30, v17
	v_max_f32_e32 v30, v33, v24
	v_min_f32_e32 v24, v33, v24
	v_max_f32_e32 v33, v14, v32
	v_min_f32_e32 v14, v14, v32
	v_max_f32_e32 v32, v31, v101
	v_min_f32_e32 v31, v31, v101
	v_max_f32_e32 v101, v6, v22
	v_min_f32_e32 v6, v6, v22
	v_max_f32_e32 v22, v9, v23
	v_min_f32_e32 v9, v9, v23
	v_max_f32_e32 v23, v16, v15
	v_min_f32_e32 v15, v16, v15
	v_max_f32_e32 v16, v7, v8
	v_min_f32_e32 v7, v7, v8
	v_max_f32_e32 v21, v26, v13
	v_min_f32_e32 v13, v26, v13
	v_max_f32_e32 v26, v29, v20
	v_min_f32_e32 v20, v29, v20
	v_max_f32_e32 v29, v10, v28
	v_min_f32_e32 v10, v10, v28
	v_max_f32_e32 v28, v27, v109
	v_min_f32_e32 v27, v27, v109
	v_max_f32_e32 v109, v2, v18
	v_min_f32_e32 v2, v2, v18
	v_max_f32_e32 v18, v5, v19
	v_min_f32_e32 v5, v5, v19
	v_max_f32_e32 v19, v12, v11
	v_min_f32_e32 v11, v12, v11
	v_max_f32_e32 v12, v3, v4
	v_min_f32_e32 v3, v3, v4
	v_max_f32_e32 v111, v0, v43
	v_min_f32_e32 v112, v104, v39
	v_max_f32_e32 v103, v104, v39
	v_min_f32_e32 v0, v0, v43
	v_max_f32_e32 v8, v25, v33
	v_min_f32_e32 v25, v25, v33
	v_max_f32_e32 v33, v30, v32
	v_min_f32_e32 v30, v30, v32
	v_max_f32_e32 v32, v17, v14
	v_min_f32_e32 v14, v17, v14
	v_max_f32_e32 v17, v24, v31
	v_min_f32_e32 v24, v24, v31
	v_max_f32_e32 v31, v101, v23
	v_min_f32_e32 v23, v101, v23
	v_max_f32_e32 v101, v22, v16
	v_min_f32_e32 v16, v22, v16
	v_max_f32_e32 v22, v6, v15
	v_min_f32_e32 v6, v6, v15
	v_max_f32_e32 v15, v9, v7
	v_min_f32_e32 v7, v9, v7
	v_max_f32_e32 v4, v21, v29
	v_min_f32_e32 v21, v21, v29
	v_max_f32_e32 v29, v26, v28
	v_min_f32_e32 v26, v26, v28
	v_max_f32_e32 v28, v13, v10
	v_min_f32_e32 v10, v13, v10
	v_max_f32_e32 v13, v20, v27
	v_min_f32_e32 v20, v20, v27
	v_max_f32_e32 v27, v109, v19
	v_min_f32_e32 v19, v109, v19
	v_max_f32_e32 v109, v18, v12
	v_min_f32_e32 v12, v18, v12
	v_max_f32_e32 v18, v2, v11
	v_min_f32_e32 v2, v2, v11
	v_max_f32_e32 v11, v5, v3
	v_min_f32_e32 v3, v5, v3
	v_min_f32_e32 v63, v107, v108
	v_min_f32_e32 v39, v111, v103
	v_max_f32_e32 v71, v107, v108
	v_max_f32_e32 v51, v111, v103
	v_max_f32_e32 v43, v0, v112
	v_min_f32_e32 v0, v0, v112
	v_min_f32_e32 v9, v8, v33
	v_min_f32_e32 v102, v25, v30
	v_min_f32_e32 v103, v32, v17
	v_min_f32_e32 v104, v14, v24
	v_min_f32_e32 v105, v31, v101
	v_min_f32_e32 v106, v23, v16
	v_min_f32_e32 v107, v22, v15
	v_min_f32_e32 v108, v6, v7
	v_min_f32_e32 v5, v4, v29
	v_min_f32_e32 v110, v21, v26
	v_min_f32_e32 v111, v28, v13
	v_min_f32_e32 v112, v10, v20
	v_min_f32_e32 v113, v27, v109
	v_min_f32_e32 v114, v19, v12
	v_min_f32_e32 v115, v18, v11
	v_min_f32_e32 v116, v2, v3
	v_max3_f32 v8, v8, v33, v116
	v_max3_f32 v2, v9, v2, v3
	v_max3_f32 v3, v25, v30, v115
	v_max3_f32 v9, v102, v18, v11
	v_max3_f32 v11, v32, v17, v114
	v_max3_f32 v12, v103, v19, v12
	v_max3_f32 v14, v14, v24, v113
	v_max3_f32 v17, v104, v27, v109
	v_max3_f32 v18, v31, v101, v112
	v_max3_f32 v10, v105, v10, v20
	v_max3_f32 v16, v23, v16, v111
	v_max3_f32 v13, v106, v28, v13
	v_max3_f32 v15, v22, v15, v110
	v_max3_f32 v19, v107, v21, v26
	v_max3_f32 v5, v6, v7, v5
	v_max3_f32 v4, v108, v4, v29
	v_max_f32_e32 v6, v8, v18
	v_min_f32_e32 v7, v8, v18
	v_max_f32_e32 v8, v2, v10
	v_min_f32_e32 v2, v2, v10
	v_max_f32_e32 v10, v3, v16
	v_min_f32_e32 v3, v3, v16
	v_max_f32_e32 v16, v9, v13
	v_min_f32_e32 v9, v9, v13
	v_max_f32_e32 v13, v11, v15
	v_min_f32_e32 v11, v11, v15
	v_max_f32_e32 v15, v12, v19
	v_min_f32_e32 v12, v12, v19
	v_max_f32_e32 v18, v14, v5
	v_min_f32_e32 v5, v14, v5
	v_max_f32_e32 v14, v17, v4
	v_min_f32_e32 v4, v17, v4
	v_max_f32_e32 v17, v6, v13
	v_min_f32_e32 v6, v6, v13
	v_max_f32_e32 v13, v8, v15
	v_min_f32_e32 v8, v8, v15
	v_max_f32_e32 v15, v10, v18
	v_min_f32_e32 v10, v10, v18
	v_max_f32_e32 v18, v16, v14
	v_min_f32_e32 v14, v16, v14
	v_max_f32_e32 v16, v7, v11
	v_min_f32_e32 v7, v7, v11
	v_max_f32_e32 v11, v2, v12
	v_min_f32_e32 v2, v2, v12
	v_max_f32_e32 v12, v3, v5
	v_min_f32_e32 v3, v3, v5
	v_max_f32_e32 v5, v9, v4
	v_min_f32_e32 v4, v9, v4
	v_max_f32_e32 v9, v17, v15
	v_min_f32_e32 v15, v17, v15
	v_max_f32_e32 v17, v13, v18
	v_min_f32_e32 v13, v13, v18
	v_max_f32_e32 v18, v6, v10
	v_min_f32_e32 v6, v6, v10
	v_max_f32_e32 v10, v8, v14
	v_min_f32_e32 v8, v8, v14
	v_max_f32_e32 v14, v16, v12
	v_min_f32_e32 v12, v16, v12
	v_max_f32_e32 v16, v11, v5
	v_min_f32_e32 v5, v11, v5
	v_max_f32_e32 v11, v7, v3
	v_min_f32_e32 v3, v7, v3
	v_max_f32_e32 v7, v2, v4
	v_min_f32_e32 v2, v2, v4
	v_max_f32_e32 v4, v9, v17
	v_min_f32_e32 v9, v9, v17
	v_max_f32_e32 v17, v15, v13
	v_min_f32_e32 v13, v15, v13
	v_max_f32_e32 v15, v18, v10
	v_min_f32_e32 v10, v18, v10
	v_max_f32_e32 v18, v6, v8
	v_min_f32_e32 v6, v6, v8
	v_max_f32_e32 v8, v14, v16
	v_min_f32_e32 v14, v14, v16
	v_max_f32_e32 v16, v12, v5
	v_min_f32_e32 v5, v12, v5
	v_max_f32_e32 v12, v11, v7
	v_min_f32_e32 v7, v11, v7
	v_max_f32_e32 v11, v3, v2
	v_min_f32_e32 v2, v3, v2
	ds_bpermute_b32 v3, v95, v2
	ds_bpermute_b32 v19, v95, v11
	ds_bpermute_b32 v20, v95, v7
	ds_bpermute_b32 v21, v95, v12
	ds_bpermute_b32 v22, v95, v5
	ds_bpermute_b32 v23, v95, v16
	s_waitcnt lgkmcnt(5)
	ds_bpermute_b32 v24, v95, v14
	ds_bpermute_b32 v33, v95, v4
	v_max_f32_e32 v3, v4, v3
	s_waitcnt lgkmcnt(6)
	ds_bpermute_b32 v25, v95, v8
	ds_bpermute_b32 v32, v95, v9
	v_max_f32_e32 v4, v9, v19
	s_waitcnt lgkmcnt(7)
	ds_bpermute_b32 v26, v95, v6
	ds_bpermute_b32 v31, v95, v17
	v_max_f32_e32 v9, v17, v20
	s_waitcnt lgkmcnt(8)
	ds_bpermute_b32 v27, v95, v18
	ds_bpermute_b32 v30, v95, v13
	v_max_f32_e32 v13, v13, v21
	s_waitcnt lgkmcnt(9)
; DEV void merge_xor(float (&l)[16], int mask) {
;   float t[16];
; #pragma unroll
;   for (int i = 0; i < 16; i++) t[i] = __shfl_xor(l[15 - i], mask);
; #pragma unroll
;   for (int i = 0; i < 16; i++) l[i] = fmaxf(l[i], t[i]);
;   bitonic16(l);
; }
; DEV void phase_peer_score(const Params& p, int layer, int M, char* smem) {
;     ...
;     unsigned char* tab = (unsigned char*)smem + 73728 + (w * 16 + l15) * 32;
; #pragma unroll
;     for (int i = 0; i < 16; i++) { tab[i] = (unsigned char)(__float_as_uint(L0[i]) & 127u); tab[16 + i] = (unsigned char)(__float_as_uint(L1[i]) & 127u); }
	ds_bpermute_b32 v28, v95, v10
	ds_bpermute_b32 v29, v95, v15
	v_max_f32_e32 v15, v15, v22
	s_waitcnt lgkmcnt(10)
	v_max_f32_e32 v10, v10, v23
	s_waitcnt lgkmcnt(9)
	v_max_f32_e32 v17, v18, v24
	s_waitcnt lgkmcnt(7)
	v_max_f32_e32 v6, v6, v25
	s_waitcnt lgkmcnt(5)
	v_max_f32_e32 v8, v8, v26
	s_waitcnt lgkmcnt(3)
	v_max_f32_e32 v14, v14, v27
	s_waitcnt lgkmcnt(1)
	v_max_f32_e32 v16, v16, v28
	s_waitcnt lgkmcnt(0)
	v_max_f32_e32 v5, v5, v29
	v_max_f32_e32 v12, v12, v30
	v_max_f32_e32 v7, v7, v31
	v_max_f32_e32 v11, v11, v32
	v_max_f32_e32 v2, v2, v33
	v_max_f32_e32 v18, v3, v8
	v_min_f32_e32 v3, v3, v8
	v_max_f32_e32 v8, v4, v14
	v_min_f32_e32 v4, v4, v14
	v_max_f32_e32 v14, v9, v16
	v_min_f32_e32 v9, v9, v16
	v_max_f32_e32 v16, v13, v5
	v_min_f32_e32 v5, v13, v5
	v_max_f32_e32 v13, v15, v12
	v_min_f32_e32 v12, v15, v12
	v_max_f32_e32 v15, v10, v7
	v_min_f32_e32 v7, v10, v7
	v_max_f32_e32 v10, v17, v11
	v_min_f32_e32 v11, v17, v11
	v_max_f32_e32 v17, v6, v2
	v_min_f32_e32 v2, v6, v2
	v_max_f32_e32 v6, v18, v13
	v_min_f32_e32 v13, v18, v13
	v_max_f32_e32 v18, v8, v15
	v_min_f32_e32 v8, v8, v15
	v_max_f32_e32 v15, v14, v10
	v_min_f32_e32 v10, v14, v10
	v_max_f32_e32 v14, v16, v17
	v_min_f32_e32 v16, v16, v17
	v_max_f32_e32 v17, v3, v12
	v_min_f32_e32 v3, v3, v12
	v_max_f32_e32 v12, v4, v7
	v_min_f32_e32 v4, v4, v7
	v_max_f32_e32 v7, v9, v11
	v_min_f32_e32 v9, v9, v11
	v_max_f32_e32 v11, v5, v2
	v_min_f32_e32 v2, v5, v2
	v_max_f32_e32 v5, v6, v15
	v_min_f32_e32 v6, v6, v15
	v_max_f32_e32 v15, v18, v14
	v_min_f32_e32 v14, v18, v14
	v_max_f32_e32 v18, v13, v10
	v_min_f32_e32 v10, v13, v10
	v_max_f32_e32 v13, v8, v16
	v_min_f32_e32 v8, v8, v16
	v_max_f32_e32 v16, v17, v7
	v_min_f32_e32 v7, v17, v7
	v_max_f32_e32 v17, v12, v11
	v_min_f32_e32 v11, v12, v11
	v_max_f32_e32 v12, v3, v9
	v_min_f32_e32 v3, v3, v9
	v_max_f32_e32 v9, v4, v2
	v_min_f32_e32 v2, v4, v2
	v_max_f32_e32 v4, v5, v15
	v_min_f32_e32 v5, v5, v15
	v_max_f32_e32 v15, v6, v14
	v_min_f32_e32 v6, v6, v14
	v_max_f32_e32 v14, v18, v13
	v_min_f32_e32 v13, v18, v13
	v_max_f32_e32 v18, v10, v8
	v_min_f32_e32 v8, v10, v8
	v_max_f32_e32 v10, v16, v17
	v_min_f32_e32 v16, v16, v17
	v_max_f32_e32 v17, v7, v11
	v_min_f32_e32 v7, v7, v11
	v_max_f32_e32 v11, v12, v9
	v_min_f32_e32 v9, v12, v9
	v_max_f32_e32 v12, v3, v2
	v_min_f32_e32 v2, v3, v2
	ds_bpermute_b32 v3, v99, v2
	ds_bpermute_b32 v19, v99, v12
	ds_bpermute_b32 v20, v99, v9
	ds_bpermute_b32 v21, v99, v11
	ds_bpermute_b32 v22, v99, v7
	ds_bpermute_b32 v23, v99, v17
	s_waitcnt lgkmcnt(5)
	ds_bpermute_b32 v24, v99, v16
	ds_bpermute_b32 v33, v99, v4
	v_max_f32_e32 v3, v4, v3
	s_waitcnt lgkmcnt(6)
	ds_bpermute_b32 v25, v99, v10
	ds_bpermute_b32 v32, v99, v5
	v_max_f32_e32 v4, v5, v19
	s_waitcnt lgkmcnt(7)
	ds_bpermute_b32 v26, v99, v8
	ds_bpermute_b32 v31, v99, v15
	v_max_f32_e32 v5, v15, v20
	s_waitcnt lgkmcnt(8)
	ds_bpermute_b32 v27, v99, v18
	ds_bpermute_b32 v30, v99, v6
	v_max_f32_e32 v6, v6, v21
	s_waitcnt lgkmcnt(9)
	ds_bpermute_b32 v28, v99, v13
	ds_bpermute_b32 v29, v99, v14
	v_max_f32_e32 v14, v14, v22
	s_waitcnt lgkmcnt(10)
	v_max_f32_e32 v13, v13, v23
	s_waitcnt lgkmcnt(9)
	v_max_f32_e32 v15, v18, v24
	s_waitcnt lgkmcnt(7)
	v_max_f32_e32 v8, v8, v25
	s_waitcnt lgkmcnt(5)
	v_max_f32_e32 v10, v10, v26
	s_waitcnt lgkmcnt(3)
	v_max_f32_e32 v16, v16, v27
	s_waitcnt lgkmcnt(1)
	v_max_f32_e32 v17, v17, v28
	s_waitcnt lgkmcnt(0)
	v_max_f32_e32 v7, v7, v29
	v_max_f32_e32 v11, v11, v30
	v_max_f32_e32 v9, v9, v31
	v_max_f32_e32 v12, v12, v32
	v_max_f32_e32 v2, v2, v33
	v_max_f32_e32 v18, v3, v10
	v_min_f32_e32 v3, v3, v10
	v_max_f32_e32 v10, v4, v16
	v_min_f32_e32 v4, v4, v16
	v_max_f32_e32 v16, v5, v17
	v_min_f32_e32 v5, v5, v17
	v_max_f32_e32 v17, v6, v7
	v_min_f32_e32 v6, v6, v7
	v_max_f32_e32 v7, v14, v11
	v_min_f32_e32 v11, v14, v11
	v_max_f32_e32 v14, v13, v9
	v_min_f32_e32 v9, v13, v9
	v_max_f32_e32 v13, v15, v12
	v_min_f32_e32 v12, v15, v12
	v_max_f32_e32 v15, v8, v2
	v_min_f32_e32 v2, v8, v2
	v_max_f32_e32 v8, v18, v7
	v_min_f32_e32 v7, v18, v7
	v_max_f32_e32 v18, v10, v14
	v_min_f32_e32 v10, v10, v14
	v_max_f32_e32 v14, v16, v13
	v_min_f32_e32 v13, v16, v13
	v_max_f32_e32 v16, v17, v15
	v_min_f32_e32 v15, v17, v15
	v_max_f32_e32 v17, v3, v11
	v_min_f32_e32 v3, v3, v11
	v_max_f32_e32 v11, v4, v9
	v_min_f32_e32 v4, v4, v9
	v_max_f32_e32 v9, v5, v12
	v_min_f32_e32 v5, v5, v12
	v_max_f32_e32 v12, v6, v2
	v_min_f32_e32 v2, v6, v2
	v_max_f32_e32 v6, v8, v14
	v_min_f32_e32 v8, v8, v14
	v_max_f32_e32 v14, v18, v16
	v_min_f32_e32 v16, v18, v16
	v_max_f32_e32 v18, v7, v13
	v_max_f32_e32 v19, v10, v15
	s_movk_i32 s8, 0x7f
	v_min_f32_e32 v13, v7, v13
	v_min_f32_e32 v10, v10, v15
	v_max_f32_e32 v15, v17, v9
	v_min_f32_e32 v21, v17, v9
	v_max_f32_e32 v17, v11, v12
	v_min_f32_e32 v22, v11, v12
	v_max_f32_e32 v23, v3, v5
	v_min_f32_e32 v3, v3, v5
	v_max_f32_e32 v5, v4, v2
	v_min_f32_e32 v24, v4, v2
	v_max_f32_e32 v9, v18, v19
	v_min_f32_e32 v12, v18, v19
	v_and_b32_sdwa v18, v63, s8 dst_sel:BYTE_1 dst_unused:UNUSED_PAD src0_sel:DWORD src1_sel:DWORD
	v_max_f32_e32 v2, v6, v14
	v_min_f32_e32 v4, v6, v14
	v_max_f32_e32 v11, v13, v10
	v_min_f32_e32 v10, v13, v10
	v_max_f32_e32 v14, v23, v5
	v_min_f32_e32 v13, v23, v5
	v_max_f32_e32 v6, v3, v24
	v_min_f32_e32 v5, v3, v24
	v_and_b32_sdwa v3, v75, s8 dst_sel:BYTE_1 dst_unused:UNUSED_PAD src0_sel:DWORD src1_sel:DWORD
	v_bitop3_b16 v18, v71, v18, s8 bitop3:0xec
	v_bitop3_b16 v3, v79, v3, s8 bitop3:0xec
	v_lshlrev_b32_e32 v18, 16, v18
	v_or_b32_sdwa v23, v3, v18 dst_sel:DWORD dst_unused:UNUSED_PAD src0_sel:WORD_0 src1_sel:DWORD
	v_and_b32_sdwa v18, v83, s8 dst_sel:BYTE_1 dst_unused:UNUSED_PAD src0_sel:DWORD src1_sel:DWORD
; DEV void ce(float& a, float& b) { float hi = fmaxf(a, b), lo = fminf(a, b); a = hi; b = lo; }
; DEV void phase_peer_score(const Params& p, int layer, int M, char* smem) {
;     ...
;     float R[16];
; #pragma unroll
;     for (int i = 0; i < 16; i++) R[i] = -3.0e38f;
; #pragma unroll
;     for (int i = 0; i < 16; i++)
; #pragma unroll
;       for (int j = 0; j < 16; j++)
;         if ((i + 1) * (j + 1) <= 16) {
;           float v = L0[i] + L1[j];
;           v = __uint_as_float((__float_as_uint(v) & ~255u) | (unsigned)(i * 16 + j));
; #pragma unroll
;           for (int t = 0; t < 16; t++)
;             if (t >= (i + 1) * (j + 1) - 1) ce(R[t], v);
;         }
;     unsigned char* tab = (unsigned char*)smem + 73728 + (w * 16 + l15) * 32;
; #pragma unroll
;     for (int i = 0; i < 16; i++) { tab[i] = (unsigned char)(__float_as_uint(L0[i]) & 127u); tab[16 + i] = (unsigned char)(__float_as_uint(L1[i]) & 127u); }
	v_and_b32_sdwa v3, v91, s8 dst_sel:BYTE_1 dst_unused:UNUSED_PAD src0_sel:DWORD src1_sel:DWORD
	v_bitop3_b16 v18, v87, v18, s8 bitop3:0xec
	v_bitop3_b16 v3, v100, v3, s8 bitop3:0xec
	v_lshlrev_b32_e32 v18, 16, v18
	v_max_f32_e32 v7, v8, v16
	v_min_f32_e32 v8, v8, v16
	v_max_f32_e32 v20, v15, v17
	v_min_f32_e32 v17, v15, v17
	v_max_f32_e32 v16, v21, v22
	v_min_f32_e32 v15, v21, v22
	v_or_b32_sdwa v22, v3, v18 dst_sel:DWORD dst_unused:UNUSED_PAD src0_sel:WORD_0 src1_sel:DWORD
	v_and_b32_sdwa v18, v10, s8 dst_sel:BYTE_1 dst_unused:UNUSED_PAD src0_sel:DWORD src1_sel:DWORD
	v_and_b32_sdwa v3, v12, s8 dst_sel:BYTE_1 dst_unused:UNUSED_PAD src0_sel:DWORD src1_sel:DWORD
	v_bitop3_b16 v18, v11, v18, s8 bitop3:0xec
	v_bitop3_b16 v3, v9, v3, s8 bitop3:0xec
	v_lshlrev_b32_e32 v18, 16, v18
	v_or_b32_sdwa v27, v3, v18 dst_sel:DWORD dst_unused:UNUSED_PAD src0_sel:WORD_0 src1_sel:DWORD
	v_and_b32_sdwa v18, v8, s8 dst_sel:BYTE_1 dst_unused:UNUSED_PAD src0_sel:DWORD src1_sel:DWORD
	v_and_b32_sdwa v3, v4, s8 dst_sel:BYTE_1 dst_unused:UNUSED_PAD src0_sel:DWORD src1_sel:DWORD
	v_bitop3_b16 v18, v7, v18, s8 bitop3:0xec
	v_bitop3_b16 v3, v2, v3, s8 bitop3:0xec
	v_lshlrev_b32_e32 v18, 16, v18
	v_or_b32_sdwa v26, v3, v18 dst_sel:DWORD dst_unused:UNUSED_PAD src0_sel:WORD_0 src1_sel:DWORD
	v_and_b32_sdwa v18, v0, s8 dst_sel:BYTE_1 dst_unused:UNUSED_PAD src0_sel:DWORD src1_sel:DWORD
	v_and_b32_sdwa v3, v39, s8 dst_sel:BYTE_1 dst_unused:UNUSED_PAD src0_sel:DWORD src1_sel:DWORD
	v_bitop3_b16 v18, v43, v18, s8 bitop3:0xec
	v_bitop3_b16 v3, v51, v3, s8 bitop3:0xec
	v_lshlrev_b32_e32 v18, 16, v18
	v_or_b32_sdwa v25, v3, v18 dst_sel:DWORD dst_unused:UNUSED_PAD src0_sel:WORD_0 src1_sel:DWORD
	v_and_b32_sdwa v18, v47, s8 dst_sel:BYTE_1 dst_unused:UNUSED_PAD src0_sel:DWORD src1_sel:DWORD
	v_and_b32_sdwa v3, v59, s8 dst_sel:BYTE_1 dst_unused:UNUSED_PAD src0_sel:DWORD src1_sel:DWORD
	v_bitop3_b16 v18, v55, v18, s8 bitop3:0xec
	v_bitop3_b16 v3, v67, v3, s8 bitop3:0xec
	v_lshlrev_b32_e32 v18, 16, v18
	v_or_b32_sdwa v24, v3, v18 dst_sel:DWORD dst_unused:UNUSED_PAD src0_sel:WORD_0 src1_sel:DWORD
	v_and_b32_sdwa v18, v5, s8 dst_sel:BYTE_1 dst_unused:UNUSED_PAD src0_sel:DWORD src1_sel:DWORD
	v_and_b32_sdwa v3, v13, s8 dst_sel:BYTE_1 dst_unused:UNUSED_PAD src0_sel:DWORD src1_sel:DWORD
	v_bitop3_b16 v18, v6, v18, s8 bitop3:0xec
	v_bitop3_b16 v3, v14, v3, s8 bitop3:0xec
	v_lshlrev_b32_e32 v18, 16, v18
	v_or_b32_sdwa v29, v3, v18 dst_sel:DWORD dst_unused:UNUSED_PAD src0_sel:WORD_0 src1_sel:DWORD
	v_and_b32_sdwa v18, v15, s8 dst_sel:BYTE_1 dst_unused:UNUSED_PAD src0_sel:DWORD src1_sel:DWORD
	v_and_b32_sdwa v3, v17, s8 dst_sel:BYTE_1 dst_unused:UNUSED_PAD src0_sel:DWORD src1_sel:DWORD
	v_bitop3_b16 v18, v16, v18, s8 bitop3:0xec
	v_bitop3_b16 v3, v20, v3, s8 bitop3:0xec
	v_lshlrev_b32_e32 v18, 16, v18
	v_or_b32_sdwa v28, v3, v18 dst_sel:DWORD dst_unused:UNUSED_PAD src0_sel:WORD_0 src1_sel:DWORD
	ds_write_b128 v138, v[22:25]
	ds_write_b128 v138, v[26:29] offset:16
	s_and_saveexec_b64 s[8:9], s[38:39]
	s_cbranch_execz .LBB0_627
	s_movk_i32 s18, 0xff00
	v_add_f32_e32 v164, v100, v2
	v_and_or_b32 v164, v164, s18, 0
	v_max_f32_e32 v148, 0xff61b1e6, v164
	v_add_f32_e32 v164, v100, v4
	v_and_or_b32 v164, v164, s18, 1
	v_max_f32_e32 v149, 0xff61b1e6, v164
	v_add_f32_e32 v164, v100, v7
	v_and_or_b32 v164, v164, s18, 2
	v_max_f32_e32 v150, 0xff61b1e6, v164
	v_add_f32_e32 v164, v100, v8
	v_and_or_b32 v164, v164, s18, 3
	v_max_f32_e32 v151, 0xff61b1e6, v164
	v_add_f32_e32 v164, v100, v9
	v_and_or_b32 v164, v164, s18, 4
	v_max_f32_e32 v152, 0xff61b1e6, v164
	v_add_f32_e32 v164, v100, v12
	v_and_or_b32 v164, v164, s18, 5
	v_max_f32_e32 v153, 0xff61b1e6, v164
	v_add_f32_e32 v164, v100, v11
	v_and_or_b32 v164, v164, s18, 6
	v_max_f32_e32 v154, 0xff61b1e6, v164
	v_add_f32_e32 v164, v100, v10
	v_and_or_b32 v164, v164, s18, 7
	v_max_f32_e32 v155, 0xff61b1e6, v164
	v_add_f32_e32 v164, v100, v20
	v_and_or_b32 v164, v164, s18, 8
	v_max_f32_e32 v156, 0xff61b1e6, v164
	v_add_f32_e32 v164, v100, v17
	v_and_or_b32 v164, v164, s18, 9
	v_max_f32_e32 v157, 0xff61b1e6, v164
	v_add_f32_e32 v164, v100, v16
	v_and_or_b32 v164, v164, s18, 10
	v_max_f32_e32 v158, 0xff61b1e6, v164
	v_add_f32_e32 v164, v100, v15
	v_and_or_b32 v164, v164, s18, 11
	v_max_f32_e32 v159, 0xff61b1e6, v164
	v_add_f32_e32 v164, v100, v14
	v_and_or_b32 v164, v164, s18, 12
	v_max_f32_e32 v160, 0xff61b1e6, v164
	v_add_f32_e32 v164, v100, v13
	v_and_or_b32 v164, v164, s18, 13
	v_max_f32_e32 v161, 0xff61b1e6, v164
	v_add_f32_e32 v164, v100, v6
	v_and_or_b32 v164, v164, s18, 14
	v_max_f32_e32 v162, 0xff61b1e6, v164
	v_add_f32_e32 v164, v100, v5
	v_and_or_b32 v164, v164, s18, 15
	v_max_f32_e32 v163, 0xff61b1e6, v164
	v_min_f32_e32 v164, v148, v149
	v_max_f32_e32 v148, v148, v149
	v_mov_b32_e32 v149, v164
	v_min_f32_e32 v164, v149, v150
	v_max_f32_e32 v149, v149, v150
	v_mov_b32_e32 v150, v164
	v_min_f32_e32 v164, v150, v151
	v_max_f32_e32 v150, v150, v151
	v_mov_b32_e32 v151, v164
	v_min_f32_e32 v164, v151, v152
	v_max_f32_e32 v151, v151, v152
	v_mov_b32_e32 v152, v164
	v_min_f32_e32 v164, v152, v153
	v_max_f32_e32 v152, v152, v153
	v_mov_b32_e32 v153, v164
	v_min_f32_e32 v164, v153, v154
	v_max_f32_e32 v153, v153, v154
	v_mov_b32_e32 v154, v164
	v_min_f32_e32 v164, v154, v155
	v_max_f32_e32 v154, v154, v155
	v_mov_b32_e32 v155, v164
	v_min_f32_e32 v164, v155, v156
	v_max_f32_e32 v155, v155, v156
	v_mov_b32_e32 v156, v164
	v_min_f32_e32 v164, v156, v157
	v_max_f32_e32 v156, v156, v157
	v_mov_b32_e32 v157, v164
	v_min_f32_e32 v164, v157, v158
	v_max_f32_e32 v157, v157, v158
	v_mov_b32_e32 v158, v164
	v_min_f32_e32 v164, v158, v159
	v_max_f32_e32 v158, v158, v159
; DEV void ce(float& a, float& b) { float hi = fmaxf(a, b), lo = fminf(a, b); a = hi; b = lo; }
; DEV void phase_peer_score(const Params& p, int layer, int M, char* smem) {
;     ...
;     float R[16];
; #pragma unroll
;     for (int i = 0; i < 16; i++) R[i] = -3.0e38f;
; #pragma unroll
;     for (int i = 0; i < 16; i++)
; #pragma unroll
;       for (int j = 0; j < 16; j++)
;         if ((i + 1) * (j + 1) <= 16) {
;           float v = L0[i] + L1[j];
;           v = __uint_as_float((__float_as_uint(v) & ~255u) | (unsigned)(i * 16 + j));
; #pragma unroll
;           for (int t = 0; t < 16; t++)
;             if (t >= (i + 1) * (j + 1) - 1) ce(R[t], v);
;         }
	v_mov_b32_e32 v159, v164
	v_min_f32_e32 v164, v159, v160
	v_max_f32_e32 v159, v159, v160
	v_mov_b32_e32 v160, v164
	v_min_f32_e32 v164, v160, v161
	v_max_f32_e32 v160, v160, v161
	v_mov_b32_e32 v161, v164
	v_min_f32_e32 v164, v161, v162
	v_max_f32_e32 v161, v161, v162
	v_mov_b32_e32 v162, v164
	v_min_f32_e32 v164, v162, v163
	v_max_f32_e32 v162, v162, v163
	v_mov_b32_e32 v163, v164
	v_add_f32_e32 v164, v91, v2
	v_and_or_b32 v164, v164, s18, 16
	v_med3_f32 v163, v162, v163, v164
	v_med3_f32 v162, v161, v162, v164
	v_med3_f32 v161, v160, v161, v164
	v_med3_f32 v160, v159, v160, v164
	v_med3_f32 v159, v158, v159, v164
	v_med3_f32 v158, v157, v158, v164
	v_med3_f32 v157, v156, v157, v164
	v_med3_f32 v156, v155, v156, v164
	v_med3_f32 v155, v154, v155, v164
	v_med3_f32 v154, v153, v154, v164
	v_med3_f32 v153, v152, v153, v164
	v_med3_f32 v152, v151, v152, v164
	v_med3_f32 v151, v150, v151, v164
	v_med3_f32 v150, v149, v150, v164
	v_med3_f32 v149, v148, v149, v164
	v_max_f32_e32 v148, v148, v164
	v_add_f32_e32 v164, v91, v4
	v_and_or_b32 v164, v164, s18, 17
	v_med3_f32 v163, v162, v163, v164
	v_med3_f32 v162, v161, v162, v164
	v_med3_f32 v161, v160, v161, v164
	v_med3_f32 v160, v159, v160, v164
	v_med3_f32 v159, v158, v159, v164
	v_med3_f32 v158, v157, v158, v164
	v_med3_f32 v157, v156, v157, v164
	v_med3_f32 v156, v155, v156, v164
	v_med3_f32 v155, v154, v155, v164
	v_med3_f32 v154, v153, v154, v164
	v_med3_f32 v153, v152, v153, v164
	v_med3_f32 v152, v151, v152, v164
	v_med3_f32 v151, v150, v151, v164
	v_max_f32_e32 v150, v150, v164
	v_add_f32_e32 v164, v91, v7
	v_and_or_b32 v164, v164, s18, 18
	v_med3_f32 v163, v162, v163, v164
	v_med3_f32 v162, v161, v162, v164
	v_med3_f32 v161, v160, v161, v164
	v_med3_f32 v160, v159, v160, v164
	v_med3_f32 v159, v158, v159, v164
	v_med3_f32 v158, v157, v158, v164
	v_med3_f32 v157, v156, v157, v164
	v_med3_f32 v156, v155, v156, v164
	v_med3_f32 v155, v154, v155, v164
	v_med3_f32 v154, v153, v154, v164
	v_med3_f32 v153, v152, v153, v164
	v_max_f32_e32 v152, v152, v164
	v_add_f32_e32 v164, v91, v8
	v_and_or_b32 v164, v164, s18, 19
	v_med3_f32 v163, v162, v163, v164
	v_med3_f32 v162, v161, v162, v164
	v_med3_f32 v161, v160, v161, v164
	v_med3_f32 v160, v159, v160, v164
	v_med3_f32 v159, v158, v159, v164
	v_med3_f32 v158, v157, v158, v164
	v_med3_f32 v157, v156, v157, v164
	v_med3_f32 v156, v155, v156, v164
	v_med3_f32 v155, v154, v155, v164
	v_max_f32_e32 v154, v154, v164
	v_add_f32_e32 v164, v91, v9
	v_and_or_b32 v164, v164, s18, 20
	v_med3_f32 v163, v162, v163, v164
	v_med3_f32 v162, v161, v162, v164
	v_med3_f32 v161, v160, v161, v164
	v_med3_f32 v160, v159, v160, v164
	v_med3_f32 v159, v158, v159, v164
	v_med3_f32 v158, v157, v158, v164
	v_med3_f32 v157, v156, v157, v164
	v_max_f32_e32 v156, v156, v164
	v_add_f32_e32 v164, v91, v12
	v_and_or_b32 v164, v164, s18, 21
	v_med3_f32 v163, v162, v163, v164
	v_med3_f32 v162, v161, v162, v164
	v_med3_f32 v161, v160, v161, v164
	v_med3_f32 v160, v159, v160, v164
	v_med3_f32 v159, v158, v159, v164
	v_max_f32_e32 v158, v158, v164
	v_add_f32_e32 v164, v91, v11
	v_and_or_b32 v164, v164, s18, 22
	v_med3_f32 v163, v162, v163, v164
	v_med3_f32 v162, v161, v162, v164
	v_med3_f32 v161, v160, v161, v164
	v_max_f32_e32 v160, v160, v164
	v_add_f32_e32 v164, v91, v10
	v_and_or_b32 v164, v164, s18, 23
	v_med3_f32 v163, v162, v163, v164
	v_max_f32_e32 v162, v162, v164
	v_add_f32_e32 v164, v87, v2
	v_and_or_b32 v164, v164, s18, 32
	v_med3_f32 v163, v162, v163, v164
	v_med3_f32 v162, v161, v162, v164
	v_med3_f32 v161, v160, v161, v164
	v_med3_f32 v160, v159, v160, v164
	v_med3_f32 v159, v158, v159, v164
	v_med3_f32 v158, v157, v158, v164
	v_med3_f32 v157, v156, v157, v164
	v_med3_f32 v156, v155, v156, v164
	v_med3_f32 v155, v154, v155, v164
	v_med3_f32 v154, v153, v154, v164
	v_med3_f32 v153, v152, v153, v164
	v_med3_f32 v152, v151, v152, v164
	v_med3_f32 v151, v150, v151, v164
	v_med3_f32 v150, v149, v150, v164
	v_max_f32_e32 v149, v149, v164
	v_add_f32_e32 v164, v87, v4
	v_and_or_b32 v164, v164, s18, 33
	v_med3_f32 v163, v162, v163, v164
	v_med3_f32 v162, v161, v162, v164
	v_med3_f32 v161, v160, v161, v164
	v_med3_f32 v160, v159, v160, v164
	v_med3_f32 v159, v158, v159, v164
	v_med3_f32 v158, v157, v158, v164
	v_med3_f32 v157, v156, v157, v164
	v_med3_f32 v156, v155, v156, v164
	v_med3_f32 v155, v154, v155, v164
	v_med3_f32 v154, v153, v154, v164
	v_med3_f32 v153, v152, v153, v164
	v_max_f32_e32 v152, v152, v164
	v_add_f32_e32 v164, v87, v7
	v_and_or_b32 v164, v164, s18, 34
	v_med3_f32 v163, v162, v163, v164
	v_med3_f32 v162, v161, v162, v164
	v_med3_f32 v161, v160, v161, v164
	v_med3_f32 v160, v159, v160, v164
	v_med3_f32 v159, v158, v159, v164
	v_med3_f32 v158, v157, v158, v164
	v_med3_f32 v157, v156, v157, v164
	v_med3_f32 v156, v155, v156, v164
	v_max_f32_e32 v155, v155, v164
	v_add_f32_e32 v164, v87, v8
	v_and_or_b32 v164, v164, s18, 35
	v_med3_f32 v163, v162, v163, v164
	v_med3_f32 v162, v161, v162, v164
	v_med3_f32 v161, v160, v161, v164
	v_med3_f32 v160, v159, v160, v164
	v_med3_f32 v159, v158, v159, v164
	v_max_f32_e32 v158, v158, v164
	v_add_f32_e32 v164, v87, v9
	v_and_or_b32 v164, v164, s18, 36
	v_med3_f32 v163, v162, v163, v164
	v_med3_f32 v162, v161, v162, v164
	v_max_f32_e32 v161, v161, v164
	v_add_f32_e32 v164, v83, v2
	v_and_or_b32 v164, v164, s18, 48
	v_med3_f32 v163, v162, v163, v164
	v_med3_f32 v162, v161, v162, v164
	v_med3_f32 v161, v160, v161, v164
	v_med3_f32 v160, v159, v160, v164
	v_med3_f32 v159, v158, v159, v164
	v_med3_f32 v158, v157, v158, v164
	v_med3_f32 v157, v156, v157, v164
	v_med3_f32 v156, v155, v156, v164
	v_med3_f32 v155, v154, v155, v164
; DEV void ce(float& a, float& b) { float hi = fmaxf(a, b), lo = fminf(a, b); a = hi; b = lo; }
; DEV void phase_peer_score(const Params& p, int layer, int M, char* smem) {
;     ...
;     float R[16];
; #pragma unroll
;     for (int i = 0; i < 16; i++) R[i] = -3.0e38f;
; #pragma unroll
;     for (int i = 0; i < 16; i++)
; #pragma unroll
;       for (int j = 0; j < 16; j++)
;         if ((i + 1) * (j + 1) <= 16) {
;           float v = L0[i] + L1[j];
;           v = __uint_as_float((__float_as_uint(v) & ~255u) | (unsigned)(i * 16 + j));
; #pragma unroll
;           for (int t = 0; t < 16; t++)
;             if (t >= (i + 1) * (j + 1) - 1) ce(R[t], v);
;         }
	v_med3_f32 v154, v153, v154, v164
	v_med3_f32 v153, v152, v153, v164
	v_med3_f32 v152, v151, v152, v164
	v_med3_f32 v151, v150, v151, v164
	v_max_f32_e32 v150, v150, v164
	v_add_f32_e32 v164, v83, v4
	v_and_or_b32 v164, v164, s18, 49
	v_med3_f32 v163, v162, v163, v164
	v_med3_f32 v162, v161, v162, v164
	v_med3_f32 v161, v160, v161, v164
	v_med3_f32 v160, v159, v160, v164
	v_med3_f32 v159, v158, v159, v164
	v_med3_f32 v158, v157, v158, v164
	v_med3_f32 v157, v156, v157, v164
	v_med3_f32 v156, v155, v156, v164
	v_med3_f32 v155, v154, v155, v164
	v_max_f32_e32 v154, v154, v164
	v_add_f32_e32 v164, v83, v7
	v_and_or_b32 v164, v164, s18, 50
	v_med3_f32 v163, v162, v163, v164
	v_med3_f32 v162, v161, v162, v164
	v_med3_f32 v161, v160, v161, v164
	v_med3_f32 v160, v159, v160, v164
	v_med3_f32 v159, v158, v159, v164
	v_max_f32_e32 v158, v158, v164
	v_add_f32_e32 v164, v83, v8
	v_and_or_b32 v164, v164, s18, 51
	v_med3_f32 v163, v162, v163, v164
	v_max_f32_e32 v162, v162, v164
	v_add_f32_e32 v164, v79, v2
	v_and_or_b32 v164, v164, s18, 64
	v_med3_f32 v163, v162, v163, v164
	v_med3_f32 v162, v161, v162, v164
	v_med3_f32 v161, v160, v161, v164
	v_med3_f32 v160, v159, v160, v164
	v_med3_f32 v159, v158, v159, v164
	v_med3_f32 v158, v157, v158, v164
	v_med3_f32 v157, v156, v157, v164
	v_med3_f32 v156, v155, v156, v164
	v_med3_f32 v155, v154, v155, v164
	v_med3_f32 v154, v153, v154, v164
	v_med3_f32 v153, v152, v153, v164
	v_med3_f32 v152, v151, v152, v164
	v_max_f32_e32 v151, v151, v164
	v_add_f32_e32 v164, v79, v4
	v_and_b32_e32 v164, 0xffffff00, v164
	v_or_b32_e32 v164, 0x41, v164
	v_med3_f32 v163, v162, v163, v164
	v_med3_f32 v162, v161, v162, v164
	v_med3_f32 v161, v160, v161, v164
	v_med3_f32 v160, v159, v160, v164
	v_med3_f32 v159, v158, v159, v164
	v_med3_f32 v158, v157, v158, v164
	v_med3_f32 v157, v156, v157, v164
	v_max_f32_e32 v156, v156, v164
	v_add_f32_e32 v164, v79, v7
	v_and_b32_e32 v164, 0xffffff00, v164
	v_or_b32_e32 v164, 0x42, v164
	v_med3_f32 v163, v162, v163, v164
	v_med3_f32 v162, v161, v162, v164
	v_max_f32_e32 v161, v161, v164
	v_add_f32_e32 v164, v75, v2
	v_and_b32_e32 v164, 0xffffff00, v164
	v_or_b32_e32 v164, 0x50, v164
	v_med3_f32 v163, v162, v163, v164
	v_med3_f32 v162, v161, v162, v164
	v_med3_f32 v161, v160, v161, v164
	v_med3_f32 v160, v159, v160, v164
	v_med3_f32 v159, v158, v159, v164
	v_med3_f32 v158, v157, v158, v164
	v_med3_f32 v157, v156, v157, v164
	v_med3_f32 v156, v155, v156, v164
	v_med3_f32 v155, v154, v155, v164
	v_med3_f32 v154, v153, v154, v164
	v_med3_f32 v153, v152, v153, v164
	v_max_f32_e32 v152, v152, v164
	v_add_f32_e32 v164, v75, v4
	v_and_b32_e32 v164, 0xffffff00, v164
	v_or_b32_e32 v164, 0x51, v164
	v_med3_f32 v163, v162, v163, v164
	v_med3_f32 v162, v161, v162, v164
	v_med3_f32 v161, v160, v161, v164
	v_med3_f32 v160, v159, v160, v164
	v_med3_f32 v159, v158, v159, v164
	v_max_f32_e32 v158, v158, v164
	v_add_f32_e32 v164, v71, v2
	v_and_b32_e32 v164, 0xffffff00, v164
	v_or_b32_e32 v164, 0x60, v164
	v_med3_f32 v163, v162, v163, v164
	v_med3_f32 v162, v161, v162, v164
	v_med3_f32 v161, v160, v161, v164
	v_med3_f32 v160, v159, v160, v164
	v_med3_f32 v159, v158, v159, v164
	v_med3_f32 v158, v157, v158, v164
	v_med3_f32 v157, v156, v157, v164
	v_med3_f32 v156, v155, v156, v164
	v_med3_f32 v155, v154, v155, v164
	v_med3_f32 v154, v153, v154, v164
	v_max_f32_e32 v153, v153, v164
	v_add_f32_e32 v164, v71, v4
	v_and_b32_e32 v164, 0xffffff00, v164
	v_or_b32_e32 v164, 0x61, v164
	v_med3_f32 v163, v162, v163, v164
	v_med3_f32 v162, v161, v162, v164
	v_med3_f32 v161, v160, v161, v164
	v_max_f32_e32 v160, v160, v164
	v_add_f32_e32 v164, v63, v2
	v_and_b32_e32 v164, 0xffffff00, v164
	v_or_b32_e32 v164, 0x70, v164
	v_med3_f32 v163, v162, v163, v164
	v_med3_f32 v162, v161, v162, v164
	v_med3_f32 v161, v160, v161, v164
	v_med3_f32 v160, v159, v160, v164
	v_med3_f32 v159, v158, v159, v164
	v_med3_f32 v158, v157, v158, v164
	v_med3_f32 v157, v156, v157, v164
	v_med3_f32 v156, v155, v156, v164
	v_med3_f32 v155, v154, v155, v164
	v_max_f32_e32 v154, v154, v164
	v_add_f32_e32 v164, v63, v4
	v_and_b32_e32 v164, 0xffffff00, v164
	v_or_b32_e32 v164, 0x71, v164
	v_med3_f32 v163, v162, v163, v164
	v_max_f32_e32 v162, v162, v164
	v_add_f32_e32 v164, v67, v2
	v_and_b32_e32 v164, 0xffffff00, v164
	v_or_b32_e32 v164, 0x80, v164
	v_med3_f32 v163, v162, v163, v164
	v_med3_f32 v162, v161, v162, v164
	v_med3_f32 v161, v160, v161, v164
	v_med3_f32 v160, v159, v160, v164
	v_med3_f32 v159, v158, v159, v164
	v_med3_f32 v158, v157, v158, v164
	v_med3_f32 v157, v156, v157, v164
	v_med3_f32 v156, v155, v156, v164
	v_max_f32_e32 v155, v155, v164
	v_add_f32_e32 v164, v59, v2
	v_and_b32_e32 v164, 0xffffff00, v164
	v_or_b32_e32 v164, 0x90, v164
	v_med3_f32 v163, v162, v163, v164
	v_med3_f32 v162, v161, v162, v164
	v_med3_f32 v161, v160, v161, v164
	v_med3_f32 v160, v159, v160, v164
	v_med3_f32 v159, v158, v159, v164
	v_med3_f32 v158, v157, v158, v164
	v_med3_f32 v157, v156, v157, v164
	v_max_f32_e32 v156, v156, v164
	v_add_f32_e32 v164, v55, v2
	v_and_b32_e32 v164, 0xffffff00, v164
	v_or_b32_e32 v164, 0xa0, v164
	v_med3_f32 v163, v162, v163, v164
	v_med3_f32 v162, v161, v162, v164
	v_med3_f32 v161, v160, v161, v164
	v_med3_f32 v160, v159, v160, v164
	v_med3_f32 v159, v158, v159, v164
	v_med3_f32 v158, v157, v158, v164
	v_max_f32_e32 v157, v157, v164
	v_add_f32_e32 v164, v47, v2
	v_and_b32_e32 v164, 0xffffff00, v164
	v_or_b32_e32 v164, 0xb0, v164
	v_med3_f32 v163, v162, v163, v164
	v_med3_f32 v162, v161, v162, v164
	v_med3_f32 v161, v160, v161, v164
	v_med3_f32 v160, v159, v160, v164
	v_med3_f32 v159, v158, v159, v164
	v_max_f32_e32 v158, v158, v164
; DEV void ce(float& a, float& b) { float hi = fmaxf(a, b), lo = fminf(a, b); a = hi; b = lo; }
; DEV void phase_peer_score(const Params& p, int layer, int M, char* smem) {
;     ...
;     float R[16];
; #pragma unroll
;     for (int i = 0; i < 16; i++) R[i] = -3.0e38f;
; #pragma unroll
;     for (int i = 0; i < 16; i++)
; #pragma unroll
;       for (int j = 0; j < 16; j++)
;         if ((i + 1) * (j + 1) <= 16) {
;           float v = L0[i] + L1[j];
;           v = __uint_as_float((__float_as_uint(v) & ~255u) | (unsigned)(i * 16 + j));
; #pragma unroll
;           for (int t = 0; t < 16; t++)
;             if (t >= (i + 1) * (j + 1) - 1) ce(R[t], v);
;         }
	v_add_f32_e32 v164, v51, v2
	v_and_b32_e32 v164, 0xffffff00, v164
	v_or_b32_e32 v164, 0xc0, v164
	v_med3_f32 v163, v162, v163, v164
	v_med3_f32 v162, v161, v162, v164
	v_med3_f32 v161, v160, v161, v164
	v_med3_f32 v160, v159, v160, v164
	v_max_f32_e32 v159, v159, v164
	v_add_f32_e32 v164, v39, v2
	v_and_b32_e32 v164, 0xffffff00, v164
	v_or_b32_e32 v164, 0xd0, v164
	v_med3_f32 v163, v162, v163, v164
	v_med3_f32 v162, v161, v162, v164
	v_med3_f32 v161, v160, v161, v164
	v_max_f32_e32 v160, v160, v164
	v_add_f32_e32 v164, v43, v2
	v_and_b32_e32 v164, 0xffffff00, v164
	v_or_b32_e32 v164, 0xe0, v164
	v_med3_f32 v163, v162, v163, v164
	v_med3_f32 v162, v161, v162, v164
	v_max_f32_e32 v161, v161, v164
	v_add_f32_e32 v164, v0, v2
	v_and_b32_e32 v164, 0xffffff00, v164
	v_or_b32_e32 v164, 0xf0, v164
	v_med3_f32 v163, v162, v163, v164
	v_max_f32_e32 v162, v162, v164
	v_cmp_le_f32_e64 s[40:41], v148, v149
	v_cmp_le_f32_e32 vcc, v149, v150
	s_or_b64 s[40:41], s[40:41], vcc
	v_cmp_le_f32_e32 vcc, v150, v151
	s_or_b64 s[40:41], s[40:41], vcc
	v_cmp_le_f32_e32 vcc, v151, v152
	s_or_b64 s[40:41], s[40:41], vcc
	v_cmp_le_f32_e32 vcc, v152, v153
	s_or_b64 s[40:41], s[40:41], vcc
	v_cmp_le_f32_e32 vcc, v153, v154
	s_or_b64 s[40:41], s[40:41], vcc
	v_cmp_le_f32_e32 vcc, v154, v155
	s_or_b64 s[40:41], s[40:41], vcc
	v_cmp_le_f32_e32 vcc, v155, v156
	s_or_b64 s[40:41], s[40:41], vcc
	v_cmp_le_f32_e32 vcc, v156, v157
	s_or_b64 s[40:41], s[40:41], vcc
	v_cmp_le_f32_e32 vcc, v157, v158
	s_or_b64 s[40:41], s[40:41], vcc
	v_cmp_le_f32_e32 vcc, v158, v159
	s_or_b64 s[40:41], s[40:41], vcc
	v_cmp_le_f32_e32 vcc, v159, v160
	s_or_b64 s[40:41], s[40:41], vcc
	v_cmp_le_f32_e32 vcc, v160, v161
	s_or_b64 s[40:41], s[40:41], vcc
	v_cmp_le_f32_e32 vcc, v161, v162
	s_or_b64 s[40:41], s[40:41], vcc
	v_cmp_le_f32_e32 vcc, v162, v163
	s_or_b64 s[40:41], s[40:41], vcc
	s_and_b64 s[40:41], s[40:41], exec
	s_cbranch_scc0 .Lmed3_ok_bb_637
	v_mov_b32_e32 v148, 0xff61b1e6
	v_mov_b32_e32 v149, 0xff61b1e6
	v_mov_b32_e32 v150, 0xff61b1e6
	v_mov_b32_e32 v151, 0xff61b1e6
	v_mov_b32_e32 v152, 0xff61b1e6
	v_mov_b32_e32 v153, 0xff61b1e6
	v_mov_b32_e32 v154, 0xff61b1e6
	v_mov_b32_e32 v155, 0xff61b1e6
	v_mov_b32_e32 v156, 0xff61b1e6
	v_mov_b32_e32 v157, 0xff61b1e6
	v_mov_b32_e32 v158, 0xff61b1e6
	v_mov_b32_e32 v159, 0xff61b1e6
	v_mov_b32_e32 v160, 0xff61b1e6
	v_mov_b32_e32 v161, 0xff61b1e6
	v_mov_b32_e32 v162, 0xff61b1e6
	v_mov_b32_e32 v163, 0xff61b1e6
	v_add_f32_e32 v164, v100, v2
	v_and_or_b32 v164, v164, s18, 0
	v_min_f32_e32 v165, v148, v164
	v_max_f32_e32 v148, v148, v164
	v_min_f32_e32 v164, v149, v165
	v_max_f32_e32 v149, v149, v165
	v_min_f32_e32 v165, v150, v164
	v_max_f32_e32 v150, v150, v164
	v_min_f32_e32 v164, v151, v165
	v_max_f32_e32 v151, v151, v165
	v_min_f32_e32 v165, v152, v164
	v_max_f32_e32 v152, v152, v164
	v_min_f32_e32 v164, v153, v165
	v_max_f32_e32 v153, v153, v165
	v_min_f32_e32 v165, v154, v164
	v_max_f32_e32 v154, v154, v164
	v_min_f32_e32 v164, v155, v165
	v_max_f32_e32 v155, v155, v165
	v_min_f32_e32 v165, v156, v164
	v_max_f32_e32 v156, v156, v164
	v_min_f32_e32 v164, v157, v165
	v_max_f32_e32 v157, v157, v165
	v_min_f32_e32 v165, v158, v164
	v_max_f32_e32 v158, v158, v164
	v_min_f32_e32 v164, v159, v165
	v_max_f32_e32 v159, v159, v165
	v_min_f32_e32 v165, v160, v164
	v_max_f32_e32 v160, v160, v164
	v_min_f32_e32 v164, v161, v165
	v_max_f32_e32 v161, v161, v165
	v_min_f32_e32 v165, v162, v164
	v_max_f32_e32 v162, v162, v164
	v_max_f32_e32 v163, v163, v165
	v_add_f32_e32 v164, v100, v4
	v_and_or_b32 v164, v164, s18, 1
	v_min_f32_e32 v165, v149, v164
	v_max_f32_e32 v149, v149, v164
	v_min_f32_e32 v164, v150, v165
	v_max_f32_e32 v150, v150, v165
	v_min_f32_e32 v165, v151, v164
	v_max_f32_e32 v151, v151, v164
	v_min_f32_e32 v164, v152, v165
	v_max_f32_e32 v152, v152, v165
	v_min_f32_e32 v165, v153, v164
	v_max_f32_e32 v153, v153, v164
	v_min_f32_e32 v164, v154, v165
	v_max_f32_e32 v154, v154, v165
	v_min_f32_e32 v165, v155, v164
	v_max_f32_e32 v155, v155, v164
	v_min_f32_e32 v164, v156, v165
	v_max_f32_e32 v156, v156, v165
	v_min_f32_e32 v165, v157, v164
	v_max_f32_e32 v157, v157, v164
	v_min_f32_e32 v164, v158, v165
	v_max_f32_e32 v158, v158, v165
	v_min_f32_e32 v165, v159, v164
	v_max_f32_e32 v159, v159, v164
	v_min_f32_e32 v164, v160, v165
	v_max_f32_e32 v160, v160, v165
	v_min_f32_e32 v165, v161, v164
	v_max_f32_e32 v161, v161, v164
	v_min_f32_e32 v164, v162, v165
	v_max_f32_e32 v162, v162, v165
	v_max_f32_e32 v163, v163, v164
	v_add_f32_e32 v164, v100, v7
	v_and_or_b32 v164, v164, s18, 2
	v_min_f32_e32 v165, v150, v164
	v_max_f32_e32 v150, v150, v164
	v_min_f32_e32 v164, v151, v165
	v_max_f32_e32 v151, v151, v165
	v_min_f32_e32 v165, v152, v164
	v_max_f32_e32 v152, v152, v164
	v_min_f32_e32 v164, v153, v165
	v_max_f32_e32 v153, v153, v165
	v_min_f32_e32 v165, v154, v164
	v_max_f32_e32 v154, v154, v164
	v_min_f32_e32 v164, v155, v165
	v_max_f32_e32 v155, v155, v165
	v_min_f32_e32 v165, v156, v164
	v_max_f32_e32 v156, v156, v164
	v_min_f32_e32 v164, v157, v165
	v_max_f32_e32 v157, v157, v165
	v_min_f32_e32 v165, v158, v164
	v_max_f32_e32 v158, v158, v164
	v_min_f32_e32 v164, v159, v165
	v_max_f32_e32 v159, v159, v165
	v_min_f32_e32 v165, v160, v164
	v_max_f32_e32 v160, v160, v164
	v_min_f32_e32 v164, v161, v165
	v_max_f32_e32 v161, v161, v165
	v_min_f32_e32 v165, v162, v164
	v_max_f32_e32 v162, v162, v164
	v_max_f32_e32 v163, v163, v165
	v_add_f32_e32 v164, v100, v8
	v_and_or_b32 v164, v164, s18, 3
	v_min_f32_e32 v165, v151, v164
	v_max_f32_e32 v151, v151, v164
	v_min_f32_e32 v164, v152, v165
	v_max_f32_e32 v152, v152, v165
	v_min_f32_e32 v165, v153, v164
; DEV void ce(float& a, float& b) { float hi = fmaxf(a, b), lo = fminf(a, b); a = hi; b = lo; }
; DEV void phase_peer_score(const Params& p, int layer, int M, char* smem) {
;     ...
;     float R[16];
; #pragma unroll
;     for (int i = 0; i < 16; i++) R[i] = -3.0e38f;
; #pragma unroll
;     for (int i = 0; i < 16; i++)
; #pragma unroll
;       for (int j = 0; j < 16; j++)
;         if ((i + 1) * (j + 1) <= 16) {
;           float v = L0[i] + L1[j];
;           v = __uint_as_float((__float_as_uint(v) & ~255u) | (unsigned)(i * 16 + j));
; #pragma unroll
;           for (int t = 0; t < 16; t++)
;             if (t >= (i + 1) * (j + 1) - 1) ce(R[t], v);
;         }
	v_max_f32_e32 v153, v153, v164
	v_min_f32_e32 v164, v154, v165
	v_max_f32_e32 v154, v154, v165
	v_min_f32_e32 v165, v155, v164
	v_max_f32_e32 v155, v155, v164
	v_min_f32_e32 v164, v156, v165
	v_max_f32_e32 v156, v156, v165
	v_min_f32_e32 v165, v157, v164
	v_max_f32_e32 v157, v157, v164
	v_min_f32_e32 v164, v158, v165
	v_max_f32_e32 v158, v158, v165
	v_min_f32_e32 v165, v159, v164
	v_max_f32_e32 v159, v159, v164
	v_min_f32_e32 v164, v160, v165
	v_max_f32_e32 v160, v160, v165
	v_min_f32_e32 v165, v161, v164
	v_max_f32_e32 v161, v161, v164
	v_min_f32_e32 v164, v162, v165
	v_max_f32_e32 v162, v162, v165
	v_max_f32_e32 v163, v163, v164
	v_add_f32_e32 v164, v100, v9
	v_and_or_b32 v164, v164, s18, 4
	v_min_f32_e32 v165, v152, v164
	v_max_f32_e32 v152, v152, v164
	v_min_f32_e32 v164, v153, v165
	v_max_f32_e32 v153, v153, v165
	v_min_f32_e32 v165, v154, v164
	v_max_f32_e32 v154, v154, v164
	v_min_f32_e32 v164, v155, v165
	v_max_f32_e32 v155, v155, v165
	v_min_f32_e32 v165, v156, v164
	v_max_f32_e32 v156, v156, v164
	v_min_f32_e32 v164, v157, v165
	v_max_f32_e32 v157, v157, v165
	v_min_f32_e32 v165, v158, v164
	v_max_f32_e32 v158, v158, v164
	v_min_f32_e32 v164, v159, v165
	v_max_f32_e32 v159, v159, v165
	v_min_f32_e32 v165, v160, v164
	v_max_f32_e32 v160, v160, v164
	v_min_f32_e32 v164, v161, v165
	v_max_f32_e32 v161, v161, v165
	v_min_f32_e32 v165, v162, v164
	v_max_f32_e32 v162, v162, v164
	v_max_f32_e32 v163, v163, v165
	v_add_f32_e32 v164, v100, v12
	v_and_or_b32 v164, v164, s18, 5
	v_min_f32_e32 v165, v153, v164
	v_max_f32_e32 v153, v153, v164
	v_min_f32_e32 v164, v154, v165
	v_max_f32_e32 v154, v154, v165
	v_min_f32_e32 v165, v155, v164
	v_max_f32_e32 v155, v155, v164
	v_min_f32_e32 v164, v156, v165
	v_max_f32_e32 v156, v156, v165
	v_min_f32_e32 v165, v157, v164
	v_max_f32_e32 v157, v157, v164
	v_min_f32_e32 v164, v158, v165
	v_max_f32_e32 v158, v158, v165
	v_min_f32_e32 v165, v159, v164
	v_max_f32_e32 v159, v159, v164
	v_min_f32_e32 v164, v160, v165
	v_max_f32_e32 v160, v160, v165
	v_min_f32_e32 v165, v161, v164
	v_max_f32_e32 v161, v161, v164
	v_min_f32_e32 v164, v162, v165
	v_max_f32_e32 v162, v162, v165
	v_max_f32_e32 v163, v163, v164
	v_add_f32_e32 v164, v100, v11
	v_and_or_b32 v164, v164, s18, 6
	v_min_f32_e32 v165, v154, v164
	v_max_f32_e32 v154, v154, v164
	v_min_f32_e32 v164, v155, v165
	v_max_f32_e32 v155, v155, v165
	v_min_f32_e32 v165, v156, v164
	v_max_f32_e32 v156, v156, v164
	v_min_f32_e32 v164, v157, v165
	v_max_f32_e32 v157, v157, v165
	v_min_f32_e32 v165, v158, v164
	v_max_f32_e32 v158, v158, v164
	v_min_f32_e32 v164, v159, v165
	v_max_f32_e32 v159, v159, v165
	v_min_f32_e32 v165, v160, v164
	v_max_f32_e32 v160, v160, v164
	v_min_f32_e32 v164, v161, v165
	v_max_f32_e32 v161, v161, v165
	v_min_f32_e32 v165, v162, v164
	v_max_f32_e32 v162, v162, v164
	v_max_f32_e32 v163, v163, v165
	v_add_f32_e32 v164, v100, v10
	v_and_or_b32 v164, v164, s18, 7
	v_min_f32_e32 v165, v155, v164
	v_max_f32_e32 v155, v155, v164
	v_min_f32_e32 v164, v156, v165
	v_max_f32_e32 v156, v156, v165
	v_min_f32_e32 v165, v157, v164
	v_max_f32_e32 v157, v157, v164
	v_min_f32_e32 v164, v158, v165
	v_max_f32_e32 v158, v158, v165
	v_min_f32_e32 v165, v159, v164
	v_max_f32_e32 v159, v159, v164
	v_min_f32_e32 v164, v160, v165
	v_max_f32_e32 v160, v160, v165
	v_min_f32_e32 v165, v161, v164
	v_max_f32_e32 v161, v161, v164
	v_min_f32_e32 v164, v162, v165
	v_max_f32_e32 v162, v162, v165
	v_max_f32_e32 v163, v163, v164
	v_add_f32_e32 v164, v100, v20
	v_and_or_b32 v164, v164, s18, 8
	v_min_f32_e32 v165, v156, v164
	v_max_f32_e32 v156, v156, v164
	v_min_f32_e32 v164, v157, v165
	v_max_f32_e32 v157, v157, v165
	v_min_f32_e32 v165, v158, v164
	v_max_f32_e32 v158, v158, v164
	v_min_f32_e32 v164, v159, v165
	v_max_f32_e32 v159, v159, v165
	v_min_f32_e32 v165, v160, v164
	v_max_f32_e32 v160, v160, v164
	v_min_f32_e32 v164, v161, v165
	v_max_f32_e32 v161, v161, v165
	v_min_f32_e32 v165, v162, v164
	v_max_f32_e32 v162, v162, v164
	v_max_f32_e32 v163, v163, v165
	v_add_f32_e32 v164, v100, v17
	v_and_or_b32 v164, v164, s18, 9
	v_min_f32_e32 v165, v157, v164
	v_max_f32_e32 v157, v157, v164
	v_min_f32_e32 v164, v158, v165
	v_max_f32_e32 v158, v158, v165
	v_min_f32_e32 v165, v159, v164
	v_max_f32_e32 v159, v159, v164
	v_min_f32_e32 v164, v160, v165
	v_max_f32_e32 v160, v160, v165
	v_min_f32_e32 v165, v161, v164
	v_max_f32_e32 v161, v161, v164
	v_min_f32_e32 v164, v162, v165
	v_max_f32_e32 v162, v162, v165
	v_max_f32_e32 v163, v163, v164
	v_add_f32_e32 v164, v100, v16
	v_and_or_b32 v164, v164, s18, 10
	v_min_f32_e32 v165, v158, v164
	v_max_f32_e32 v158, v158, v164
	v_min_f32_e32 v164, v159, v165
	v_max_f32_e32 v159, v159, v165
	v_min_f32_e32 v165, v160, v164
	v_max_f32_e32 v160, v160, v164
	v_min_f32_e32 v164, v161, v165
	v_max_f32_e32 v161, v161, v165
	v_min_f32_e32 v165, v162, v164
	v_max_f32_e32 v162, v162, v164
	v_max_f32_e32 v163, v163, v165
	v_add_f32_e32 v164, v100, v15
	v_and_or_b32 v164, v164, s18, 11
	v_min_f32_e32 v165, v159, v164
	v_max_f32_e32 v159, v159, v164
	v_min_f32_e32 v164, v160, v165
	v_max_f32_e32 v160, v160, v165
	v_min_f32_e32 v165, v161, v164
	v_max_f32_e32 v161, v161, v164
	v_min_f32_e32 v164, v162, v165
	v_max_f32_e32 v162, v162, v165
	v_max_f32_e32 v163, v163, v164
	v_add_f32_e32 v164, v100, v14
	v_and_or_b32 v164, v164, s18, 12
	v_min_f32_e32 v165, v160, v164
	v_max_f32_e32 v160, v160, v164
	v_min_f32_e32 v164, v161, v165
	v_max_f32_e32 v161, v161, v165
	v_min_f32_e32 v165, v162, v164
	v_max_f32_e32 v162, v162, v164
	v_max_f32_e32 v163, v163, v165
	v_add_f32_e32 v164, v100, v13
	v_and_or_b32 v164, v164, s18, 13
	v_min_f32_e32 v165, v161, v164
; DEV void ce(float& a, float& b) { float hi = fmaxf(a, b), lo = fminf(a, b); a = hi; b = lo; }
; DEV void phase_peer_score(const Params& p, int layer, int M, char* smem) {
;     ...
;     float R[16];
; #pragma unroll
;     for (int i = 0; i < 16; i++) R[i] = -3.0e38f;
; #pragma unroll
;     for (int i = 0; i < 16; i++)
; #pragma unroll
;       for (int j = 0; j < 16; j++)
;         if ((i + 1) * (j + 1) <= 16) {
;           float v = L0[i] + L1[j];
;           v = __uint_as_float((__float_as_uint(v) & ~255u) | (unsigned)(i * 16 + j));
; #pragma unroll
;           for (int t = 0; t < 16; t++)
;             if (t >= (i + 1) * (j + 1) - 1) ce(R[t], v);
;         }
	v_max_f32_e32 v161, v161, v164
	v_min_f32_e32 v164, v162, v165
	v_max_f32_e32 v162, v162, v165
	v_max_f32_e32 v163, v163, v164
	v_add_f32_e32 v164, v100, v6
	v_and_or_b32 v164, v164, s18, 14
	v_min_f32_e32 v165, v162, v164
	v_max_f32_e32 v162, v162, v164
	v_max_f32_e32 v163, v163, v165
	v_add_f32_e32 v164, v100, v5
	v_and_or_b32 v164, v164, s18, 15
	v_max_f32_e32 v163, v163, v164
	v_add_f32_e32 v164, v91, v2
	v_and_or_b32 v164, v164, s18, 16
	v_min_f32_e32 v165, v149, v164
	v_max_f32_e32 v149, v149, v164
	v_min_f32_e32 v164, v150, v165
	v_max_f32_e32 v150, v150, v165
	v_min_f32_e32 v165, v151, v164
	v_max_f32_e32 v151, v151, v164
	v_min_f32_e32 v164, v152, v165
	v_max_f32_e32 v152, v152, v165
	v_min_f32_e32 v165, v153, v164
	v_max_f32_e32 v153, v153, v164
	v_min_f32_e32 v164, v154, v165
	v_max_f32_e32 v154, v154, v165
	v_min_f32_e32 v165, v155, v164
	v_max_f32_e32 v155, v155, v164
	v_min_f32_e32 v164, v156, v165
	v_max_f32_e32 v156, v156, v165
	v_min_f32_e32 v165, v157, v164
	v_max_f32_e32 v157, v157, v164
	v_min_f32_e32 v164, v158, v165
	v_max_f32_e32 v158, v158, v165
	v_min_f32_e32 v165, v159, v164
	v_max_f32_e32 v159, v159, v164
	v_min_f32_e32 v164, v160, v165
	v_max_f32_e32 v160, v160, v165
	v_min_f32_e32 v165, v161, v164
	v_max_f32_e32 v161, v161, v164
	v_min_f32_e32 v164, v162, v165
	v_max_f32_e32 v162, v162, v165
	v_max_f32_e32 v163, v163, v164
	v_add_f32_e32 v164, v91, v4
	v_and_or_b32 v164, v164, s18, 17
	v_min_f32_e32 v165, v151, v164
	v_max_f32_e32 v151, v151, v164
	v_min_f32_e32 v164, v152, v165
	v_max_f32_e32 v152, v152, v165
	v_min_f32_e32 v165, v153, v164
	v_max_f32_e32 v153, v153, v164
	v_min_f32_e32 v164, v154, v165
	v_max_f32_e32 v154, v154, v165
	v_min_f32_e32 v165, v155, v164
	v_max_f32_e32 v155, v155, v164
	v_min_f32_e32 v164, v156, v165
	v_max_f32_e32 v156, v156, v165
	v_min_f32_e32 v165, v157, v164
	v_max_f32_e32 v157, v157, v164
	v_min_f32_e32 v164, v158, v165
	v_max_f32_e32 v158, v158, v165
	v_min_f32_e32 v165, v159, v164
	v_max_f32_e32 v159, v159, v164
	v_min_f32_e32 v164, v160, v165
	v_max_f32_e32 v160, v160, v165
	v_min_f32_e32 v165, v161, v164
	v_max_f32_e32 v161, v161, v164
	v_min_f32_e32 v164, v162, v165
	v_max_f32_e32 v162, v162, v165
	v_max_f32_e32 v163, v163, v164
	v_add_f32_e32 v164, v91, v7
	v_and_or_b32 v164, v164, s18, 18
	v_min_f32_e32 v165, v153, v164
	v_max_f32_e32 v153, v153, v164
	v_min_f32_e32 v164, v154, v165
	v_max_f32_e32 v154, v154, v165
	v_min_f32_e32 v165, v155, v164
	v_max_f32_e32 v155, v155, v164
	v_min_f32_e32 v164, v156, v165
	v_max_f32_e32 v156, v156, v165
	v_min_f32_e32 v165, v157, v164
	v_max_f32_e32 v157, v157, v164
	v_min_f32_e32 v164, v158, v165
	v_max_f32_e32 v158, v158, v165
	v_min_f32_e32 v165, v159, v164
	v_max_f32_e32 v159, v159, v164
	v_min_f32_e32 v164, v160, v165
	v_max_f32_e32 v160, v160, v165
	v_min_f32_e32 v165, v161, v164
	v_max_f32_e32 v161, v161, v164
	v_min_f32_e32 v164, v162, v165
	v_max_f32_e32 v162, v162, v165
	v_max_f32_e32 v163, v163, v164
	v_add_f32_e32 v164, v91, v8
	v_and_or_b32 v164, v164, s18, 19
	v_min_f32_e32 v165, v155, v164
	v_max_f32_e32 v155, v155, v164
	v_min_f32_e32 v164, v156, v165
	v_max_f32_e32 v156, v156, v165
	v_min_f32_e32 v165, v157, v164
	v_max_f32_e32 v157, v157, v164
	v_min_f32_e32 v164, v158, v165
	v_max_f32_e32 v158, v158, v165
	v_min_f32_e32 v165, v159, v164
	v_max_f32_e32 v159, v159, v164
	v_min_f32_e32 v164, v160, v165
	v_max_f32_e32 v160, v160, v165
	v_min_f32_e32 v165, v161, v164
	v_max_f32_e32 v161, v161, v164
	v_min_f32_e32 v164, v162, v165
	v_max_f32_e32 v162, v162, v165
	v_max_f32_e32 v163, v163, v164
	v_add_f32_e32 v164, v91, v9
	v_and_or_b32 v164, v164, s18, 20
	v_min_f32_e32 v165, v157, v164
	v_max_f32_e32 v157, v157, v164
	v_min_f32_e32 v164, v158, v165
	v_max_f32_e32 v158, v158, v165
	v_min_f32_e32 v165, v159, v164
	v_max_f32_e32 v159, v159, v164
	v_min_f32_e32 v164, v160, v165
	v_max_f32_e32 v160, v160, v165
	v_min_f32_e32 v165, v161, v164
	v_max_f32_e32 v161, v161, v164
	v_min_f32_e32 v164, v162, v165
	v_max_f32_e32 v162, v162, v165
	v_max_f32_e32 v163, v163, v164
	v_add_f32_e32 v164, v91, v12
	v_and_or_b32 v164, v164, s18, 21
	v_min_f32_e32 v165, v159, v164
	v_max_f32_e32 v159, v159, v164
	v_min_f32_e32 v164, v160, v165
	v_max_f32_e32 v160, v160, v165
	v_min_f32_e32 v165, v161, v164
	v_max_f32_e32 v161, v161, v164
	v_min_f32_e32 v164, v162, v165
	v_max_f32_e32 v162, v162, v165
	v_max_f32_e32 v163, v163, v164
	v_add_f32_e32 v164, v91, v11
	v_and_or_b32 v164, v164, s18, 22
	v_min_f32_e32 v165, v161, v164
	v_max_f32_e32 v161, v161, v164
	v_min_f32_e32 v164, v162, v165
	v_max_f32_e32 v162, v162, v165
	v_max_f32_e32 v163, v163, v164
	v_add_f32_e32 v164, v91, v10
	v_and_or_b32 v164, v164, s18, 23
	v_max_f32_e32 v163, v163, v164
	v_add_f32_e32 v164, v87, v2
	v_and_or_b32 v164, v164, s18, 32
	v_min_f32_e32 v165, v150, v164
	v_max_f32_e32 v150, v150, v164
	v_min_f32_e32 v164, v151, v165
	v_max_f32_e32 v151, v151, v165
	v_min_f32_e32 v165, v152, v164
	v_max_f32_e32 v152, v152, v164
	v_min_f32_e32 v164, v153, v165
	v_max_f32_e32 v153, v153, v165
	v_min_f32_e32 v165, v154, v164
	v_max_f32_e32 v154, v154, v164
	v_min_f32_e32 v164, v155, v165
	v_max_f32_e32 v155, v155, v165
	v_min_f32_e32 v165, v156, v164
	v_max_f32_e32 v156, v156, v164
	v_min_f32_e32 v164, v157, v165
	v_max_f32_e32 v157, v157, v165
	v_min_f32_e32 v165, v158, v164
	v_max_f32_e32 v158, v158, v164
	v_min_f32_e32 v164, v159, v165
	v_max_f32_e32 v159, v159, v165
	v_min_f32_e32 v165, v160, v164
	v_max_f32_e32 v160, v160, v164
	v_min_f32_e32 v164, v161, v165
	v_max_f32_e32 v161, v161, v165
	v_min_f32_e32 v165, v162, v164
	v_max_f32_e32 v162, v162, v164
; DEV void ce(float& a, float& b) { float hi = fmaxf(a, b), lo = fminf(a, b); a = hi; b = lo; }
; DEV void phase_peer_score(const Params& p, int layer, int M, char* smem) {
;     ...
;     float R[16];
; #pragma unroll
;     for (int i = 0; i < 16; i++) R[i] = -3.0e38f;
; #pragma unroll
;     for (int i = 0; i < 16; i++)
; #pragma unroll
;       for (int j = 0; j < 16; j++)
;         if ((i + 1) * (j + 1) <= 16) {
;           float v = L0[i] + L1[j];
;           v = __uint_as_float((__float_as_uint(v) & ~255u) | (unsigned)(i * 16 + j));
; #pragma unroll
;           for (int t = 0; t < 16; t++)
;             if (t >= (i + 1) * (j + 1) - 1) ce(R[t], v);
;         }
	v_max_f32_e32 v163, v163, v165
	v_add_f32_e32 v164, v87, v4
	v_and_or_b32 v164, v164, s18, 33
	v_min_f32_e32 v165, v153, v164
	v_max_f32_e32 v153, v153, v164
	v_min_f32_e32 v164, v154, v165
	v_max_f32_e32 v154, v154, v165
	v_min_f32_e32 v165, v155, v164
	v_max_f32_e32 v155, v155, v164
	v_min_f32_e32 v164, v156, v165
	v_max_f32_e32 v156, v156, v165
	v_min_f32_e32 v165, v157, v164
	v_max_f32_e32 v157, v157, v164
	v_min_f32_e32 v164, v158, v165
	v_max_f32_e32 v158, v158, v165
	v_min_f32_e32 v165, v159, v164
	v_max_f32_e32 v159, v159, v164
	v_min_f32_e32 v164, v160, v165
	v_max_f32_e32 v160, v160, v165
	v_min_f32_e32 v165, v161, v164
	v_max_f32_e32 v161, v161, v164
	v_min_f32_e32 v164, v162, v165
	v_max_f32_e32 v162, v162, v165
	v_max_f32_e32 v163, v163, v164
	v_add_f32_e32 v164, v87, v7
	v_and_or_b32 v164, v164, s18, 34
	v_min_f32_e32 v165, v156, v164
	v_max_f32_e32 v156, v156, v164
	v_min_f32_e32 v164, v157, v165
	v_max_f32_e32 v157, v157, v165
	v_min_f32_e32 v165, v158, v164
	v_max_f32_e32 v158, v158, v164
	v_min_f32_e32 v164, v159, v165
	v_max_f32_e32 v159, v159, v165
	v_min_f32_e32 v165, v160, v164
	v_max_f32_e32 v160, v160, v164
	v_min_f32_e32 v164, v161, v165
	v_max_f32_e32 v161, v161, v165
	v_min_f32_e32 v165, v162, v164
	v_max_f32_e32 v162, v162, v164
	v_max_f32_e32 v163, v163, v165
	v_add_f32_e32 v164, v87, v8
	v_and_or_b32 v164, v164, s18, 35
	v_min_f32_e32 v165, v159, v164
	v_max_f32_e32 v159, v159, v164
	v_min_f32_e32 v164, v160, v165
	v_max_f32_e32 v160, v160, v165
	v_min_f32_e32 v165, v161, v164
	v_max_f32_e32 v161, v161, v164
	v_min_f32_e32 v164, v162, v165
	v_max_f32_e32 v162, v162, v165
	v_max_f32_e32 v163, v163, v164
	v_add_f32_e32 v164, v87, v9
	v_and_or_b32 v164, v164, s18, 36
	v_min_f32_e32 v165, v162, v164
	v_max_f32_e32 v162, v162, v164
	v_max_f32_e32 v163, v163, v165
	v_add_f32_e32 v164, v83, v2
	v_and_or_b32 v164, v164, s18, 48
	v_min_f32_e32 v165, v151, v164
	v_max_f32_e32 v151, v151, v164
	v_min_f32_e32 v164, v152, v165
	v_max_f32_e32 v152, v152, v165
	v_min_f32_e32 v165, v153, v164
	v_max_f32_e32 v153, v153, v164
	v_min_f32_e32 v164, v154, v165
	v_max_f32_e32 v154, v154, v165
	v_min_f32_e32 v165, v155, v164
	v_max_f32_e32 v155, v155, v164
	v_min_f32_e32 v164, v156, v165
	v_max_f32_e32 v156, v156, v165
	v_min_f32_e32 v165, v157, v164
	v_max_f32_e32 v157, v157, v164
	v_min_f32_e32 v164, v158, v165
	v_max_f32_e32 v158, v158, v165
	v_min_f32_e32 v165, v159, v164
	v_max_f32_e32 v159, v159, v164
	v_min_f32_e32 v164, v160, v165
	v_max_f32_e32 v160, v160, v165
	v_min_f32_e32 v165, v161, v164
	v_max_f32_e32 v161, v161, v164
	v_min_f32_e32 v164, v162, v165
	v_max_f32_e32 v162, v162, v165
	v_max_f32_e32 v163, v163, v164
	v_add_f32_e32 v164, v83, v4
	v_and_or_b32 v164, v164, s18, 49
	v_min_f32_e32 v165, v155, v164
	v_max_f32_e32 v155, v155, v164
	v_min_f32_e32 v164, v156, v165
	v_max_f32_e32 v156, v156, v165
	v_min_f32_e32 v165, v157, v164
	v_max_f32_e32 v157, v157, v164
	v_min_f32_e32 v164, v158, v165
	v_max_f32_e32 v158, v158, v165
	v_min_f32_e32 v165, v159, v164
	v_max_f32_e32 v159, v159, v164
	v_min_f32_e32 v164, v160, v165
	v_max_f32_e32 v160, v160, v165
	v_min_f32_e32 v165, v161, v164
	v_max_f32_e32 v161, v161, v164
	v_min_f32_e32 v164, v162, v165
	v_max_f32_e32 v162, v162, v165
	v_max_f32_e32 v163, v163, v164
	v_add_f32_e32 v164, v83, v7
	v_and_or_b32 v164, v164, s18, 50
	v_min_f32_e32 v165, v159, v164
	v_max_f32_e32 v159, v159, v164
	v_min_f32_e32 v164, v160, v165
	v_max_f32_e32 v160, v160, v165
	v_min_f32_e32 v165, v161, v164
	v_max_f32_e32 v161, v161, v164
	v_min_f32_e32 v164, v162, v165
	v_max_f32_e32 v162, v162, v165
	v_max_f32_e32 v163, v163, v164
	v_add_f32_e32 v164, v83, v8
	v_and_or_b32 v164, v164, s18, 51
	v_max_f32_e32 v163, v163, v164
	v_add_f32_e32 v164, v79, v2
	v_and_or_b32 v164, v164, s18, 64
	v_min_f32_e32 v165, v152, v164
	v_max_f32_e32 v152, v152, v164
	v_min_f32_e32 v164, v153, v165
	v_max_f32_e32 v153, v153, v165
	v_min_f32_e32 v165, v154, v164
	v_max_f32_e32 v154, v154, v164
	v_min_f32_e32 v164, v155, v165
	v_max_f32_e32 v155, v155, v165
	v_min_f32_e32 v165, v156, v164
	v_max_f32_e32 v156, v156, v164
	v_min_f32_e32 v164, v157, v165
	v_max_f32_e32 v157, v157, v165
	v_min_f32_e32 v165, v158, v164
	v_max_f32_e32 v158, v158, v164
	v_min_f32_e32 v164, v159, v165
	v_max_f32_e32 v159, v159, v165
	v_min_f32_e32 v165, v160, v164
	v_max_f32_e32 v160, v160, v164
	v_min_f32_e32 v164, v161, v165
	v_max_f32_e32 v161, v161, v165
	v_min_f32_e32 v165, v162, v164
	v_max_f32_e32 v162, v162, v164
	v_max_f32_e32 v163, v163, v165
	v_add_f32_e32 v164, v79, v4
	v_and_b32_e32 v164, 0xffffff00, v164
	v_or_b32_e32 v164, 0x41, v164
	v_min_f32_e32 v165, v157, v164
	v_max_f32_e32 v157, v157, v164
	v_min_f32_e32 v164, v158, v165
	v_max_f32_e32 v158, v158, v165
	v_min_f32_e32 v165, v159, v164
	v_max_f32_e32 v159, v159, v164
	v_min_f32_e32 v164, v160, v165
	v_max_f32_e32 v160, v160, v165
	v_min_f32_e32 v165, v161, v164
	v_max_f32_e32 v161, v161, v164
	v_min_f32_e32 v164, v162, v165
	v_max_f32_e32 v162, v162, v165
	v_max_f32_e32 v163, v163, v164
	v_add_f32_e32 v164, v79, v7
	v_and_b32_e32 v164, 0xffffff00, v164
	v_or_b32_e32 v164, 0x42, v164
	v_min_f32_e32 v165, v162, v164
	v_max_f32_e32 v162, v162, v164
	v_max_f32_e32 v163, v163, v165
	v_add_f32_e32 v164, v75, v2
	v_and_b32_e32 v164, 0xffffff00, v164
	v_or_b32_e32 v164, 0x50, v164
	v_min_f32_e32 v165, v153, v164
	v_max_f32_e32 v153, v153, v164
	v_min_f32_e32 v164, v154, v165
	v_max_f32_e32 v154, v154, v165
; DEV void ce(float& a, float& b) { float hi = fmaxf(a, b), lo = fminf(a, b); a = hi; b = lo; }
; DEV void phase_peer_score(const Params& p, int layer, int M, char* smem) {
;     ...
;     float R[16];
; #pragma unroll
;     for (int i = 0; i < 16; i++) R[i] = -3.0e38f;
; #pragma unroll
;     for (int i = 0; i < 16; i++)
; #pragma unroll
;       for (int j = 0; j < 16; j++)
;         if ((i + 1) * (j + 1) <= 16) {
;           float v = L0[i] + L1[j];
;           v = __uint_as_float((__float_as_uint(v) & ~255u) | (unsigned)(i * 16 + j));
; #pragma unroll
;           for (int t = 0; t < 16; t++)
;             if (t >= (i + 1) * (j + 1) - 1) ce(R[t], v);
;         }
	v_min_f32_e32 v165, v155, v164
	v_max_f32_e32 v155, v155, v164
	v_min_f32_e32 v164, v156, v165
	v_max_f32_e32 v156, v156, v165
	v_min_f32_e32 v165, v157, v164
	v_max_f32_e32 v157, v157, v164
	v_min_f32_e32 v164, v158, v165
	v_max_f32_e32 v158, v158, v165
	v_min_f32_e32 v165, v159, v164
	v_max_f32_e32 v159, v159, v164
	v_min_f32_e32 v164, v160, v165
	v_max_f32_e32 v160, v160, v165
	v_min_f32_e32 v165, v161, v164
	v_max_f32_e32 v161, v161, v164
	v_min_f32_e32 v164, v162, v165
	v_max_f32_e32 v162, v162, v165
	v_max_f32_e32 v163, v163, v164
	v_add_f32_e32 v164, v75, v4
	v_and_b32_e32 v164, 0xffffff00, v164
	v_or_b32_e32 v164, 0x51, v164
	v_min_f32_e32 v165, v159, v164
	v_max_f32_e32 v159, v159, v164
	v_min_f32_e32 v164, v160, v165
	v_max_f32_e32 v160, v160, v165
	v_min_f32_e32 v165, v161, v164
	v_max_f32_e32 v161, v161, v164
	v_min_f32_e32 v164, v162, v165
	v_max_f32_e32 v162, v162, v165
	v_max_f32_e32 v163, v163, v164
	v_add_f32_e32 v164, v71, v2
	v_and_b32_e32 v164, 0xffffff00, v164
	v_or_b32_e32 v164, 0x60, v164
	v_min_f32_e32 v165, v154, v164
	v_max_f32_e32 v154, v154, v164
	v_min_f32_e32 v164, v155, v165
	v_max_f32_e32 v155, v155, v165
	v_min_f32_e32 v165, v156, v164
	v_max_f32_e32 v156, v156, v164
	v_min_f32_e32 v164, v157, v165
	v_max_f32_e32 v157, v157, v165
	v_min_f32_e32 v165, v158, v164
	v_max_f32_e32 v158, v158, v164
	v_min_f32_e32 v164, v159, v165
	v_max_f32_e32 v159, v159, v165
	v_min_f32_e32 v165, v160, v164
	v_max_f32_e32 v160, v160, v164
	v_min_f32_e32 v164, v161, v165
	v_max_f32_e32 v161, v161, v165
	v_min_f32_e32 v165, v162, v164
	v_max_f32_e32 v162, v162, v164
	v_max_f32_e32 v163, v163, v165
	v_add_f32_e32 v164, v71, v4
	v_and_b32_e32 v164, 0xffffff00, v164
	v_or_b32_e32 v164, 0x61, v164
	v_min_f32_e32 v165, v161, v164
	v_max_f32_e32 v161, v161, v164
	v_min_f32_e32 v164, v162, v165
	v_max_f32_e32 v162, v162, v165
	v_max_f32_e32 v163, v163, v164
	v_add_f32_e32 v164, v63, v2
	v_and_b32_e32 v164, 0xffffff00, v164
	v_or_b32_e32 v164, 0x70, v164
	v_min_f32_e32 v165, v155, v164
	v_max_f32_e32 v155, v155, v164
	v_min_f32_e32 v164, v156, v165
	v_max_f32_e32 v156, v156, v165
	v_min_f32_e32 v165, v157, v164
	v_max_f32_e32 v157, v157, v164
	v_min_f32_e32 v164, v158, v165
	v_max_f32_e32 v158, v158, v165
	v_min_f32_e32 v165, v159, v164
	v_max_f32_e32 v159, v159, v164
	v_min_f32_e32 v164, v160, v165
	v_max_f32_e32 v160, v160, v165
	v_min_f32_e32 v165, v161, v164
	v_max_f32_e32 v161, v161, v164
	v_min_f32_e32 v164, v162, v165
	v_max_f32_e32 v162, v162, v165
	v_max_f32_e32 v163, v163, v164
	v_add_f32_e32 v164, v63, v4
	v_and_b32_e32 v164, 0xffffff00, v164
	v_or_b32_e32 v164, 0x71, v164
	v_max_f32_e32 v163, v163, v164
	v_add_f32_e32 v164, v67, v2
	v_and_b32_e32 v164, 0xffffff00, v164
	v_or_b32_e32 v164, 0x80, v164
	v_min_f32_e32 v165, v156, v164
	v_max_f32_e32 v156, v156, v164
	v_min_f32_e32 v164, v157, v165
	v_max_f32_e32 v157, v157, v165
	v_min_f32_e32 v165, v158, v164
	v_max_f32_e32 v158, v158, v164
	v_min_f32_e32 v164, v159, v165
	v_max_f32_e32 v159, v159, v165
	v_min_f32_e32 v165, v160, v164
	v_max_f32_e32 v160, v160, v164
	v_min_f32_e32 v164, v161, v165
	v_max_f32_e32 v161, v161, v165
	v_min_f32_e32 v165, v162, v164
	v_max_f32_e32 v162, v162, v164
	v_max_f32_e32 v163, v163, v165
	v_add_f32_e32 v164, v59, v2
	v_and_b32_e32 v164, 0xffffff00, v164
	v_or_b32_e32 v164, 0x90, v164
	v_min_f32_e32 v165, v157, v164
	v_max_f32_e32 v157, v157, v164
	v_min_f32_e32 v164, v158, v165
	v_max_f32_e32 v158, v158, v165
	v_min_f32_e32 v165, v159, v164
	v_max_f32_e32 v159, v159, v164
	v_min_f32_e32 v164, v160, v165
	v_max_f32_e32 v160, v160, v165
	v_min_f32_e32 v165, v161, v164
	v_max_f32_e32 v161, v161, v164
	v_min_f32_e32 v164, v162, v165
	v_max_f32_e32 v162, v162, v165
	v_max_f32_e32 v163, v163, v164
	v_add_f32_e32 v164, v55, v2
	v_and_b32_e32 v164, 0xffffff00, v164
	v_or_b32_e32 v164, 0xa0, v164
	v_min_f32_e32 v165, v158, v164
	v_max_f32_e32 v158, v158, v164
	v_min_f32_e32 v164, v159, v165
	v_max_f32_e32 v159, v159, v165
	v_min_f32_e32 v165, v160, v164
	v_max_f32_e32 v160, v160, v164
	v_min_f32_e32 v164, v161, v165
	v_max_f32_e32 v161, v161, v165
	v_min_f32_e32 v165, v162, v164
	v_max_f32_e32 v162, v162, v164
	v_max_f32_e32 v163, v163, v165
	v_add_f32_e32 v164, v47, v2
	v_and_b32_e32 v164, 0xffffff00, v164
	v_or_b32_e32 v164, 0xb0, v164
	v_min_f32_e32 v165, v159, v164
	v_max_f32_e32 v159, v159, v164
	v_min_f32_e32 v164, v160, v165
	v_max_f32_e32 v160, v160, v165
	v_min_f32_e32 v165, v161, v164
	v_max_f32_e32 v161, v161, v164
	v_min_f32_e32 v164, v162, v165
	v_max_f32_e32 v162, v162, v165
	v_max_f32_e32 v163, v163, v164
	v_add_f32_e32 v164, v51, v2
	v_and_b32_e32 v164, 0xffffff00, v164
	v_or_b32_e32 v164, 0xc0, v164
	v_min_f32_e32 v165, v160, v164
	v_max_f32_e32 v160, v160, v164
	v_min_f32_e32 v164, v161, v165
	v_max_f32_e32 v161, v161, v165
	v_min_f32_e32 v165, v162, v164
	v_max_f32_e32 v162, v162, v164
	v_max_f32_e32 v163, v163, v165
	v_add_f32_e32 v164, v39, v2
	v_and_b32_e32 v164, 0xffffff00, v164
	v_or_b32_e32 v164, 0xd0, v164
	v_min_f32_e32 v165, v161, v164
	v_max_f32_e32 v161, v161, v164
	v_min_f32_e32 v164, v162, v165
	v_max_f32_e32 v162, v162, v165
	v_max_f32_e32 v163, v163, v164
	v_add_f32_e32 v164, v43, v2
	v_and_b32_e32 v164, 0xffffff00, v164
	v_or_b32_e32 v164, 0xe0, v164
	v_min_f32_e32 v165, v162, v164
	v_max_f32_e32 v162, v162, v164
	v_max_f32_e32 v163, v163, v165
	v_add_f32_e32 v164, v0, v2
	v_and_b32_e32 v164, 0xffffff00, v164
	v_or_b32_e32 v164, 0xf0, v164
	v_max_f32_e32 v163, v163, v164
